# extra s_setprio 0/1 yield point after every 8 MFMAs (at operand-group turns) in each GEMM phase block, on v32
# speedup vs baseline: 1.0014x; 1.0014x over previous
; #define PG8_STAGE(bufoff, gbase, voff) do { _Pragma("unroll") for (int _i = 0; _i < 2; ++_i) \
;         __builtin_amdgcn_global_load_lds((const unsigned*)((const char*)(gbase) + (voff)[_i]), (LAS unsigned*)(lds + (bufoff) + ldsw + _i * 8192), 16, 0, 0); } while (0)
; #define PG8_LDA(dst, b, h) do { _Pragma("unroll") for (int m = 0; m < 4; ++m) _Pragma("unroll") for (int k = 0; k < 2; ++k) dst[m][k] = *(const LAS bf16x8*)(lds + PG8_SA(b, h) + aoff + m * 2048 + k * 1024); } while (0)
; #define PG8_LDB(dst, b, h) do { _Pragma("unroll") for (int n = 0; n < 2; ++n) _Pragma("unroll") for (int k = 0; k < 2; ++k) dst[n][k] = *(const LAS bf16x8*)(lds + PG8_SB(b, h) + boff + n * 2048 + k * 1024); } while (0)
; #define PG8_MMA(ai, bj, At, Bt) do { __builtin_amdgcn_s_setprio(1); _Pragma("unroll") for (int m = 0; m < 4; ++m) _Pragma("unroll") for (int n = 0; n < 2; ++n) _Pragma("unroll") for (int k = 0; k < 2; ++k) \
;         acc[ai][bj][m][n] = __builtin_amdgcn_mfma_f32_16x16x32_bf16(Bt[n][k], At[m][k], acc[ai][bj][m][n], 0, 0, 0); __builtin_amdgcn_s_setprio(0); } while (0)
; #define PG8_WAIT_V(n) asm volatile("s_waitcnt vmcnt(" #n ")" ::: "memory")
; #define PG8_WAIT_L(n) asm volatile("s_waitcnt lgkmcnt(" #n ")" ::: "memory")
; #define PG8_BAR __builtin_amdgcn_s_barrier()
; #define PG8_SCHED __builtin_amdgcn_sched_barrier(0)
; template <class Epi>
; __device__ __forceinline__ void gemm_phase(LAS unsigned char* lds, const Gemm g, const StaticOrder& S, const Epi& E) {
;     ...
;             const bool last = (t == nt - 2);
;             const char* a1 = cA + (size_t)(t + 1) * kstep;
;             const char* a2 = last ? nA : cA + (size_t)(t + 2) * kstep; const char* b2 = last ? nB : cB + (size_t)(t + 2) * kstep;
;             const char* a3 = a2 + kstep; const char* b3 = b2 + kstep;
;             PG8_LDB(B0, 0, 0); PG8_LDB(B1, 0, 1); PG8_SCHED; PG8_LDA(At, 0, 0); PG8_STAGE(PG8_SA(1, 1), a1 + hstepA, voffA);
;             PG8_WAIT_V(8); PG8_WAIT_L(0); PG8_BAR; PG8_MMA(0, 0, At, B0); PG8_MMA(0, 1, At, B1); PG8_BAR; PG8_SCHED;
;             PG8_LDA(At, 0, 1); PG8_STAGE(PG8_SB(0, 0), b2, voffB); PG8_STAGE(PG8_SB(0, 1), b2 + hstepB, voffB); PG8_STAGE(PG8_SA(0, 0), a2, voffA);
.LBB0_245:
	ds_read_b128 v[152:155], v148
	ds_read_b128 v[156:159], v148 offset:1024
	ds_read_b128 v[160:163], v148 offset:2048
	ds_read_b128 v[164:167], v148 offset:3072
	ds_read_b128 v[168:171], v149
	ds_read_b128 v[172:175], v149 offset:1024
	ds_read_b128 v[176:179], v149 offset:2048
	ds_read_b128 v[180:183], v149 offset:3072
	s_add_i32 s64, s26, 2
	s_add_u32 s27, s24, 0xfff80080
	s_addc_u32 s30, s25, -1
	s_cmp_eq_u32 s54, s26
	s_cselect_b32 s26, s61, s62
	s_cselect_b32 s31, s15, s30
	s_cselect_b32 s30, s17, s27
	s_cselect_b32 s27, s60, s63
	v_lshl_add_u64 v[220:221], s[24:25], 0, v[138:139]
	s_add_i32 m0, s44, 0xc000
	ds_read_b128 v[184:187], v150
	ds_read_b128 v[188:191], v150 offset:1024
	ds_read_b128 v[192:195], v150 offset:2048
	ds_read_b128 v[196:199], v150 offset:3072
	ds_read_b128 v[200:203], v150 offset:4096
	ds_read_b128 v[208:211], v150 offset:5120
	ds_read_b128 v[212:215], v150 offset:6144
	ds_read_b128 v[216:219], v150 offset:7168
	global_load_lds_dwordx4 v[220:221], off
	v_lshl_add_u64 v[220:221], s[24:25], 0, v[140:141]
	s_add_i32 m0, s44, 0xe000
	s_nop 0
	global_load_lds_dwordx4 v[220:221], off
	s_waitcnt vmcnt(8)
	s_waitcnt lgkmcnt(0)
	s_barrier
	s_setprio 1
	s_waitcnt lgkmcnt(0)
	v_mfma_f32_16x16x32_bf16 v[120:123], v[152:155], v[184:187], v[120:123]
	v_mfma_f32_16x16x32_bf16 v[120:123], v[156:159], v[188:191], v[120:123]
	v_mfma_f32_16x16x32_bf16 v[116:119], v[164:167], v[188:191], v[116:119]
	v_mfma_f32_16x16x32_bf16 v[116:119], v[160:163], v[184:187], v[116:119]
	v_mfma_f32_16x16x32_bf16 v[124:127], v[168:171], v[184:187], v[124:127]
	v_mfma_f32_16x16x32_bf16 v[124:127], v[172:175], v[188:191], v[124:127]
	v_mfma_f32_16x16x32_bf16 v[112:115], v[180:183], v[188:191], v[112:115]
	v_mfma_f32_16x16x32_bf16 v[112:115], v[176:179], v[184:187], v[112:115]
	s_setprio 0
	s_setprio 1
	v_mfma_f32_16x16x32_bf16 v[96:99], v[176:179], v[192:195], v[96:99]
	v_mfma_f32_16x16x32_bf16 v[96:99], v[180:183], v[196:199], v[96:99]
	v_mfma_f32_16x16x32_bf16 v[104:107], v[172:175], v[196:199], v[104:107]
	v_mfma_f32_16x16x32_bf16 v[104:107], v[168:171], v[192:195], v[104:107]
	v_mfma_f32_16x16x32_bf16 v[100:103], v[160:163], v[192:195], v[100:103]
	v_mfma_f32_16x16x32_bf16 v[100:103], v[164:167], v[196:199], v[100:103]
	v_mfma_f32_16x16x32_bf16 v[108:111], v[156:159], v[196:199], v[108:111]
	v_mfma_f32_16x16x32_bf16 v[108:111], v[152:155], v[192:195], v[108:111]
	s_setprio 0
	s_setprio 1
	v_mfma_f32_16x16x32_bf16 v[92:95], v[152:155], v[200:203], v[92:95]
	v_mfma_f32_16x16x32_bf16 v[92:95], v[156:159], v[208:211], v[92:95]
	v_mfma_f32_16x16x32_bf16 v[84:87], v[164:167], v[208:211], v[84:87]
	v_mfma_f32_16x16x32_bf16 v[84:87], v[160:163], v[200:203], v[84:87]
	v_mfma_f32_16x16x32_bf16 v[88:91], v[168:171], v[200:203], v[88:91]
	v_mfma_f32_16x16x32_bf16 v[88:91], v[172:175], v[208:211], v[88:91]
	v_mfma_f32_16x16x32_bf16 v[80:83], v[180:183], v[208:211], v[80:83]
	v_mfma_f32_16x16x32_bf16 v[80:83], v[176:179], v[200:203], v[80:83]
	s_setprio 0
	s_setprio 1
	v_mfma_f32_16x16x32_bf16 v[64:67], v[176:179], v[212:215], v[64:67]
	v_mfma_f32_16x16x32_bf16 v[64:67], v[180:183], v[216:219], v[64:67]
	v_mfma_f32_16x16x32_bf16 v[72:75], v[172:175], v[216:219], v[72:75]
	v_mfma_f32_16x16x32_bf16 v[72:75], v[168:171], v[212:215], v[72:75]
	v_mfma_f32_16x16x32_bf16 v[68:71], v[160:163], v[212:215], v[68:71]
	v_mfma_f32_16x16x32_bf16 v[68:71], v[164:167], v[216:219], v[68:71]
	v_mfma_f32_16x16x32_bf16 v[76:79], v[156:159], v[216:219], v[76:79]
	v_mfma_f32_16x16x32_bf16 v[76:79], v[152:155], v[212:215], v[76:79]
	s_setprio 0
	s_barrier
	s_add_i32 s65, s57, s33
	v_lshl_add_u64 v[220:221], s[26:27], 0, v[132:133]
	s_mov_b32 m0, s65
	ds_read_b128 v[184:187], v150 offset:16384
	ds_read_b128 v[188:191], v150 offset:17408
	ds_read_b128 v[192:195], v150 offset:18432
	ds_read_b128 v[196:199], v150 offset:19456
	ds_read_b128 v[200:203], v150 offset:20480
	ds_read_b128 v[208:211], v150 offset:21504
	ds_read_b128 v[212:215], v150 offset:22528
	ds_read_b128 v[216:219], v150 offset:23552
	global_load_lds_dwordx4 v[220:221], off
	s_add_i32 m0, s65, 0x2000
	s_add_u32 s66, s26, 0x80000
	v_lshl_add_u64 v[222:223], s[26:27], 0, v[128:129]
	s_addc_u32 s67, s27, 0
	s_add_i32 s65, s58, s33
	global_load_lds_dwordx4 v[222:223], off
	v_lshl_add_u64 v[224:225], s[66:67], 0, v[132:133]
	s_mov_b32 m0, s65
	v_lshl_add_u64 v[226:227], s[30:31], 0, v[130:131]
	global_load_lds_dwordx4 v[224:225], off
	v_lshl_add_u64 v[224:225], s[66:67], 0, v[128:129]
	s_add_i32 m0, s65, 0x2000
	s_nop 0
	global_load_lds_dwordx4 v[224:225], off
	v_lshl_add_u64 v[224:225], s[30:31], 0, v[134:135]
	s_mov_b32 m0, s44
	s_nop 0
	global_load_lds_dwordx4 v[224:225], off
	s_mov_b32 m0, s45
	s_nop 0
	global_load_lds_dwordx4 v[226:227], off
	s_waitcnt vmcnt(8)
	s_waitcnt lgkmcnt(0)
	s_barrier
; #define PG8_STAGE(bufoff, gbase, voff) do { _Pragma("unroll") for (int _i = 0; _i < 2; ++_i) \
;         __builtin_amdgcn_global_load_lds((const unsigned*)((const char*)(gbase) + (voff)[_i]), (LAS unsigned*)(lds + (bufoff) + ldsw + _i * 8192), 16, 0, 0); } while (0)
; #define PG8_LDA(dst, b, h) do { _Pragma("unroll") for (int m = 0; m < 4; ++m) _Pragma("unroll") for (int k = 0; k < 2; ++k) dst[m][k] = *(const LAS bf16x8*)(lds + PG8_SA(b, h) + aoff + m * 2048 + k * 1024); } while (0)
; #define PG8_LDB(dst, b, h) do { _Pragma("unroll") for (int n = 0; n < 2; ++n) _Pragma("unroll") for (int k = 0; k < 2; ++k) dst[n][k] = *(const LAS bf16x8*)(lds + PG8_SB(b, h) + boff + n * 2048 + k * 1024); } while (0)
; #define PG8_MMA(ai, bj, At, Bt) do { __builtin_amdgcn_s_setprio(1); _Pragma("unroll") for (int m = 0; m < 4; ++m) _Pragma("unroll") for (int n = 0; n < 2; ++n) _Pragma("unroll") for (int k = 0; k < 2; ++k) \
;         acc[ai][bj][m][n] = __builtin_amdgcn_mfma_f32_16x16x32_bf16(Bt[n][k], At[m][k], acc[ai][bj][m][n], 0, 0, 0); __builtin_amdgcn_s_setprio(0); } while (0)
; #define PG8_WAIT_V(n) asm volatile("s_waitcnt vmcnt(" #n ")" ::: "memory")
; #define PG8_WAIT_L(n) asm volatile("s_waitcnt lgkmcnt(" #n ")" ::: "memory")
; #define PG8_BAR __builtin_amdgcn_s_barrier()
; #define PG8_SCHED __builtin_amdgcn_sched_barrier(0)
; template <class Epi>
; __device__ __forceinline__ void gemm_phase(LAS unsigned char* lds, const Gemm g, const StaticOrder& S, const Epi& E) {
;     ...
;             PG8_WAIT_V(8); PG8_WAIT_L(0); PG8_BAR; PG8_MMA(1, 0, At, B0); PG8_MMA(1, 1, At, B1); PG8_BAR; PG8_SCHED;
;             PG8_LDB(B0, 1, 0); PG8_LDB(B1, 1, 1); PG8_SCHED; PG8_LDA(At, 1, 0); PG8_STAGE(PG8_SA(0, 1), a2 + hstepA, voffA);
;             PG8_WAIT_V(8); PG8_WAIT_L(0); PG8_BAR; PG8_MMA(0, 0, At, B0); PG8_MMA(0, 1, At, B1); PG8_BAR; PG8_SCHED;
	s_setprio 1
	s_waitcnt lgkmcnt(0)
	v_mfma_f32_16x16x32_bf16 v[60:63], v[152:155], v[184:187], v[60:63]
	v_mfma_f32_16x16x32_bf16 v[60:63], v[156:159], v[188:191], v[60:63]
	v_mfma_f32_16x16x32_bf16 v[52:55], v[164:167], v[188:191], v[52:55]
	v_mfma_f32_16x16x32_bf16 v[52:55], v[160:163], v[184:187], v[52:55]
	v_mfma_f32_16x16x32_bf16 v[56:59], v[168:171], v[184:187], v[56:59]
	v_mfma_f32_16x16x32_bf16 v[56:59], v[172:175], v[188:191], v[56:59]
	v_mfma_f32_16x16x32_bf16 v[48:51], v[180:183], v[188:191], v[48:51]
	v_mfma_f32_16x16x32_bf16 v[48:51], v[176:179], v[184:187], v[48:51]
	s_setprio 0
	s_setprio 1
	v_mfma_f32_16x16x32_bf16 v[32:35], v[176:179], v[192:195], v[32:35]
	v_mfma_f32_16x16x32_bf16 v[32:35], v[180:183], v[196:199], v[32:35]
	v_mfma_f32_16x16x32_bf16 v[40:43], v[172:175], v[196:199], v[40:43]
	v_mfma_f32_16x16x32_bf16 v[40:43], v[168:171], v[192:195], v[40:43]
	v_mfma_f32_16x16x32_bf16 v[36:39], v[160:163], v[192:195], v[36:39]
	v_mfma_f32_16x16x32_bf16 v[36:39], v[164:167], v[196:199], v[36:39]
	v_mfma_f32_16x16x32_bf16 v[44:47], v[156:159], v[196:199], v[44:47]
	v_mfma_f32_16x16x32_bf16 v[44:47], v[152:155], v[192:195], v[44:47]
	s_setprio 0
	s_setprio 1
	v_mfma_f32_16x16x32_bf16 v[28:31], v[152:155], v[200:203], v[28:31]
	v_mfma_f32_16x16x32_bf16 v[28:31], v[156:159], v[208:211], v[28:31]
	v_mfma_f32_16x16x32_bf16 v[20:23], v[164:167], v[208:211], v[20:23]
	v_mfma_f32_16x16x32_bf16 v[20:23], v[160:163], v[200:203], v[20:23]
	v_mfma_f32_16x16x32_bf16 v[24:27], v[168:171], v[200:203], v[24:27]
	v_mfma_f32_16x16x32_bf16 v[24:27], v[172:175], v[208:211], v[24:27]
	v_mfma_f32_16x16x32_bf16 v[16:19], v[180:183], v[208:211], v[16:19]
	v_mfma_f32_16x16x32_bf16 v[16:19], v[176:179], v[200:203], v[16:19]
	s_setprio 0
	s_setprio 1
	v_mfma_f32_16x16x32_bf16 v[0:3], v[176:179], v[212:215], v[0:3]
	v_mfma_f32_16x16x32_bf16 v[0:3], v[180:183], v[216:219], v[0:3]
	v_mfma_f32_16x16x32_bf16 v[8:11], v[172:175], v[216:219], v[8:11]
	v_mfma_f32_16x16x32_bf16 v[8:11], v[168:171], v[212:215], v[8:11]
	v_mfma_f32_16x16x32_bf16 v[4:7], v[160:163], v[212:215], v[4:7]
	v_mfma_f32_16x16x32_bf16 v[4:7], v[164:167], v[216:219], v[4:7]
	v_mfma_f32_16x16x32_bf16 v[12:15], v[156:159], v[216:219], v[12:15]
	v_mfma_f32_16x16x32_bf16 v[12:15], v[152:155], v[212:215], v[12:15]
	s_setprio 0
	s_barrier
	s_add_i32 s65, 0, 0x18000
	v_add_u32_e32 v151, s65, v146
	s_add_i32 s66, 0, 0x1c000
	ds_read_b128 v[152:155], v151
	ds_read_b128 v[156:159], v151 offset:1024
	ds_read_b128 v[160:163], v151 offset:2048
	ds_read_b128 v[164:167], v151 offset:3072
	v_add_u32_e32 v151, s66, v146
	ds_read_b128 v[168:171], v151
	ds_read_b128 v[172:175], v151 offset:1024
	ds_read_b128 v[176:179], v151 offset:2048
	ds_read_b128 v[180:183], v151 offset:3072
	s_add_u32 s30, s30, 0x80000
	s_addc_u32 s31, s31, 0
	s_mov_b32 m0, s46
	v_lshl_add_u64 v[230:231], s[30:31], 0, v[134:135]
	ds_read_b128 v[184:187], v150 offset:32768
	ds_read_b128 v[188:191], v150 offset:33792
	ds_read_b128 v[192:195], v150 offset:34816
	ds_read_b128 v[196:199], v150 offset:35840
	ds_read_b128 v[200:203], v150 offset:36864
	ds_read_b128 v[208:211], v150 offset:37888
	ds_read_b128 v[212:215], v150 offset:38912
	ds_read_b128 v[216:219], v150 offset:39936
	global_load_lds_dwordx4 v[230:231], off
	v_lshl_add_u64 v[230:231], s[30:31], 0, v[130:131]
	s_mov_b32 m0, s47
	s_nop 0
	global_load_lds_dwordx4 v[230:231], off
	s_waitcnt vmcnt(8)
	s_waitcnt lgkmcnt(0)
	s_barrier
	s_setprio 1
	s_waitcnt lgkmcnt(0)
	v_mfma_f32_16x16x32_bf16 v[120:123], v[152:155], v[184:187], v[120:123]
	v_mfma_f32_16x16x32_bf16 v[120:123], v[156:159], v[188:191], v[120:123]
	v_mfma_f32_16x16x32_bf16 v[116:119], v[164:167], v[188:191], v[116:119]
	v_mfma_f32_16x16x32_bf16 v[116:119], v[160:163], v[184:187], v[116:119]
	v_mfma_f32_16x16x32_bf16 v[124:127], v[168:171], v[184:187], v[124:127]
	v_mfma_f32_16x16x32_bf16 v[124:127], v[172:175], v[188:191], v[124:127]
	v_mfma_f32_16x16x32_bf16 v[112:115], v[180:183], v[188:191], v[112:115]
	v_mfma_f32_16x16x32_bf16 v[112:115], v[176:179], v[184:187], v[112:115]
	s_setprio 0
	s_setprio 1
	v_mfma_f32_16x16x32_bf16 v[96:99], v[176:179], v[192:195], v[96:99]
	v_mfma_f32_16x16x32_bf16 v[96:99], v[180:183], v[196:199], v[96:99]
	v_mfma_f32_16x16x32_bf16 v[104:107], v[172:175], v[196:199], v[104:107]
	v_mfma_f32_16x16x32_bf16 v[104:107], v[168:171], v[192:195], v[104:107]
	v_mfma_f32_16x16x32_bf16 v[100:103], v[160:163], v[192:195], v[100:103]
	v_mfma_f32_16x16x32_bf16 v[100:103], v[164:167], v[196:199], v[100:103]
	v_mfma_f32_16x16x32_bf16 v[108:111], v[156:159], v[196:199], v[108:111]
	v_mfma_f32_16x16x32_bf16 v[108:111], v[152:155], v[192:195], v[108:111]
	s_setprio 0
	s_setprio 1
	v_mfma_f32_16x16x32_bf16 v[92:95], v[152:155], v[200:203], v[92:95]
	v_mfma_f32_16x16x32_bf16 v[92:95], v[156:159], v[208:211], v[92:95]
	v_mfma_f32_16x16x32_bf16 v[84:87], v[164:167], v[208:211], v[84:87]
	v_mfma_f32_16x16x32_bf16 v[84:87], v[160:163], v[200:203], v[84:87]
	v_mfma_f32_16x16x32_bf16 v[88:91], v[168:171], v[200:203], v[88:91]
	v_mfma_f32_16x16x32_bf16 v[88:91], v[172:175], v[208:211], v[88:91]
	v_mfma_f32_16x16x32_bf16 v[80:83], v[180:183], v[208:211], v[80:83]
	v_mfma_f32_16x16x32_bf16 v[80:83], v[176:179], v[200:203], v[80:83]
	s_setprio 0
	s_setprio 1
	v_mfma_f32_16x16x32_bf16 v[64:67], v[176:179], v[212:215], v[64:67]
	v_mfma_f32_16x16x32_bf16 v[64:67], v[180:183], v[216:219], v[64:67]
	v_mfma_f32_16x16x32_bf16 v[72:75], v[172:175], v[216:219], v[72:75]
	v_mfma_f32_16x16x32_bf16 v[72:75], v[168:171], v[212:215], v[72:75]
	v_mfma_f32_16x16x32_bf16 v[68:71], v[160:163], v[212:215], v[68:71]
	v_mfma_f32_16x16x32_bf16 v[68:71], v[164:167], v[216:219], v[68:71]
	v_mfma_f32_16x16x32_bf16 v[76:79], v[156:159], v[216:219], v[76:79]
	v_mfma_f32_16x16x32_bf16 v[76:79], v[152:155], v[212:215], v[76:79]
	s_setprio 0
	s_barrier
; #define PG8_STAGE(bufoff, gbase, voff) do { _Pragma("unroll") for (int _i = 0; _i < 2; ++_i) \
;         __builtin_amdgcn_global_load_lds((const unsigned*)((const char*)(gbase) + (voff)[_i]), (LAS unsigned*)(lds + (bufoff) + ldsw + _i * 8192), 16, 0, 0); } while (0)
; #define PG8_LDA(dst, b, h) do { _Pragma("unroll") for (int m = 0; m < 4; ++m) _Pragma("unroll") for (int k = 0; k < 2; ++k) dst[m][k] = *(const LAS bf16x8*)(lds + PG8_SA(b, h) + aoff + m * 2048 + k * 1024); } while (0)
; #define PG8_MMA(ai, bj, At, Bt) do { __builtin_amdgcn_s_setprio(1); _Pragma("unroll") for (int m = 0; m < 4; ++m) _Pragma("unroll") for (int n = 0; n < 2; ++n) _Pragma("unroll") for (int k = 0; k < 2; ++k) \
;         acc[ai][bj][m][n] = __builtin_amdgcn_mfma_f32_16x16x32_bf16(Bt[n][k], At[m][k], acc[ai][bj][m][n], 0, 0, 0); __builtin_amdgcn_s_setprio(0); } while (0)
; #define PG8_WAIT_V(n) asm volatile("s_waitcnt vmcnt(" #n ")" ::: "memory")
; #define PG8_WAIT_L(n) asm volatile("s_waitcnt lgkmcnt(" #n ")" ::: "memory")
; #define PG8_BAR __builtin_amdgcn_s_barrier()
; #define PG8_SCHED __builtin_amdgcn_sched_barrier(0)
; template <class Epi>
; __device__ __forceinline__ void gemm_phase(LAS unsigned char* lds, const Gemm g, const StaticOrder& S, const Epi& E) {
;     ...
;         for (int t = 0; t < nt; t += 2) {
;             const bool last = (t == nt - 2);
;             const char* a1 = cA + (size_t)(t + 1) * kstep;
;             const char* a2 = last ? nA : cA + (size_t)(t + 2) * kstep; const char* b2 = last ? nB : cB + (size_t)(t + 2) * kstep;
;             const char* a3 = a2 + kstep; const char* b3 = b2 + kstep;
;     ...
;             PG8_LDA(At, 1, 1); PG8_STAGE(PG8_SB(1, 0), b3, voffB); PG8_STAGE(PG8_SB(1, 1), b3 + hstepB, voffB); PG8_STAGE(PG8_SA(1, 0), a3, voffA);
;             PG8_WAIT_V(8); PG8_WAIT_L(0); PG8_BAR; PG8_MMA(1, 0, At, B0); PG8_MMA(1, 1, At, B1); PG8_BAR; PG8_SCHED;
;         }
	s_add_i32 s30, s65, s33
	v_lshl_add_u64 v[220:221], v[220:221], 0, s[8:9]
	s_mov_b32 m0, s30
	ds_read_b128 v[184:187], v150 offset:49152
	ds_read_b128 v[188:191], v150 offset:50176
	ds_read_b128 v[192:195], v150 offset:51200
	ds_read_b128 v[196:199], v150 offset:52224
	ds_read_b128 v[200:203], v150 offset:53248
	ds_read_b128 v[208:211], v150 offset:54272
	ds_read_b128 v[212:215], v150 offset:55296
	ds_read_b128 v[216:219], v150 offset:56320
	global_load_lds_dwordx4 v[220:221], off
	s_add_i32 m0, s30, 0x2000
	s_add_u32 s26, s26, 0x80080
	v_lshl_add_u64 v[220:221], v[222:223], 0, s[8:9]
	s_addc_u32 s27, s27, 0
	s_add_i32 s30, s66, s33
	global_load_lds_dwordx4 v[220:221], off
	v_lshl_add_u64 v[220:221], s[26:27], 0, v[132:133]
	s_mov_b32 m0, s30
	s_nop 0
	global_load_lds_dwordx4 v[220:221], off
	v_lshl_add_u64 v[220:221], s[26:27], 0, v[128:129]
	s_add_i32 m0, s30, 0x2000
	s_nop 0
	global_load_lds_dwordx4 v[220:221], off
	v_lshl_add_u64 v[220:221], v[224:225], 0, s[8:9]
	s_mov_b32 m0, s52
	s_nop 0
	global_load_lds_dwordx4 v[220:221], off
	v_lshl_add_u64 v[220:221], v[226:227], 0, s[8:9]
	s_mov_b32 m0, s53
	s_nop 0
	global_load_lds_dwordx4 v[220:221], off
	s_waitcnt vmcnt(8)
	s_waitcnt lgkmcnt(0)
	s_barrier
	s_setprio 1
	s_waitcnt lgkmcnt(0)
	v_mfma_f32_16x16x32_bf16 v[60:63], v[152:155], v[184:187], v[60:63]
	v_mfma_f32_16x16x32_bf16 v[60:63], v[156:159], v[188:191], v[60:63]
	v_mfma_f32_16x16x32_bf16 v[52:55], v[164:167], v[188:191], v[52:55]
	v_mfma_f32_16x16x32_bf16 v[52:55], v[160:163], v[184:187], v[52:55]
	v_mfma_f32_16x16x32_bf16 v[56:59], v[168:171], v[184:187], v[56:59]
	v_mfma_f32_16x16x32_bf16 v[56:59], v[172:175], v[188:191], v[56:59]
	v_mfma_f32_16x16x32_bf16 v[48:51], v[180:183], v[188:191], v[48:51]
	v_mfma_f32_16x16x32_bf16 v[48:51], v[176:179], v[184:187], v[48:51]
	s_setprio 0
	s_setprio 1
	v_mfma_f32_16x16x32_bf16 v[32:35], v[176:179], v[192:195], v[32:35]
	v_mfma_f32_16x16x32_bf16 v[32:35], v[180:183], v[196:199], v[32:35]
	v_mfma_f32_16x16x32_bf16 v[40:43], v[172:175], v[196:199], v[40:43]
	v_mfma_f32_16x16x32_bf16 v[40:43], v[168:171], v[192:195], v[40:43]
	v_mfma_f32_16x16x32_bf16 v[36:39], v[160:163], v[192:195], v[36:39]
	v_mfma_f32_16x16x32_bf16 v[36:39], v[164:167], v[196:199], v[36:39]
	v_mfma_f32_16x16x32_bf16 v[44:47], v[156:159], v[196:199], v[44:47]
	v_mfma_f32_16x16x32_bf16 v[44:47], v[152:155], v[192:195], v[44:47]
	s_setprio 0
	s_setprio 1
	v_mfma_f32_16x16x32_bf16 v[28:31], v[152:155], v[200:203], v[28:31]
	v_mfma_f32_16x16x32_bf16 v[28:31], v[156:159], v[208:211], v[28:31]
	v_mfma_f32_16x16x32_bf16 v[20:23], v[164:167], v[208:211], v[20:23]
	v_mfma_f32_16x16x32_bf16 v[20:23], v[160:163], v[200:203], v[20:23]
	v_mfma_f32_16x16x32_bf16 v[24:27], v[168:171], v[200:203], v[24:27]
	v_mfma_f32_16x16x32_bf16 v[24:27], v[172:175], v[208:211], v[24:27]
	v_mfma_f32_16x16x32_bf16 v[16:19], v[180:183], v[208:211], v[16:19]
	v_mfma_f32_16x16x32_bf16 v[16:19], v[176:179], v[200:203], v[16:19]
	s_setprio 0
	s_setprio 1
	v_mfma_f32_16x16x32_bf16 v[0:3], v[176:179], v[212:215], v[0:3]
	v_mfma_f32_16x16x32_bf16 v[0:3], v[180:183], v[216:219], v[0:3]
	v_mfma_f32_16x16x32_bf16 v[8:11], v[172:175], v[216:219], v[8:11]
	v_mfma_f32_16x16x32_bf16 v[8:11], v[168:171], v[212:215], v[8:11]
	v_mfma_f32_16x16x32_bf16 v[4:7], v[160:163], v[212:215], v[4:7]
	v_mfma_f32_16x16x32_bf16 v[4:7], v[164:167], v[216:219], v[4:7]
	v_mfma_f32_16x16x32_bf16 v[12:15], v[156:159], v[216:219], v[12:15]
	v_mfma_f32_16x16x32_bf16 v[12:15], v[152:155], v[212:215], v[12:15]
	s_setprio 0
	s_barrier
	s_add_u32 s24, s24, 0x100
	s_addc_u32 s25, s25, 0
	s_add_u32 s62, s62, 0x100
	s_addc_u32 s63, s63, 0
	s_cmp_ge_i32 s64, s49
	s_mov_b32 s26, s64
	s_cbranch_scc0 .LBB0_245

; #define PG8_STAGE(bufoff, gbase, voff) do { _Pragma("unroll") for (int _i = 0; _i < 2; ++_i) \
;         __builtin_amdgcn_global_load_lds((const unsigned*)((const char*)(gbase) + (voff)[_i]), (LAS unsigned*)(lds + (bufoff) + ldsw + _i * 8192), 16, 0, 0); } while (0)
; #define PG8_LDA(dst, b, h) do { _Pragma("unroll") for (int m = 0; m < 4; ++m) _Pragma("unroll") for (int k = 0; k < 2; ++k) dst[m][k] = *(const LAS bf16x8*)(lds + PG8_SA(b, h) + aoff + m * 2048 + k * 1024); } while (0)
; #define PG8_LDB(dst, b, h) do { _Pragma("unroll") for (int n = 0; n < 2; ++n) _Pragma("unroll") for (int k = 0; k < 2; ++k) dst[n][k] = *(const LAS bf16x8*)(lds + PG8_SB(b, h) + boff + n * 2048 + k * 1024); } while (0)
; #define PG8_MMA(ai, bj, At, Bt) do { __builtin_amdgcn_s_setprio(1); _Pragma("unroll") for (int m = 0; m < 4; ++m) _Pragma("unroll") for (int n = 0; n < 2; ++n) _Pragma("unroll") for (int k = 0; k < 2; ++k) \
;         acc[ai][bj][m][n] = __builtin_amdgcn_mfma_f32_16x16x32_bf16(Bt[n][k], At[m][k], acc[ai][bj][m][n], 0, 0, 0); __builtin_amdgcn_s_setprio(0); } while (0)
; #define PG8_WAIT_V(n) asm volatile("s_waitcnt vmcnt(" #n ")" ::: "memory")
; #define PG8_WAIT_L(n) asm volatile("s_waitcnt lgkmcnt(" #n ")" ::: "memory")
; #define PG8_BAR __builtin_amdgcn_s_barrier()
; #define PG8_SCHED __builtin_amdgcn_sched_barrier(0)
; template <class Epi>
; __device__ __forceinline__ void gemm_phase(LAS unsigned char* lds, const Gemm g, const StaticOrder& S, const Epi& E) {
;     ...
;             const bool last = (t == nt - 2);
;             const char* a1 = cA + (size_t)(t + 1) * kstep;
;             const char* a2 = last ? nA : cA + (size_t)(t + 2) * kstep; const char* b2 = last ? nB : cB + (size_t)(t + 2) * kstep;
;             const char* a3 = a2 + kstep; const char* b3 = b2 + kstep;
;             PG8_LDB(B0, 0, 0); PG8_LDB(B1, 0, 1); PG8_SCHED; PG8_LDA(At, 0, 0); PG8_STAGE(PG8_SA(1, 1), a1 + hstepA, voffA);
;             PG8_WAIT_V(8); PG8_WAIT_L(0); PG8_BAR; PG8_MMA(0, 0, At, B0); PG8_MMA(0, 1, At, B1); PG8_BAR; PG8_SCHED;
;             PG8_LDA(At, 0, 1); PG8_STAGE(PG8_SB(0, 0), b2, voffB); PG8_STAGE(PG8_SB(0, 1), b2 + hstepB, voffB); PG8_STAGE(PG8_SA(0, 0), a2, voffA);
.LBB0_445:
	ds_read_b128 v[148:151], v218
	ds_read_b128 v[152:155], v218 offset:1024
	ds_read_b128 v[156:159], v218 offset:2048
	ds_read_b128 v[160:163], v218 offset:3072
	ds_read_b128 v[164:167], v219
	ds_read_b128 v[168:171], v219 offset:1024
	ds_read_b128 v[172:175], v219 offset:2048
	ds_read_b128 v[176:179], v219 offset:3072
	s_add_i32 s65, s34, 2
	s_add_u32 s30, s4, 0x100
	s_addc_u32 s31, s5, 0
	s_cmp_eq_u32 s49, s34
	s_cselect_b32 s34, s26, s1
	s_cselect_b32 s37, s11, s31
	s_cselect_b32 s36, s10, s30
	s_cselect_b32 s35, s27, s64
	v_lshl_add_u64 v[216:217], s[4:5], 0, v[140:141]
	s_add_i32 m0, s41, 0xc000
	ds_read_b128 v[180:183], v220
	ds_read_b128 v[184:187], v220 offset:1024
	ds_read_b128 v[188:191], v220 offset:2048
	ds_read_b128 v[192:195], v220 offset:3072
	ds_read_b128 v[196:199], v220 offset:4096
	ds_read_b128 v[200:203], v220 offset:5120
	ds_read_b128 v[208:211], v220 offset:6144
	ds_read_b128 v[212:215], v220 offset:7168
	global_load_lds_dwordx4 v[216:217], off
	v_lshl_add_u64 v[216:217], s[4:5], 0, v[142:143]
	s_add_i32 m0, s41, 0xe000
	s_nop 0
	global_load_lds_dwordx4 v[216:217], off
	s_waitcnt vmcnt(8)
	s_waitcnt lgkmcnt(0)
	s_barrier
	s_setprio 1
	s_waitcnt lgkmcnt(0)
	v_mfma_f32_16x16x32_bf16 v[124:127], v[148:151], v[180:183], v[124:127]
	v_mfma_f32_16x16x32_bf16 v[124:127], v[152:155], v[184:187], v[124:127]
	v_mfma_f32_16x16x32_bf16 v[120:123], v[160:163], v[184:187], v[120:123]
	v_mfma_f32_16x16x32_bf16 v[120:123], v[156:159], v[180:183], v[120:123]
	v_mfma_f32_16x16x32_bf16 v[108:111], v[164:167], v[180:183], v[108:111]
	v_mfma_f32_16x16x32_bf16 v[108:111], v[168:171], v[184:187], v[108:111]
	v_mfma_f32_16x16x32_bf16 v[100:103], v[176:179], v[184:187], v[100:103]
	v_mfma_f32_16x16x32_bf16 v[100:103], v[172:175], v[180:183], v[100:103]
	s_setprio 0
	s_setprio 1
	v_mfma_f32_16x16x32_bf16 v[84:87], v[172:175], v[188:191], v[84:87]
	v_mfma_f32_16x16x32_bf16 v[84:87], v[176:179], v[192:195], v[84:87]
	v_mfma_f32_16x16x32_bf16 v[92:95], v[168:171], v[192:195], v[92:95]
	v_mfma_f32_16x16x32_bf16 v[92:95], v[164:167], v[188:191], v[92:95]
	v_mfma_f32_16x16x32_bf16 v[112:115], v[156:159], v[188:191], v[112:115]
	v_mfma_f32_16x16x32_bf16 v[112:115], v[160:163], v[192:195], v[112:115]
	v_mfma_f32_16x16x32_bf16 v[116:119], v[152:155], v[192:195], v[116:119]
	v_mfma_f32_16x16x32_bf16 v[116:119], v[148:151], v[188:191], v[116:119]
	s_setprio 0
	s_setprio 1
	v_mfma_f32_16x16x32_bf16 v[104:107], v[148:151], v[196:199], v[104:107]
	v_mfma_f32_16x16x32_bf16 v[104:107], v[152:155], v[200:203], v[104:107]
	v_mfma_f32_16x16x32_bf16 v[96:99], v[160:163], v[200:203], v[96:99]
	v_mfma_f32_16x16x32_bf16 v[96:99], v[156:159], v[196:199], v[96:99]
	v_mfma_f32_16x16x32_bf16 v[76:79], v[164:167], v[196:199], v[76:79]
	v_mfma_f32_16x16x32_bf16 v[76:79], v[168:171], v[200:203], v[76:79]
	v_mfma_f32_16x16x32_bf16 v[72:75], v[176:179], v[200:203], v[72:75]
	v_mfma_f32_16x16x32_bf16 v[72:75], v[172:175], v[196:199], v[72:75]
	s_setprio 0
	s_setprio 1
	v_mfma_f32_16x16x32_bf16 v[64:67], v[172:175], v[208:211], v[64:67]
	v_mfma_f32_16x16x32_bf16 v[64:67], v[176:179], v[212:215], v[64:67]
	v_mfma_f32_16x16x32_bf16 v[68:71], v[168:171], v[212:215], v[68:71]
	v_mfma_f32_16x16x32_bf16 v[68:71], v[164:167], v[208:211], v[68:71]
	v_mfma_f32_16x16x32_bf16 v[80:83], v[156:159], v[208:211], v[80:83]
	v_mfma_f32_16x16x32_bf16 v[80:83], v[160:163], v[212:215], v[80:83]
	v_mfma_f32_16x16x32_bf16 v[88:91], v[152:155], v[212:215], v[88:91]
	v_mfma_f32_16x16x32_bf16 v[88:91], v[148:151], v[208:211], v[88:91]
	s_setprio 0
	s_barrier
	s_add_i32 s4, s54, s40
	v_lshl_add_u64 v[216:217], s[34:35], 0, v[130:131]
	s_mov_b32 m0, s4
	ds_read_b128 v[180:183], v220 offset:16384
	ds_read_b128 v[184:187], v220 offset:17408
	ds_read_b128 v[188:191], v220 offset:18432
	ds_read_b128 v[192:195], v220 offset:19456
	ds_read_b128 v[196:199], v220 offset:20480
	ds_read_b128 v[200:203], v220 offset:21504
	ds_read_b128 v[208:211], v220 offset:22528
	ds_read_b128 v[212:215], v220 offset:23552
	global_load_lds_dwordx4 v[216:217], off
	s_add_i32 m0, s4, 0x2000
	s_add_u32 s4, s34, 0x158000
	v_lshl_add_u64 v[222:223], s[34:35], 0, v[134:135]
	s_addc_u32 s5, s35, 0
	s_add_i32 s66, s55, s40
	global_load_lds_dwordx4 v[222:223], off
	v_lshl_add_u64 v[224:225], s[4:5], 0, v[130:131]
	s_mov_b32 m0, s66
	v_lshl_add_u64 v[226:227], s[36:37], 0, v[132:133]
	global_load_lds_dwordx4 v[224:225], off
	v_lshl_add_u64 v[224:225], s[4:5], 0, v[134:135]
	s_add_i32 m0, s66, 0x2000
	s_nop 0
	global_load_lds_dwordx4 v[224:225], off
	v_lshl_add_u64 v[224:225], s[36:37], 0, v[128:129]
	s_mov_b32 m0, s41
	s_nop 0
	global_load_lds_dwordx4 v[224:225], off
	s_mov_b32 m0, s42
	s_nop 0
	global_load_lds_dwordx4 v[226:227], off
	s_waitcnt vmcnt(8)
	s_waitcnt lgkmcnt(0)
	s_barrier
; #define PG8_STAGE(bufoff, gbase, voff) do { _Pragma("unroll") for (int _i = 0; _i < 2; ++_i) \
;         __builtin_amdgcn_global_load_lds((const unsigned*)((const char*)(gbase) + (voff)[_i]), (LAS unsigned*)(lds + (bufoff) + ldsw + _i * 8192), 16, 0, 0); } while (0)
; #define PG8_LDA(dst, b, h) do { _Pragma("unroll") for (int m = 0; m < 4; ++m) _Pragma("unroll") for (int k = 0; k < 2; ++k) dst[m][k] = *(const LAS bf16x8*)(lds + PG8_SA(b, h) + aoff + m * 2048 + k * 1024); } while (0)
; #define PG8_LDB(dst, b, h) do { _Pragma("unroll") for (int n = 0; n < 2; ++n) _Pragma("unroll") for (int k = 0; k < 2; ++k) dst[n][k] = *(const LAS bf16x8*)(lds + PG8_SB(b, h) + boff + n * 2048 + k * 1024); } while (0)
; #define PG8_MMA(ai, bj, At, Bt) do { __builtin_amdgcn_s_setprio(1); _Pragma("unroll") for (int m = 0; m < 4; ++m) _Pragma("unroll") for (int n = 0; n < 2; ++n) _Pragma("unroll") for (int k = 0; k < 2; ++k) \
;         acc[ai][bj][m][n] = __builtin_amdgcn_mfma_f32_16x16x32_bf16(Bt[n][k], At[m][k], acc[ai][bj][m][n], 0, 0, 0); __builtin_amdgcn_s_setprio(0); } while (0)
; #define PG8_WAIT_V(n) asm volatile("s_waitcnt vmcnt(" #n ")" ::: "memory")
; #define PG8_WAIT_L(n) asm volatile("s_waitcnt lgkmcnt(" #n ")" ::: "memory")
; #define PG8_BAR __builtin_amdgcn_s_barrier()
; #define PG8_SCHED __builtin_amdgcn_sched_barrier(0)
; template <class Epi>
; __device__ __forceinline__ void gemm_phase(LAS unsigned char* lds, const Gemm g, const StaticOrder& S, const Epi& E) {
;     ...
;             PG8_WAIT_V(8); PG8_WAIT_L(0); PG8_BAR; PG8_MMA(1, 0, At, B0); PG8_MMA(1, 1, At, B1); PG8_BAR; PG8_SCHED;
;             PG8_LDB(B0, 1, 0); PG8_LDB(B1, 1, 1); PG8_SCHED; PG8_LDA(At, 1, 0); PG8_STAGE(PG8_SA(0, 1), a2 + hstepA, voffA);
;             PG8_WAIT_V(8); PG8_WAIT_L(0); PG8_BAR; PG8_MMA(0, 0, At, B0); PG8_MMA(0, 1, At, B1); PG8_BAR; PG8_SCHED;
	s_setprio 1
	s_waitcnt lgkmcnt(0)
	v_mfma_f32_16x16x32_bf16 v[60:63], v[148:151], v[180:183], v[60:63]
	v_mfma_f32_16x16x32_bf16 v[60:63], v[152:155], v[184:187], v[60:63]
	v_mfma_f32_16x16x32_bf16 v[56:59], v[160:163], v[184:187], v[56:59]
	v_mfma_f32_16x16x32_bf16 v[56:59], v[156:159], v[180:183], v[56:59]
	v_mfma_f32_16x16x32_bf16 v[44:47], v[164:167], v[180:183], v[44:47]
	v_mfma_f32_16x16x32_bf16 v[44:47], v[168:171], v[184:187], v[44:47]
	v_mfma_f32_16x16x32_bf16 v[36:39], v[176:179], v[184:187], v[36:39]
	v_mfma_f32_16x16x32_bf16 v[36:39], v[172:175], v[180:183], v[36:39]
	s_setprio 0
	s_setprio 1
	v_mfma_f32_16x16x32_bf16 v[20:23], v[172:175], v[188:191], v[20:23]
	v_mfma_f32_16x16x32_bf16 v[20:23], v[176:179], v[192:195], v[20:23]
	v_mfma_f32_16x16x32_bf16 v[28:31], v[168:171], v[192:195], v[28:31]
	v_mfma_f32_16x16x32_bf16 v[28:31], v[164:167], v[188:191], v[28:31]
	v_mfma_f32_16x16x32_bf16 v[48:51], v[156:159], v[188:191], v[48:51]
	v_mfma_f32_16x16x32_bf16 v[48:51], v[160:163], v[192:195], v[48:51]
	v_mfma_f32_16x16x32_bf16 v[52:55], v[152:155], v[192:195], v[52:55]
	v_mfma_f32_16x16x32_bf16 v[52:55], v[148:151], v[188:191], v[52:55]
	s_setprio 0
	s_setprio 1
	v_mfma_f32_16x16x32_bf16 v[40:43], v[148:151], v[196:199], v[40:43]
	v_mfma_f32_16x16x32_bf16 v[40:43], v[152:155], v[200:203], v[40:43]
	v_mfma_f32_16x16x32_bf16 v[32:35], v[160:163], v[200:203], v[32:35]
	v_mfma_f32_16x16x32_bf16 v[32:35], v[156:159], v[196:199], v[32:35]
	v_mfma_f32_16x16x32_bf16 v[12:15], v[164:167], v[196:199], v[12:15]
	v_mfma_f32_16x16x32_bf16 v[12:15], v[168:171], v[200:203], v[12:15]
	v_mfma_f32_16x16x32_bf16 v[8:11], v[176:179], v[200:203], v[8:11]
	v_mfma_f32_16x16x32_bf16 v[8:11], v[172:175], v[196:199], v[8:11]
	s_setprio 0
	s_setprio 1
	v_mfma_f32_16x16x32_bf16 v[0:3], v[172:175], v[208:211], v[0:3]
	v_mfma_f32_16x16x32_bf16 v[0:3], v[176:179], v[212:215], v[0:3]
	v_mfma_f32_16x16x32_bf16 v[4:7], v[168:171], v[212:215], v[4:7]
	v_mfma_f32_16x16x32_bf16 v[4:7], v[164:167], v[208:211], v[4:7]
	v_mfma_f32_16x16x32_bf16 v[16:19], v[156:159], v[208:211], v[16:19]
	v_mfma_f32_16x16x32_bf16 v[16:19], v[160:163], v[212:215], v[16:19]
	v_mfma_f32_16x16x32_bf16 v[24:27], v[152:155], v[212:215], v[24:27]
	v_mfma_f32_16x16x32_bf16 v[24:27], v[148:151], v[208:211], v[24:27]
	s_setprio 0
	s_barrier
	s_add_i32 s66, 0, 0x18000
	s_add_i32 s67, 0, 0x1c000
	v_add_u32_e32 v160, s66, v207
	v_add_u32_e32 v176, s67, v207
	ds_read_b128 v[148:151], v160
	ds_read_b128 v[152:155], v160 offset:1024
	ds_read_b128 v[156:159], v160 offset:2048
	ds_read_b128 v[160:163], v160 offset:3072
	ds_read_b128 v[164:167], v176
	ds_read_b128 v[168:171], v176 offset:1024
	ds_read_b128 v[172:175], v176 offset:2048
	ds_read_b128 v[176:179], v176 offset:3072
	s_add_u32 s4, s36, 0x158000
	s_addc_u32 s5, s37, 0
	s_mov_b32 m0, s43
	v_lshl_add_u64 v[230:231], s[4:5], 0, v[128:129]
	ds_read_b128 v[180:183], v220 offset:32768
	ds_read_b128 v[184:187], v220 offset:33792
	ds_read_b128 v[188:191], v220 offset:34816
	ds_read_b128 v[192:195], v220 offset:35840
	ds_read_b128 v[196:199], v220 offset:36864
	ds_read_b128 v[200:203], v220 offset:37888
	ds_read_b128 v[208:211], v220 offset:38912
	ds_read_b128 v[212:215], v220 offset:39936
	global_load_lds_dwordx4 v[230:231], off
	v_lshl_add_u64 v[230:231], s[4:5], 0, v[132:133]
	s_mov_b32 m0, s44
	s_nop 0
	global_load_lds_dwordx4 v[230:231], off
	s_waitcnt vmcnt(8)
	s_waitcnt lgkmcnt(0)
	s_barrier
	s_setprio 1
	s_waitcnt lgkmcnt(0)
	v_mfma_f32_16x16x32_bf16 v[124:127], v[148:151], v[180:183], v[124:127]
	v_mfma_f32_16x16x32_bf16 v[124:127], v[152:155], v[184:187], v[124:127]
	v_mfma_f32_16x16x32_bf16 v[120:123], v[160:163], v[184:187], v[120:123]
	v_mfma_f32_16x16x32_bf16 v[120:123], v[156:159], v[180:183], v[120:123]
	v_mfma_f32_16x16x32_bf16 v[108:111], v[164:167], v[180:183], v[108:111]
	v_mfma_f32_16x16x32_bf16 v[108:111], v[168:171], v[184:187], v[108:111]
	v_mfma_f32_16x16x32_bf16 v[100:103], v[176:179], v[184:187], v[100:103]
	v_mfma_f32_16x16x32_bf16 v[100:103], v[172:175], v[180:183], v[100:103]
	s_setprio 0
	s_setprio 1
	v_mfma_f32_16x16x32_bf16 v[84:87], v[172:175], v[188:191], v[84:87]
	v_mfma_f32_16x16x32_bf16 v[84:87], v[176:179], v[192:195], v[84:87]
	v_mfma_f32_16x16x32_bf16 v[92:95], v[168:171], v[192:195], v[92:95]
	v_mfma_f32_16x16x32_bf16 v[92:95], v[164:167], v[188:191], v[92:95]
	v_mfma_f32_16x16x32_bf16 v[112:115], v[156:159], v[188:191], v[112:115]
	v_mfma_f32_16x16x32_bf16 v[112:115], v[160:163], v[192:195], v[112:115]
	v_mfma_f32_16x16x32_bf16 v[116:119], v[152:155], v[192:195], v[116:119]
	v_mfma_f32_16x16x32_bf16 v[116:119], v[148:151], v[188:191], v[116:119]
	s_setprio 0
	s_setprio 1
	v_mfma_f32_16x16x32_bf16 v[104:107], v[148:151], v[196:199], v[104:107]
	v_mfma_f32_16x16x32_bf16 v[104:107], v[152:155], v[200:203], v[104:107]
	v_mfma_f32_16x16x32_bf16 v[96:99], v[160:163], v[200:203], v[96:99]
	v_mfma_f32_16x16x32_bf16 v[96:99], v[156:159], v[196:199], v[96:99]
	v_mfma_f32_16x16x32_bf16 v[76:79], v[164:167], v[196:199], v[76:79]
	v_mfma_f32_16x16x32_bf16 v[76:79], v[168:171], v[200:203], v[76:79]
	v_mfma_f32_16x16x32_bf16 v[72:75], v[176:179], v[200:203], v[72:75]
	v_mfma_f32_16x16x32_bf16 v[72:75], v[172:175], v[196:199], v[72:75]
	s_setprio 0
	s_setprio 1
	v_mfma_f32_16x16x32_bf16 v[64:67], v[172:175], v[208:211], v[64:67]
	v_mfma_f32_16x16x32_bf16 v[64:67], v[176:179], v[212:215], v[64:67]
	v_mfma_f32_16x16x32_bf16 v[68:71], v[168:171], v[212:215], v[68:71]
	v_mfma_f32_16x16x32_bf16 v[68:71], v[164:167], v[208:211], v[68:71]
	v_mfma_f32_16x16x32_bf16 v[80:83], v[156:159], v[208:211], v[80:83]
	v_mfma_f32_16x16x32_bf16 v[80:83], v[160:163], v[212:215], v[80:83]
	v_mfma_f32_16x16x32_bf16 v[88:91], v[152:155], v[212:215], v[88:91]
	v_mfma_f32_16x16x32_bf16 v[88:91], v[148:151], v[208:211], v[88:91]
	s_setprio 0
	s_barrier
; #define PG8_STAGE(bufoff, gbase, voff) do { _Pragma("unroll") for (int _i = 0; _i < 2; ++_i) \
;         __builtin_amdgcn_global_load_lds((const unsigned*)((const char*)(gbase) + (voff)[_i]), (LAS unsigned*)(lds + (bufoff) + ldsw + _i * 8192), 16, 0, 0); } while (0)
; #define PG8_LDA(dst, b, h) do { _Pragma("unroll") for (int m = 0; m < 4; ++m) _Pragma("unroll") for (int k = 0; k < 2; ++k) dst[m][k] = *(const LAS bf16x8*)(lds + PG8_SA(b, h) + aoff + m * 2048 + k * 1024); } while (0)
; #define PG8_MMA(ai, bj, At, Bt) do { __builtin_amdgcn_s_setprio(1); _Pragma("unroll") for (int m = 0; m < 4; ++m) _Pragma("unroll") for (int n = 0; n < 2; ++n) _Pragma("unroll") for (int k = 0; k < 2; ++k) \
;         acc[ai][bj][m][n] = __builtin_amdgcn_mfma_f32_16x16x32_bf16(Bt[n][k], At[m][k], acc[ai][bj][m][n], 0, 0, 0); __builtin_amdgcn_s_setprio(0); } while (0)
; #define PG8_WAIT_V(n) asm volatile("s_waitcnt vmcnt(" #n ")" ::: "memory")
; #define PG8_WAIT_L(n) asm volatile("s_waitcnt lgkmcnt(" #n ")" ::: "memory")
; #define PG8_BAR __builtin_amdgcn_s_barrier()
; #define PG8_SCHED __builtin_amdgcn_sched_barrier(0)
; template <class Epi>
; __device__ __forceinline__ void gemm_phase(LAS unsigned char* lds, const Gemm g, const StaticOrder& S, const Epi& E) {
;     ...
;         for (int t = 0; t < nt; t += 2) {
;             const bool last = (t == nt - 2);
;             const char* a1 = cA + (size_t)(t + 1) * kstep;
;             const char* a2 = last ? nA : cA + (size_t)(t + 2) * kstep; const char* b2 = last ? nB : cB + (size_t)(t + 2) * kstep;
;             const char* a3 = a2 + kstep; const char* b3 = b2 + kstep;
;     ...
;             PG8_LDA(At, 1, 1); PG8_STAGE(PG8_SB(1, 0), b3, voffB); PG8_STAGE(PG8_SB(1, 1), b3 + hstepB, voffB); PG8_STAGE(PG8_SA(1, 0), a3, voffA);
;             PG8_WAIT_V(8); PG8_WAIT_L(0); PG8_BAR; PG8_MMA(1, 0, At, B0); PG8_MMA(1, 1, At, B1); PG8_BAR; PG8_SCHED;
;         }
	s_add_i32 s4, s66, s40
	v_lshl_add_u64 v[216:217], v[216:217], 0, s[16:17]
	s_mov_b32 m0, s4
	ds_read_b128 v[180:183], v220 offset:49152
	ds_read_b128 v[184:187], v220 offset:50176
	ds_read_b128 v[188:191], v220 offset:51200
	ds_read_b128 v[192:195], v220 offset:52224
	ds_read_b128 v[196:199], v220 offset:53248
	ds_read_b128 v[200:203], v220 offset:54272
	ds_read_b128 v[208:211], v220 offset:55296
	ds_read_b128 v[212:215], v220 offset:56320
	global_load_lds_dwordx4 v[216:217], off
	s_add_i32 m0, s4, 0x2000
	s_add_u32 s4, s34, 0x158080
	v_lshl_add_u64 v[216:217], v[222:223], 0, s[16:17]
	s_addc_u32 s5, s35, 0
	s_add_i32 s34, s67, s40
	global_load_lds_dwordx4 v[216:217], off
	v_lshl_add_u64 v[216:217], s[4:5], 0, v[130:131]
	s_mov_b32 m0, s34
	s_nop 0
	global_load_lds_dwordx4 v[216:217], off
	v_lshl_add_u64 v[216:217], s[4:5], 0, v[134:135]
	s_add_i32 m0, s34, 0x2000
	s_nop 0
	global_load_lds_dwordx4 v[216:217], off
	v_lshl_add_u64 v[216:217], v[224:225], 0, s[16:17]
	s_mov_b32 m0, s47
	s_nop 0
	global_load_lds_dwordx4 v[216:217], off
	v_lshl_add_u64 v[216:217], v[226:227], 0, s[16:17]
	s_mov_b32 m0, s48
	s_nop 0
	global_load_lds_dwordx4 v[216:217], off
	s_waitcnt vmcnt(8)
	s_waitcnt lgkmcnt(0)
	s_barrier
	s_setprio 1
	s_waitcnt lgkmcnt(0)
	v_mfma_f32_16x16x32_bf16 v[60:63], v[148:151], v[180:183], v[60:63]
	v_mfma_f32_16x16x32_bf16 v[60:63], v[152:155], v[184:187], v[60:63]
	v_mfma_f32_16x16x32_bf16 v[56:59], v[160:163], v[184:187], v[56:59]
	v_mfma_f32_16x16x32_bf16 v[56:59], v[156:159], v[180:183], v[56:59]
	v_mfma_f32_16x16x32_bf16 v[44:47], v[164:167], v[180:183], v[44:47]
	v_mfma_f32_16x16x32_bf16 v[44:47], v[168:171], v[184:187], v[44:47]
	v_mfma_f32_16x16x32_bf16 v[36:39], v[176:179], v[184:187], v[36:39]
	v_mfma_f32_16x16x32_bf16 v[36:39], v[172:175], v[180:183], v[36:39]
	s_setprio 0
	s_setprio 1
	v_mfma_f32_16x16x32_bf16 v[20:23], v[172:175], v[188:191], v[20:23]
	v_mfma_f32_16x16x32_bf16 v[20:23], v[176:179], v[192:195], v[20:23]
	v_mfma_f32_16x16x32_bf16 v[28:31], v[168:171], v[192:195], v[28:31]
	v_mfma_f32_16x16x32_bf16 v[28:31], v[164:167], v[188:191], v[28:31]
	v_mfma_f32_16x16x32_bf16 v[48:51], v[156:159], v[188:191], v[48:51]
	v_mfma_f32_16x16x32_bf16 v[48:51], v[160:163], v[192:195], v[48:51]
	v_mfma_f32_16x16x32_bf16 v[52:55], v[152:155], v[192:195], v[52:55]
	v_mfma_f32_16x16x32_bf16 v[52:55], v[148:151], v[188:191], v[52:55]
	s_setprio 0
	s_setprio 1
	v_mfma_f32_16x16x32_bf16 v[40:43], v[148:151], v[196:199], v[40:43]
	v_mfma_f32_16x16x32_bf16 v[40:43], v[152:155], v[200:203], v[40:43]
	v_mfma_f32_16x16x32_bf16 v[32:35], v[160:163], v[200:203], v[32:35]
	v_mfma_f32_16x16x32_bf16 v[32:35], v[156:159], v[196:199], v[32:35]
	v_mfma_f32_16x16x32_bf16 v[12:15], v[164:167], v[196:199], v[12:15]
	v_mfma_f32_16x16x32_bf16 v[12:15], v[168:171], v[200:203], v[12:15]
	v_mfma_f32_16x16x32_bf16 v[8:11], v[176:179], v[200:203], v[8:11]
	v_mfma_f32_16x16x32_bf16 v[8:11], v[172:175], v[196:199], v[8:11]
	s_setprio 0
	s_setprio 1
	v_mfma_f32_16x16x32_bf16 v[0:3], v[172:175], v[208:211], v[0:3]
	v_mfma_f32_16x16x32_bf16 v[0:3], v[176:179], v[212:215], v[0:3]
	v_mfma_f32_16x16x32_bf16 v[4:7], v[168:171], v[212:215], v[4:7]
	v_mfma_f32_16x16x32_bf16 v[4:7], v[164:167], v[208:211], v[4:7]
	v_mfma_f32_16x16x32_bf16 v[16:19], v[156:159], v[208:211], v[16:19]
	v_mfma_f32_16x16x32_bf16 v[16:19], v[160:163], v[212:215], v[16:19]
	v_mfma_f32_16x16x32_bf16 v[24:27], v[152:155], v[212:215], v[24:27]
	v_mfma_f32_16x16x32_bf16 v[24:27], v[148:151], v[208:211], v[24:27]
	s_setprio 0
	s_barrier
	s_add_u32 s1, s1, 0x100
	s_addc_u32 s64, s64, 0
	s_cmp_ge_i32 s65, s46
	s_mov_b64 s[4:5], s[30:31]
	s_mov_b32 s34, s65
	s_cbranch_scc0 .LBB0_445
;     __device__ __forceinline__ void operator()(Acc& acc, const Unit& u, int wr, int wc, int fr, int fq) const {
;         const size_t off0 = ((size_t)u.pm * BM + wr * 64 + fr) * DM + u.pn * BM + wc * 32 + 8 * fq;
;         u32x4 pa[2][2], pb[2][2];
	v_pk_mul_f32 v[164:165], v[126:127], 0.5 op_sel_hi:[1,0]
	v_pk_mul_f32 v[200:201], v[124:125], 0.5 op_sel_hi:[1,0]
	v_pk_mul_f32 v[202:203], v[122:123], 0.5 op_sel_hi:[1,0]
	v_pk_mul_f32 v[208:209], v[120:121], 0.5 op_sel_hi:[1,0]
	v_pk_mul_f32 v[210:211], v[110:111], 0.5 op_sel_hi:[1,0]
	v_pk_mul_f32 v[212:213], v[108:109], 0.5 op_sel_hi:[1,0]
	v_pk_mul_f32 v[214:215], v[102:103], 0.5 op_sel_hi:[1,0]
	v_pk_mul_f32 v[216:217], v[100:101], 0.5 op_sel_hi:[1,0]
	v_pk_mul_f32 v[188:189], v[118:119], 0.5 op_sel_hi:[1,0]
	v_pk_mul_f32 v[186:187], v[116:117], 0.5 op_sel_hi:[1,0]
	v_pk_mul_f32 v[184:185], v[114:115], 0.5 op_sel_hi:[1,0]
	v_pk_mul_f32 v[182:183], v[112:113], 0.5 op_sel_hi:[1,0]
	v_pk_mul_f32 v[196:197], v[94:95], 0.5 op_sel_hi:[1,0]
	v_pk_mul_f32 v[194:195], v[92:93], 0.5 op_sel_hi:[1,0]
	v_pk_mul_f32 v[192:193], v[86:87], 0.5 op_sel_hi:[1,0]
	v_pk_mul_f32 v[190:191], v[84:85], 0.5 op_sel_hi:[1,0]
	v_pk_mul_f32 v[166:167], v[106:107], 0.5 op_sel_hi:[1,0]
	v_pk_mul_f32 v[168:169], v[104:105], 0.5 op_sel_hi:[1,0]
	v_pk_mul_f32 v[170:171], v[98:99], 0.5 op_sel_hi:[1,0]
	v_pk_mul_f32 v[172:173], v[96:97], 0.5 op_sel_hi:[1,0]
	v_pk_mul_f32 v[174:175], v[78:79], 0.5 op_sel_hi:[1,0]
	v_pk_mul_f32 v[176:177], v[76:77], 0.5 op_sel_hi:[1,0]
	v_pk_mul_f32 v[178:179], v[74:75], 0.5 op_sel_hi:[1,0]
	v_pk_mul_f32 v[180:181], v[72:73], 0.5 op_sel_hi:[1,0]
	v_pk_mul_f32 v[154:155], v[90:91], 0.5 op_sel_hi:[1,0]
	v_pk_mul_f32 v[152:153], v[88:89], 0.5 op_sel_hi:[1,0]
	v_pk_mul_f32 v[150:151], v[82:83], 0.5 op_sel_hi:[1,0]
	v_pk_mul_f32 v[148:149], v[80:81], 0.5 op_sel_hi:[1,0]
	v_pk_mul_f32 v[162:163], v[70:71], 0.5 op_sel_hi:[1,0]
	v_pk_mul_f32 v[160:161], v[68:69], 0.5 op_sel_hi:[1,0]
	v_pk_mul_f32 v[158:159], v[66:67], 0.5 op_sel_hi:[1,0]
	v_pk_mul_f32 v[156:157], v[64:65], 0.5 op_sel_hi:[1,0]
	v_pk_mul_f32 v[112:113], v[62:63], 0.5 op_sel_hi:[1,0]
	v_pk_mul_f32 v[114:115], v[60:61], 0.5 op_sel_hi:[1,0]
	v_pk_mul_f32 v[116:117], v[58:59], 0.5 op_sel_hi:[1,0]
	v_pk_mul_f32 v[118:119], v[56:57], 0.5 op_sel_hi:[1,0]
	v_pk_mul_f32 v[120:121], v[46:47], 0.5 op_sel_hi:[1,0]
	v_pk_mul_f32 v[122:123], v[44:45], 0.5 op_sel_hi:[1,0]
	v_pk_mul_f32 v[124:125], v[38:39], 0.5 op_sel_hi:[1,0]
	v_pk_mul_f32 v[126:127], v[36:37], 0.5 op_sel_hi:[1,0]
	v_pk_mul_f32 v[102:103], v[54:55], 0.5 op_sel_hi:[1,0]
	v_pk_mul_f32 v[100:101], v[52:53], 0.5 op_sel_hi:[1,0]
	v_pk_mul_f32 v[98:99], v[50:51], 0.5 op_sel_hi:[1,0]
	v_pk_mul_f32 v[96:97], v[48:49], 0.5 op_sel_hi:[1,0]
	v_pk_mul_f32 v[110:111], v[30:31], 0.5 op_sel_hi:[1,0]
	v_pk_mul_f32 v[108:109], v[28:29], 0.5 op_sel_hi:[1,0]
	v_pk_mul_f32 v[106:107], v[22:23], 0.5 op_sel_hi:[1,0]
	v_pk_mul_f32 v[104:105], v[20:21], 0.5 op_sel_hi:[1,0]
	v_pk_mul_f32 v[86:87], v[42:43], 0.5 op_sel_hi:[1,0]
	v_pk_mul_f32 v[84:85], v[40:41], 0.5 op_sel_hi:[1,0]
	v_pk_mul_f32 v[82:83], v[34:35], 0.5 op_sel_hi:[1,0]
	v_pk_mul_f32 v[80:81], v[32:33], 0.5 op_sel_hi:[1,0]
	v_pk_mul_f32 v[94:95], v[14:15], 0.5 op_sel_hi:[1,0]
	v_pk_mul_f32 v[92:93], v[12:13], 0.5 op_sel_hi:[1,0]
	v_pk_mul_f32 v[90:91], v[10:11], 0.5 op_sel_hi:[1,0]
	v_pk_mul_f32 v[88:89], v[8:9], 0.5 op_sel_hi:[1,0]
	v_pk_mul_f32 v[70:71], v[26:27], 0.5 op_sel_hi:[1,0]
	v_pk_mul_f32 v[68:69], v[24:25], 0.5 op_sel_hi:[1,0]
	v_pk_mul_f32 v[66:67], v[18:19], 0.5 op_sel_hi:[1,0]
	v_pk_mul_f32 v[64:65], v[16:17], 0.5 op_sel_hi:[1,0]
	v_pk_mul_f32 v[78:79], v[6:7], 0.5 op_sel_hi:[1,0]
	v_pk_mul_f32 v[76:77], v[4:5], 0.5 op_sel_hi:[1,0]
	v_pk_mul_f32 v[74:75], v[2:3], 0.5 op_sel_hi:[1,0]
	v_pk_mul_f32 v[72:73], v[0:1], 0.5 op_sel_hi:[1,0]

; #define PG8_STAGE(bufoff, gbase, voff) do { _Pragma("unroll") for (int _i = 0; _i < 2; ++_i) \
;         __builtin_amdgcn_global_load_lds((const unsigned*)((const char*)(gbase) + (voff)[_i]), (LAS unsigned*)(lds + (bufoff) + ldsw + _i * 8192), 16, 0, 0); } while (0)
; #define PG8_LDA(dst, b, h) do { _Pragma("unroll") for (int m = 0; m < 4; ++m) _Pragma("unroll") for (int k = 0; k < 2; ++k) dst[m][k] = *(const LAS bf16x8*)(lds + PG8_SA(b, h) + aoff + m * 2048 + k * 1024); } while (0)
; #define PG8_LDB(dst, b, h) do { _Pragma("unroll") for (int n = 0; n < 2; ++n) _Pragma("unroll") for (int k = 0; k < 2; ++k) dst[n][k] = *(const LAS bf16x8*)(lds + PG8_SB(b, h) + boff + n * 2048 + k * 1024); } while (0)
; #define PG8_MMA(ai, bj, At, Bt) do { __builtin_amdgcn_s_setprio(1); _Pragma("unroll") for (int m = 0; m < 4; ++m) _Pragma("unroll") for (int n = 0; n < 2; ++n) _Pragma("unroll") for (int k = 0; k < 2; ++k) \
;         acc[ai][bj][m][n] = __builtin_amdgcn_mfma_f32_16x16x32_bf16(Bt[n][k], At[m][k], acc[ai][bj][m][n], 0, 0, 0); __builtin_amdgcn_s_setprio(0); } while (0)
; #define PG8_WAIT_V(n) asm volatile("s_waitcnt vmcnt(" #n ")" ::: "memory")
; #define PG8_WAIT_L(n) asm volatile("s_waitcnt lgkmcnt(" #n ")" ::: "memory")
; #define PG8_BAR __builtin_amdgcn_s_barrier()
; #define PG8_SCHED __builtin_amdgcn_sched_barrier(0)
; template <class Epi>
; __device__ __forceinline__ void gemm_phase(LAS unsigned char* lds, const Gemm g, const StaticOrder& S, const Epi& E) {
;     ...
;             const bool last = (t == nt - 2);
;             const char* a1 = cA + (size_t)(t + 1) * kstep;
;             const char* a2 = last ? nA : cA + (size_t)(t + 2) * kstep; const char* b2 = last ? nB : cB + (size_t)(t + 2) * kstep;
;             const char* a3 = a2 + kstep; const char* b3 = b2 + kstep;
;             PG8_LDB(B0, 0, 0); PG8_LDB(B1, 0, 1); PG8_SCHED; PG8_LDA(At, 0, 0); PG8_STAGE(PG8_SA(1, 1), a1 + hstepA, voffA);
;             PG8_WAIT_V(8); PG8_WAIT_L(0); PG8_BAR; PG8_MMA(0, 0, At, B0); PG8_MMA(0, 1, At, B1); PG8_BAR; PG8_SCHED;
;             PG8_LDA(At, 0, 1); PG8_STAGE(PG8_SB(0, 0), b2, voffB); PG8_STAGE(PG8_SB(0, 1), b2 + hstepB, voffB); PG8_STAGE(PG8_SA(0, 0), a2, voffA);
.LBB0_541:
	ds_read_b128 v[148:151], v155
	ds_read_b128 v[160:163], v155 offset:1024
	ds_read_b128 v[164:167], v155 offset:2048
	ds_read_b128 v[168:171], v155 offset:3072
	ds_read_b128 v[172:175], v156
	ds_read_b128 v[176:179], v156 offset:1024
	ds_read_b128 v[180:183], v156 offset:2048
	ds_read_b128 v[184:187], v156 offset:3072
	s_add_i32 s35, s26, 2
	s_add_u32 s27, s8, 0xfff80080
	s_addc_u32 s30, s9, -1
	s_cmp_eq_u32 s49, s26
	s_cselect_b32 s26, s21, s33
	s_cselect_b32 s31, s1, s30
	s_cselect_b32 s30, s5, s27
	s_cselect_b32 s27, s19, s34
	v_lshl_add_u64 v[224:225], s[8:9], 0, v[140:141]
	s_add_i32 m0, s39, 0xc000
	ds_read_b128 v[188:191], v157
	ds_read_b128 v[192:195], v157 offset:1024
	ds_read_b128 v[196:199], v157 offset:2048
	ds_read_b128 v[200:203], v157 offset:3072
	ds_read_b128 v[208:211], v157 offset:4096
	ds_read_b128 v[212:215], v157 offset:5120
	ds_read_b128 v[216:219], v157 offset:6144
	ds_read_b128 v[220:223], v157 offset:7168
	global_load_lds_dwordx4 v[224:225], off
	v_lshl_add_u64 v[224:225], s[8:9], 0, v[142:143]
	s_add_i32 m0, s39, 0xe000
	s_nop 0
	global_load_lds_dwordx4 v[224:225], off
	s_waitcnt vmcnt(8)
	s_waitcnt lgkmcnt(0)
	s_barrier
	s_setprio 1
	s_waitcnt lgkmcnt(0)
	v_mfma_f32_16x16x32_bf16 v[120:123], v[148:151], v[188:191], v[120:123]
	v_mfma_f32_16x16x32_bf16 v[120:123], v[160:163], v[192:195], v[120:123]
	v_mfma_f32_16x16x32_bf16 v[124:127], v[168:171], v[192:195], v[124:127]
	v_mfma_f32_16x16x32_bf16 v[124:127], v[164:167], v[188:191], v[124:127]
	v_mfma_f32_16x16x32_bf16 v[116:119], v[172:175], v[188:191], v[116:119]
	v_mfma_f32_16x16x32_bf16 v[116:119], v[176:179], v[192:195], v[116:119]
	v_mfma_f32_16x16x32_bf16 v[112:115], v[184:187], v[192:195], v[112:115]
	v_mfma_f32_16x16x32_bf16 v[112:115], v[180:183], v[188:191], v[112:115]
	s_setprio 0
	s_setprio 1
	v_mfma_f32_16x16x32_bf16 v[96:99], v[180:183], v[196:199], v[96:99]
	v_mfma_f32_16x16x32_bf16 v[96:99], v[184:187], v[200:203], v[96:99]
	v_mfma_f32_16x16x32_bf16 v[100:103], v[176:179], v[200:203], v[100:103]
	v_mfma_f32_16x16x32_bf16 v[100:103], v[172:175], v[196:199], v[100:103]
	v_mfma_f32_16x16x32_bf16 v[104:107], v[164:167], v[196:199], v[104:107]
	v_mfma_f32_16x16x32_bf16 v[104:107], v[168:171], v[200:203], v[104:107]
	v_mfma_f32_16x16x32_bf16 v[108:111], v[160:163], v[200:203], v[108:111]
	v_mfma_f32_16x16x32_bf16 v[108:111], v[148:151], v[196:199], v[108:111]
	s_setprio 0
	s_setprio 1
	v_mfma_f32_16x16x32_bf16 v[92:95], v[148:151], v[208:211], v[92:95]
	v_mfma_f32_16x16x32_bf16 v[92:95], v[160:163], v[212:215], v[92:95]
	v_mfma_f32_16x16x32_bf16 v[88:91], v[168:171], v[212:215], v[88:91]
	v_mfma_f32_16x16x32_bf16 v[88:91], v[164:167], v[208:211], v[88:91]
	v_mfma_f32_16x16x32_bf16 v[84:87], v[172:175], v[208:211], v[84:87]
	v_mfma_f32_16x16x32_bf16 v[84:87], v[176:179], v[212:215], v[84:87]
	v_mfma_f32_16x16x32_bf16 v[80:83], v[184:187], v[212:215], v[80:83]
	v_mfma_f32_16x16x32_bf16 v[80:83], v[180:183], v[208:211], v[80:83]
	s_setprio 0
	s_setprio 1
	v_mfma_f32_16x16x32_bf16 v[64:67], v[180:183], v[216:219], v[64:67]
	v_mfma_f32_16x16x32_bf16 v[64:67], v[184:187], v[220:223], v[64:67]
	v_mfma_f32_16x16x32_bf16 v[68:71], v[176:179], v[220:223], v[68:71]
	v_mfma_f32_16x16x32_bf16 v[68:71], v[172:175], v[216:219], v[68:71]
	v_mfma_f32_16x16x32_bf16 v[72:75], v[164:167], v[216:219], v[72:75]
	v_mfma_f32_16x16x32_bf16 v[72:75], v[168:171], v[220:223], v[72:75]
	v_mfma_f32_16x16x32_bf16 v[76:79], v[160:163], v[220:223], v[76:79]
	v_mfma_f32_16x16x32_bf16 v[76:79], v[148:151], v[216:219], v[76:79]
	s_setprio 0
	s_barrier
	s_add_i32 s58, s54, s38
	v_lshl_add_u64 v[224:225], s[26:27], 0, v[130:131]
	s_mov_b32 m0, s58
	ds_read_b128 v[188:191], v157 offset:16384
	ds_read_b128 v[192:195], v157 offset:17408
	ds_read_b128 v[196:199], v157 offset:18432
	ds_read_b128 v[200:203], v157 offset:19456
	ds_read_b128 v[208:211], v157 offset:20480
	ds_read_b128 v[212:215], v157 offset:21504
	ds_read_b128 v[216:219], v157 offset:22528
	ds_read_b128 v[220:223], v157 offset:23552
	global_load_lds_dwordx4 v[224:225], off
	s_add_i32 m0, s58, 0x2000
	s_add_u32 s58, s26, 0x80000
	v_lshl_add_u64 v[226:227], s[26:27], 0, v[134:135]
	s_addc_u32 s59, s27, 0
	s_add_i32 s60, s55, s38
	global_load_lds_dwordx4 v[226:227], off
	v_lshl_add_u64 v[230:231], s[58:59], 0, v[130:131]
	s_mov_b32 m0, s60
	v_lshl_add_u64 v[232:233], s[30:31], 0, v[132:133]
	global_load_lds_dwordx4 v[230:231], off
	v_lshl_add_u64 v[230:231], s[58:59], 0, v[134:135]
	s_add_i32 m0, s60, 0x2000
	s_nop 0
	global_load_lds_dwordx4 v[230:231], off
	v_lshl_add_u64 v[230:231], s[30:31], 0, v[128:129]
	s_mov_b32 m0, s39
	s_nop 0
	global_load_lds_dwordx4 v[230:231], off
	s_mov_b32 m0, s40
	s_nop 0
	global_load_lds_dwordx4 v[232:233], off
	s_waitcnt vmcnt(8)
	s_waitcnt lgkmcnt(0)
	s_barrier
; #define PG8_STAGE(bufoff, gbase, voff) do { _Pragma("unroll") for (int _i = 0; _i < 2; ++_i) \
;         __builtin_amdgcn_global_load_lds((const unsigned*)((const char*)(gbase) + (voff)[_i]), (LAS unsigned*)(lds + (bufoff) + ldsw + _i * 8192), 16, 0, 0); } while (0)
; #define PG8_LDA(dst, b, h) do { _Pragma("unroll") for (int m = 0; m < 4; ++m) _Pragma("unroll") for (int k = 0; k < 2; ++k) dst[m][k] = *(const LAS bf16x8*)(lds + PG8_SA(b, h) + aoff + m * 2048 + k * 1024); } while (0)
; #define PG8_LDB(dst, b, h) do { _Pragma("unroll") for (int n = 0; n < 2; ++n) _Pragma("unroll") for (int k = 0; k < 2; ++k) dst[n][k] = *(const LAS bf16x8*)(lds + PG8_SB(b, h) + boff + n * 2048 + k * 1024); } while (0)
; #define PG8_MMA(ai, bj, At, Bt) do { __builtin_amdgcn_s_setprio(1); _Pragma("unroll") for (int m = 0; m < 4; ++m) _Pragma("unroll") for (int n = 0; n < 2; ++n) _Pragma("unroll") for (int k = 0; k < 2; ++k) \
;         acc[ai][bj][m][n] = __builtin_amdgcn_mfma_f32_16x16x32_bf16(Bt[n][k], At[m][k], acc[ai][bj][m][n], 0, 0, 0); __builtin_amdgcn_s_setprio(0); } while (0)
; #define PG8_WAIT_V(n) asm volatile("s_waitcnt vmcnt(" #n ")" ::: "memory")
; #define PG8_WAIT_L(n) asm volatile("s_waitcnt lgkmcnt(" #n ")" ::: "memory")
; #define PG8_BAR __builtin_amdgcn_s_barrier()
; #define PG8_SCHED __builtin_amdgcn_sched_barrier(0)
; template <class Epi>
; __device__ __forceinline__ void gemm_phase(LAS unsigned char* lds, const Gemm g, const StaticOrder& S, const Epi& E) {
;     ...
;             PG8_WAIT_V(8); PG8_WAIT_L(0); PG8_BAR; PG8_MMA(1, 0, At, B0); PG8_MMA(1, 1, At, B1); PG8_BAR; PG8_SCHED;
;             PG8_LDB(B0, 1, 0); PG8_LDB(B1, 1, 1); PG8_SCHED; PG8_LDA(At, 1, 0); PG8_STAGE(PG8_SA(0, 1), a2 + hstepA, voffA);
;             PG8_WAIT_V(8); PG8_WAIT_L(0); PG8_BAR; PG8_MMA(0, 0, At, B0); PG8_MMA(0, 1, At, B1); PG8_BAR; PG8_SCHED;
	s_setprio 1
	s_waitcnt lgkmcnt(0)
	v_mfma_f32_16x16x32_bf16 v[60:63], v[148:151], v[188:191], v[60:63]
	v_mfma_f32_16x16x32_bf16 v[60:63], v[160:163], v[192:195], v[60:63]
	v_mfma_f32_16x16x32_bf16 v[56:59], v[168:171], v[192:195], v[56:59]
	v_mfma_f32_16x16x32_bf16 v[56:59], v[164:167], v[188:191], v[56:59]
	v_mfma_f32_16x16x32_bf16 v[52:55], v[172:175], v[188:191], v[52:55]
	v_mfma_f32_16x16x32_bf16 v[52:55], v[176:179], v[192:195], v[52:55]
	v_mfma_f32_16x16x32_bf16 v[48:51], v[184:187], v[192:195], v[48:51]
	v_mfma_f32_16x16x32_bf16 v[48:51], v[180:183], v[188:191], v[48:51]
	s_setprio 0
	s_setprio 1
	v_mfma_f32_16x16x32_bf16 v[32:35], v[180:183], v[196:199], v[32:35]
	v_mfma_f32_16x16x32_bf16 v[32:35], v[184:187], v[200:203], v[32:35]
	v_mfma_f32_16x16x32_bf16 v[36:39], v[176:179], v[200:203], v[36:39]
	v_mfma_f32_16x16x32_bf16 v[36:39], v[172:175], v[196:199], v[36:39]
	v_mfma_f32_16x16x32_bf16 v[40:43], v[164:167], v[196:199], v[40:43]
	v_mfma_f32_16x16x32_bf16 v[40:43], v[168:171], v[200:203], v[40:43]
	v_mfma_f32_16x16x32_bf16 v[44:47], v[160:163], v[200:203], v[44:47]
	v_mfma_f32_16x16x32_bf16 v[44:47], v[148:151], v[196:199], v[44:47]
	s_setprio 0
	s_setprio 1
	v_mfma_f32_16x16x32_bf16 v[28:31], v[148:151], v[208:211], v[28:31]
	v_mfma_f32_16x16x32_bf16 v[28:31], v[160:163], v[212:215], v[28:31]
	v_mfma_f32_16x16x32_bf16 v[24:27], v[168:171], v[212:215], v[24:27]
	v_mfma_f32_16x16x32_bf16 v[24:27], v[164:167], v[208:211], v[24:27]
	v_mfma_f32_16x16x32_bf16 v[20:23], v[172:175], v[208:211], v[20:23]
	v_mfma_f32_16x16x32_bf16 v[20:23], v[176:179], v[212:215], v[20:23]
	v_mfma_f32_16x16x32_bf16 v[16:19], v[184:187], v[212:215], v[16:19]
	v_mfma_f32_16x16x32_bf16 v[16:19], v[180:183], v[208:211], v[16:19]
	s_setprio 0
	s_setprio 1
	v_mfma_f32_16x16x32_bf16 v[0:3], v[180:183], v[216:219], v[0:3]
	v_mfma_f32_16x16x32_bf16 v[0:3], v[184:187], v[220:223], v[0:3]
	v_mfma_f32_16x16x32_bf16 v[4:7], v[176:179], v[220:223], v[4:7]
	v_mfma_f32_16x16x32_bf16 v[4:7], v[172:175], v[216:219], v[4:7]
	v_mfma_f32_16x16x32_bf16 v[8:11], v[164:167], v[216:219], v[8:11]
	v_mfma_f32_16x16x32_bf16 v[8:11], v[168:171], v[220:223], v[8:11]
	v_mfma_f32_16x16x32_bf16 v[12:15], v[160:163], v[220:223], v[12:15]
	v_mfma_f32_16x16x32_bf16 v[12:15], v[148:151], v[216:219], v[12:15]
	s_setprio 0
	s_barrier
	s_add_i32 s58, 0, 0x18000
	v_add_u32_e32 v136, s58, v154
	s_add_i32 s59, 0, 0x1c000
	ds_read_b128 v[148:151], v136
	ds_read_b128 v[160:163], v136 offset:1024
	ds_read_b128 v[164:167], v136 offset:2048
	ds_read_b128 v[168:171], v136 offset:3072
	v_add_u32_e32 v136, s59, v154
	ds_read_b128 v[172:175], v136
	ds_read_b128 v[176:179], v136 offset:1024
	ds_read_b128 v[180:183], v136 offset:2048
	ds_read_b128 v[184:187], v136 offset:3072
	s_add_u32 s30, s30, 0x80000
	s_addc_u32 s31, s31, 0
	s_mov_b32 m0, s41
	v_lshl_add_u64 v[234:235], s[30:31], 0, v[128:129]
	ds_read_b128 v[188:191], v157 offset:32768
	ds_read_b128 v[192:195], v157 offset:33792
	ds_read_b128 v[196:199], v157 offset:34816
	ds_read_b128 v[200:203], v157 offset:35840
	ds_read_b128 v[208:211], v157 offset:36864
	ds_read_b128 v[212:215], v157 offset:37888
	ds_read_b128 v[216:219], v157 offset:38912
	ds_read_b128 v[220:223], v157 offset:39936
	global_load_lds_dwordx4 v[234:235], off
	v_lshl_add_u64 v[234:235], s[30:31], 0, v[132:133]
	s_mov_b32 m0, s42
	s_nop 0
	global_load_lds_dwordx4 v[234:235], off
	s_waitcnt vmcnt(8)
	s_waitcnt lgkmcnt(0)
	s_barrier
	s_setprio 1
	s_waitcnt lgkmcnt(0)
	v_mfma_f32_16x16x32_bf16 v[120:123], v[148:151], v[188:191], v[120:123]
	v_mfma_f32_16x16x32_bf16 v[120:123], v[160:163], v[192:195], v[120:123]
	v_mfma_f32_16x16x32_bf16 v[124:127], v[168:171], v[192:195], v[124:127]
	v_mfma_f32_16x16x32_bf16 v[124:127], v[164:167], v[188:191], v[124:127]
	v_mfma_f32_16x16x32_bf16 v[116:119], v[172:175], v[188:191], v[116:119]
	v_mfma_f32_16x16x32_bf16 v[116:119], v[176:179], v[192:195], v[116:119]
	v_mfma_f32_16x16x32_bf16 v[112:115], v[184:187], v[192:195], v[112:115]
	v_mfma_f32_16x16x32_bf16 v[112:115], v[180:183], v[188:191], v[112:115]
	s_setprio 0
	s_setprio 1
	v_mfma_f32_16x16x32_bf16 v[96:99], v[180:183], v[196:199], v[96:99]
	v_mfma_f32_16x16x32_bf16 v[96:99], v[184:187], v[200:203], v[96:99]
	v_mfma_f32_16x16x32_bf16 v[100:103], v[176:179], v[200:203], v[100:103]
	v_mfma_f32_16x16x32_bf16 v[100:103], v[172:175], v[196:199], v[100:103]
	v_mfma_f32_16x16x32_bf16 v[104:107], v[164:167], v[196:199], v[104:107]
	v_mfma_f32_16x16x32_bf16 v[104:107], v[168:171], v[200:203], v[104:107]
	v_mfma_f32_16x16x32_bf16 v[108:111], v[160:163], v[200:203], v[108:111]
	v_mfma_f32_16x16x32_bf16 v[108:111], v[148:151], v[196:199], v[108:111]
	s_setprio 0
	s_setprio 1
	v_mfma_f32_16x16x32_bf16 v[92:95], v[148:151], v[208:211], v[92:95]
	v_mfma_f32_16x16x32_bf16 v[92:95], v[160:163], v[212:215], v[92:95]
	v_mfma_f32_16x16x32_bf16 v[88:91], v[168:171], v[212:215], v[88:91]
	v_mfma_f32_16x16x32_bf16 v[88:91], v[164:167], v[208:211], v[88:91]
	v_mfma_f32_16x16x32_bf16 v[84:87], v[172:175], v[208:211], v[84:87]
	v_mfma_f32_16x16x32_bf16 v[84:87], v[176:179], v[212:215], v[84:87]
	v_mfma_f32_16x16x32_bf16 v[80:83], v[184:187], v[212:215], v[80:83]
	v_mfma_f32_16x16x32_bf16 v[80:83], v[180:183], v[208:211], v[80:83]
	s_setprio 0
	s_setprio 1
	v_mfma_f32_16x16x32_bf16 v[64:67], v[180:183], v[216:219], v[64:67]
	v_mfma_f32_16x16x32_bf16 v[64:67], v[184:187], v[220:223], v[64:67]
	v_mfma_f32_16x16x32_bf16 v[68:71], v[176:179], v[220:223], v[68:71]
	v_mfma_f32_16x16x32_bf16 v[68:71], v[172:175], v[216:219], v[68:71]
	v_mfma_f32_16x16x32_bf16 v[72:75], v[164:167], v[216:219], v[72:75]
	v_mfma_f32_16x16x32_bf16 v[72:75], v[168:171], v[220:223], v[72:75]
	v_mfma_f32_16x16x32_bf16 v[76:79], v[160:163], v[220:223], v[76:79]
	v_mfma_f32_16x16x32_bf16 v[76:79], v[148:151], v[216:219], v[76:79]
	s_setprio 0
	s_barrier
; #define PG8_STAGE(bufoff, gbase, voff) do { _Pragma("unroll") for (int _i = 0; _i < 2; ++_i) \
;         __builtin_amdgcn_global_load_lds((const unsigned*)((const char*)(gbase) + (voff)[_i]), (LAS unsigned*)(lds + (bufoff) + ldsw + _i * 8192), 16, 0, 0); } while (0)
; #define PG8_LDA(dst, b, h) do { _Pragma("unroll") for (int m = 0; m < 4; ++m) _Pragma("unroll") for (int k = 0; k < 2; ++k) dst[m][k] = *(const LAS bf16x8*)(lds + PG8_SA(b, h) + aoff + m * 2048 + k * 1024); } while (0)
; #define PG8_MMA(ai, bj, At, Bt) do { __builtin_amdgcn_s_setprio(1); _Pragma("unroll") for (int m = 0; m < 4; ++m) _Pragma("unroll") for (int n = 0; n < 2; ++n) _Pragma("unroll") for (int k = 0; k < 2; ++k) \
;         acc[ai][bj][m][n] = __builtin_amdgcn_mfma_f32_16x16x32_bf16(Bt[n][k], At[m][k], acc[ai][bj][m][n], 0, 0, 0); __builtin_amdgcn_s_setprio(0); } while (0)
; #define PG8_WAIT_V(n) asm volatile("s_waitcnt vmcnt(" #n ")" ::: "memory")
; #define PG8_WAIT_L(n) asm volatile("s_waitcnt lgkmcnt(" #n ")" ::: "memory")
; #define PG8_BAR __builtin_amdgcn_s_barrier()
; #define PG8_SCHED __builtin_amdgcn_sched_barrier(0)
; template <class Epi>
; __device__ __forceinline__ void gemm_phase(LAS unsigned char* lds, const Gemm g, const StaticOrder& S, const Epi& E) {
;     ...
;             PG8_LDA(At, 1, 1); PG8_STAGE(PG8_SB(1, 0), b3, voffB); PG8_STAGE(PG8_SB(1, 1), b3 + hstepB, voffB); PG8_STAGE(PG8_SA(1, 0), a3, voffA);
;             PG8_WAIT_V(8); PG8_WAIT_L(0); PG8_BAR; PG8_MMA(1, 0, At, B0); PG8_MMA(1, 1, At, B1); PG8_BAR; PG8_SCHED;
;         }
	s_add_i32 s30, s58, s38
	v_lshl_add_u64 v[224:225], v[224:225], 0, s[12:13]
	s_mov_b32 m0, s30
	ds_read_b128 v[188:191], v157 offset:49152
	ds_read_b128 v[192:195], v157 offset:50176
	ds_read_b128 v[196:199], v157 offset:51200
	ds_read_b128 v[200:203], v157 offset:52224
	ds_read_b128 v[208:211], v157 offset:53248
	ds_read_b128 v[212:215], v157 offset:54272
	ds_read_b128 v[216:219], v157 offset:55296
	ds_read_b128 v[220:223], v157 offset:56320
	global_load_lds_dwordx4 v[224:225], off
	s_add_i32 m0, s30, 0x2000
	s_add_u32 s26, s26, 0x80080
	v_lshl_add_u64 v[224:225], v[226:227], 0, s[12:13]
	s_addc_u32 s27, s27, 0
	s_add_i32 s30, s59, s38
	global_load_lds_dwordx4 v[224:225], off
	v_lshl_add_u64 v[224:225], s[26:27], 0, v[130:131]
	s_mov_b32 m0, s30
	s_nop 0
	global_load_lds_dwordx4 v[224:225], off
	v_lshl_add_u64 v[224:225], s[26:27], 0, v[134:135]
	s_add_i32 m0, s30, 0x2000
	s_nop 0
	global_load_lds_dwordx4 v[224:225], off
	v_lshl_add_u64 v[224:225], v[230:231], 0, s[12:13]
	s_mov_b32 m0, s47
	s_nop 0
	global_load_lds_dwordx4 v[224:225], off
	v_lshl_add_u64 v[224:225], v[232:233], 0, s[12:13]
	s_mov_b32 m0, s48
	s_nop 0
	global_load_lds_dwordx4 v[224:225], off
	s_waitcnt vmcnt(8)
	s_waitcnt lgkmcnt(0)
	s_barrier
	s_setprio 1
	s_waitcnt lgkmcnt(0)
	v_mfma_f32_16x16x32_bf16 v[60:63], v[148:151], v[188:191], v[60:63]
	v_mfma_f32_16x16x32_bf16 v[60:63], v[160:163], v[192:195], v[60:63]
	v_mfma_f32_16x16x32_bf16 v[56:59], v[168:171], v[192:195], v[56:59]
	v_mfma_f32_16x16x32_bf16 v[56:59], v[164:167], v[188:191], v[56:59]
	v_mfma_f32_16x16x32_bf16 v[52:55], v[172:175], v[188:191], v[52:55]
	v_mfma_f32_16x16x32_bf16 v[52:55], v[176:179], v[192:195], v[52:55]
	v_mfma_f32_16x16x32_bf16 v[48:51], v[184:187], v[192:195], v[48:51]
	v_mfma_f32_16x16x32_bf16 v[48:51], v[180:183], v[188:191], v[48:51]
	s_setprio 0
	s_setprio 1
	v_mfma_f32_16x16x32_bf16 v[32:35], v[180:183], v[196:199], v[32:35]
	v_mfma_f32_16x16x32_bf16 v[32:35], v[184:187], v[200:203], v[32:35]
	v_mfma_f32_16x16x32_bf16 v[36:39], v[176:179], v[200:203], v[36:39]
	v_mfma_f32_16x16x32_bf16 v[36:39], v[172:175], v[196:199], v[36:39]
	v_mfma_f32_16x16x32_bf16 v[40:43], v[164:167], v[196:199], v[40:43]
	v_mfma_f32_16x16x32_bf16 v[40:43], v[168:171], v[200:203], v[40:43]
	v_mfma_f32_16x16x32_bf16 v[44:47], v[160:163], v[200:203], v[44:47]
	v_mfma_f32_16x16x32_bf16 v[44:47], v[148:151], v[196:199], v[44:47]
	s_setprio 0
	s_setprio 1
	v_mfma_f32_16x16x32_bf16 v[28:31], v[148:151], v[208:211], v[28:31]
	v_mfma_f32_16x16x32_bf16 v[28:31], v[160:163], v[212:215], v[28:31]
	v_mfma_f32_16x16x32_bf16 v[24:27], v[168:171], v[212:215], v[24:27]
	v_mfma_f32_16x16x32_bf16 v[24:27], v[164:167], v[208:211], v[24:27]
	v_mfma_f32_16x16x32_bf16 v[20:23], v[172:175], v[208:211], v[20:23]
	v_mfma_f32_16x16x32_bf16 v[20:23], v[176:179], v[212:215], v[20:23]
	v_mfma_f32_16x16x32_bf16 v[16:19], v[184:187], v[212:215], v[16:19]
	v_mfma_f32_16x16x32_bf16 v[16:19], v[180:183], v[208:211], v[16:19]
	s_setprio 0
	s_setprio 1
	v_mfma_f32_16x16x32_bf16 v[0:3], v[180:183], v[216:219], v[0:3]
	v_mfma_f32_16x16x32_bf16 v[0:3], v[184:187], v[220:223], v[0:3]
	v_mfma_f32_16x16x32_bf16 v[4:7], v[176:179], v[220:223], v[4:7]
	v_mfma_f32_16x16x32_bf16 v[4:7], v[172:175], v[216:219], v[4:7]
	v_mfma_f32_16x16x32_bf16 v[8:11], v[164:167], v[216:219], v[8:11]
	v_mfma_f32_16x16x32_bf16 v[8:11], v[168:171], v[220:223], v[8:11]
	v_mfma_f32_16x16x32_bf16 v[12:15], v[160:163], v[220:223], v[12:15]
	v_mfma_f32_16x16x32_bf16 v[12:15], v[148:151], v[216:219], v[12:15]
	s_setprio 0
	s_barrier
	s_add_u32 s8, s8, 0x100
	s_addc_u32 s9, s9, 0
	s_add_u32 s33, s33, 0x100
	s_addc_u32 s34, s34, 0
	s_cmp_ge_i32 s35, s44
	s_mov_b32 s26, s35
	s_cbranch_scc0 .LBB0_541

; #define PG8_STAGE(bufoff, gbase, voff) do { _Pragma("unroll") for (int _i = 0; _i < 2; ++_i) \
;         __builtin_amdgcn_global_load_lds((const unsigned*)((const char*)(gbase) + (voff)[_i]), (LAS unsigned*)(lds + (bufoff) + ldsw + _i * 8192), 16, 0, 0); } while (0)
; #define PG8_LDA(dst, b, h) do { _Pragma("unroll") for (int m = 0; m < 4; ++m) _Pragma("unroll") for (int k = 0; k < 2; ++k) dst[m][k] = *(const LAS bf16x8*)(lds + PG8_SA(b, h) + aoff + m * 2048 + k * 1024); } while (0)
; #define PG8_LDB(dst, b, h) do { _Pragma("unroll") for (int n = 0; n < 2; ++n) _Pragma("unroll") for (int k = 0; k < 2; ++k) dst[n][k] = *(const LAS bf16x8*)(lds + PG8_SB(b, h) + boff + n * 2048 + k * 1024); } while (0)
; #define PG8_MMA(ai, bj, At, Bt) do { __builtin_amdgcn_s_setprio(1); _Pragma("unroll") for (int m = 0; m < 4; ++m) _Pragma("unroll") for (int n = 0; n < 2; ++n) _Pragma("unroll") for (int k = 0; k < 2; ++k) \
;         acc[ai][bj][m][n] = __builtin_amdgcn_mfma_f32_16x16x32_bf16(Bt[n][k], At[m][k], acc[ai][bj][m][n], 0, 0, 0); __builtin_amdgcn_s_setprio(0); } while (0)
; #define PG8_WAIT_V(n) asm volatile("s_waitcnt vmcnt(" #n ")" ::: "memory")
; #define PG8_WAIT_L(n) asm volatile("s_waitcnt lgkmcnt(" #n ")" ::: "memory")
; #define PG8_BAR __builtin_amdgcn_s_barrier()
; #define PG8_SCHED __builtin_amdgcn_sched_barrier(0)
; template <class Epi>
; __device__ __forceinline__ void gemm_phase(LAS unsigned char* lds, const Gemm g, const StaticOrder& S, const Epi& E) {
;     ...
;         for (int t = 0; t < nt; t += 2) {
;             const bool last = (t == nt - 2);
;             const char* a1 = cA + (size_t)(t + 1) * kstep;
;             const char* a2 = last ? nA : cA + (size_t)(t + 2) * kstep; const char* b2 = last ? nB : cB + (size_t)(t + 2) * kstep;
;             const char* a3 = a2 + kstep; const char* b3 = b2 + kstep;
;             PG8_LDB(B0, 0, 0); PG8_LDB(B1, 0, 1); PG8_SCHED; PG8_LDA(At, 0, 0); PG8_STAGE(PG8_SA(1, 1), a1 + hstepA, voffA);
;             PG8_WAIT_V(8); PG8_WAIT_L(0); PG8_BAR; PG8_MMA(0, 0, At, B0); PG8_MMA(0, 1, At, B1); PG8_BAR; PG8_SCHED;
;             PG8_LDA(At, 0, 1); PG8_STAGE(PG8_SB(0, 0), b2, voffB); PG8_STAGE(PG8_SB(0, 1), b2 + hstepB, voffB); PG8_STAGE(PG8_SA(0, 0), a2, voffA);
;             PG8_WAIT_V(8); PG8_WAIT_L(0); PG8_BAR; PG8_MMA(1, 0, At, B0); PG8_MMA(1, 1, At, B1); PG8_BAR; PG8_SCHED;
.LBB0_685:
	ds_read_b128 v[88:91], v85
	ds_read_b128 v[92:95], v85 offset:1024
	ds_read_b128 v[96:99], v85 offset:2048
	ds_read_b128 v[100:103], v85 offset:3072
	s_add_i32 s61, s34, 2
	s_add_u32 s8, s30, 0x100
	s_addc_u32 s9, s31, 0
	s_cmp_eq_u32 s53, s34
	s_cselect_b32 s34, s25, s59
	s_cselect_b32 s37, s27, s9
	s_cselect_b32 s36, s26, s8
	s_cselect_b32 s35, s17, s60
	v_lshl_add_u64 v[136:137], s[30:31], 0, v[76:77]
	s_add_i32 m0, s40, 0xc000
	ds_read_b128 v[104:107], v86
	ds_read_b128 v[108:111], v86 offset:1024
	ds_read_b128 v[112:115], v86 offset:2048
	ds_read_b128 v[116:119], v86 offset:3072
	ds_read_b128 v[120:123], v86 offset:4096
	ds_read_b128 v[124:127], v86 offset:5120
	ds_read_b128 v[128:131], v86 offset:6144
	ds_read_b128 v[132:135], v86 offset:7168
	global_load_lds_dwordx4 v[136:137], off
	v_lshl_add_u64 v[136:137], s[30:31], 0, v[78:79]
	s_add_i32 m0, s40, 0xe000
	s_nop 0
	global_load_lds_dwordx4 v[136:137], off
	s_waitcnt vmcnt(8)
	s_waitcnt lgkmcnt(0)
	s_barrier
	s_setprio 1
	s_waitcnt lgkmcnt(0)
	v_mfma_f32_16x16x32_bf16 v[60:63], v[88:91], v[104:107], v[60:63]
	v_mfma_f32_16x16x32_bf16 v[60:63], v[92:95], v[108:111], v[60:63]
	v_mfma_f32_16x16x32_bf16 v[56:59], v[100:103], v[108:111], v[56:59]
	v_mfma_f32_16x16x32_bf16 v[56:59], v[96:99], v[104:107], v[56:59]
	v_mfma_f32_16x16x32_bf16 v[48:51], v[96:99], v[112:115], v[48:51]
	v_mfma_f32_16x16x32_bf16 v[48:51], v[100:103], v[116:119], v[48:51]
	v_mfma_f32_16x16x32_bf16 v[52:55], v[92:95], v[116:119], v[52:55]
	v_mfma_f32_16x16x32_bf16 v[52:55], v[88:91], v[112:115], v[52:55]
	s_setprio 0
	s_setprio 1
	v_mfma_f32_16x16x32_bf16 v[44:47], v[88:91], v[120:123], v[44:47]
	v_mfma_f32_16x16x32_bf16 v[44:47], v[92:95], v[124:127], v[44:47]
	v_mfma_f32_16x16x32_bf16 v[40:43], v[100:103], v[124:127], v[40:43]
	v_mfma_f32_16x16x32_bf16 v[40:43], v[96:99], v[120:123], v[40:43]
	v_mfma_f32_16x16x32_bf16 v[32:35], v[96:99], v[128:131], v[32:35]
	v_mfma_f32_16x16x32_bf16 v[32:35], v[100:103], v[132:135], v[32:35]
	v_mfma_f32_16x16x32_bf16 v[36:39], v[92:95], v[132:135], v[36:39]
	v_mfma_f32_16x16x32_bf16 v[36:39], v[88:91], v[128:131], v[36:39]
	s_setprio 0
	s_setprio 1
	s_setprio 0
	s_barrier
	s_add_i32 s30, s56, s39
	v_lshl_add_u64 v[136:137], s[34:35], 0, v[66:67]
	s_mov_b32 m0, s30
	ds_read_b128 v[104:107], v86 offset:16384
	ds_read_b128 v[108:111], v86 offset:17408
	ds_read_b128 v[112:115], v86 offset:18432
	ds_read_b128 v[116:119], v86 offset:19456
	ds_read_b128 v[120:123], v86 offset:20480
	ds_read_b128 v[124:127], v86 offset:21504
	ds_read_b128 v[128:131], v86 offset:22528
	ds_read_b128 v[132:135], v86 offset:23552
	global_load_lds_dwordx4 v[136:137], off
	s_add_i32 m0, s30, 0x2000
	s_add_u32 s30, s34, 0x10000
	v_lshl_add_u64 v[138:139], s[34:35], 0, v[70:71]
	s_addc_u32 s31, s35, 0
	global_load_lds_dwordx4 v[138:139], off
	v_lshl_add_u64 v[140:141], s[30:31], 0, v[66:67]
	s_mov_b32 m0, s41
	v_lshl_add_u64 v[142:143], s[36:37], 0, v[68:69]
	global_load_lds_dwordx4 v[140:141], off
	v_lshl_add_u64 v[140:141], s[30:31], 0, v[70:71]
	s_mov_b32 m0, s42
	s_nop 0
	global_load_lds_dwordx4 v[140:141], off
	v_lshl_add_u64 v[140:141], s[36:37], 0, v[64:65]
	s_mov_b32 m0, s40
	s_nop 0
	global_load_lds_dwordx4 v[140:141], off
	s_mov_b32 m0, s43
	s_nop 0
	global_load_lds_dwordx4 v[142:143], off
	s_waitcnt vmcnt(8)
	s_waitcnt lgkmcnt(0)
	s_barrier
	s_setprio 1
	s_waitcnt lgkmcnt(0)
	v_mfma_f32_16x16x32_bf16 v[28:31], v[88:91], v[104:107], v[28:31]
	v_mfma_f32_16x16x32_bf16 v[28:31], v[92:95], v[108:111], v[28:31]
	v_mfma_f32_16x16x32_bf16 v[24:27], v[100:103], v[108:111], v[24:27]
	v_mfma_f32_16x16x32_bf16 v[24:27], v[96:99], v[104:107], v[24:27]
	v_mfma_f32_16x16x32_bf16 v[16:19], v[96:99], v[112:115], v[16:19]
	v_mfma_f32_16x16x32_bf16 v[16:19], v[100:103], v[116:119], v[16:19]
	v_mfma_f32_16x16x32_bf16 v[20:23], v[92:95], v[116:119], v[20:23]
	v_mfma_f32_16x16x32_bf16 v[20:23], v[88:91], v[112:115], v[20:23]
	s_setprio 0
	s_setprio 1
	v_mfma_f32_16x16x32_bf16 v[12:15], v[88:91], v[120:123], v[12:15]
	v_mfma_f32_16x16x32_bf16 v[12:15], v[92:95], v[124:127], v[12:15]
	v_mfma_f32_16x16x32_bf16 v[8:11], v[100:103], v[124:127], v[8:11]
	v_mfma_f32_16x16x32_bf16 v[8:11], v[96:99], v[120:123], v[8:11]
	v_mfma_f32_16x16x32_bf16 v[0:3], v[96:99], v[128:131], v[0:3]
	v_mfma_f32_16x16x32_bf16 v[0:3], v[100:103], v[132:135], v[0:3]
	v_mfma_f32_16x16x32_bf16 v[4:7], v[92:95], v[132:135], v[4:7]
	v_mfma_f32_16x16x32_bf16 v[4:7], v[88:91], v[128:131], v[4:7]
	s_setprio 0
	s_setprio 1
	s_setprio 0
	s_barrier
; #define PG8_STAGE(bufoff, gbase, voff) do { _Pragma("unroll") for (int _i = 0; _i < 2; ++_i) \
;         __builtin_amdgcn_global_load_lds((const unsigned*)((const char*)(gbase) + (voff)[_i]), (LAS unsigned*)(lds + (bufoff) + ldsw + _i * 8192), 16, 0, 0); } while (0)
; #define PG8_LDA(dst, b, h) do { _Pragma("unroll") for (int m = 0; m < 4; ++m) _Pragma("unroll") for (int k = 0; k < 2; ++k) dst[m][k] = *(const LAS bf16x8*)(lds + PG8_SA(b, h) + aoff + m * 2048 + k * 1024); } while (0)
; #define PG8_LDB(dst, b, h) do { _Pragma("unroll") for (int n = 0; n < 2; ++n) _Pragma("unroll") for (int k = 0; k < 2; ++k) dst[n][k] = *(const LAS bf16x8*)(lds + PG8_SB(b, h) + boff + n * 2048 + k * 1024); } while (0)
; #define PG8_MMA(ai, bj, At, Bt) do { __builtin_amdgcn_s_setprio(1); _Pragma("unroll") for (int m = 0; m < 4; ++m) _Pragma("unroll") for (int n = 0; n < 2; ++n) _Pragma("unroll") for (int k = 0; k < 2; ++k) \
;         acc[ai][bj][m][n] = __builtin_amdgcn_mfma_f32_16x16x32_bf16(Bt[n][k], At[m][k], acc[ai][bj][m][n], 0, 0, 0); __builtin_amdgcn_s_setprio(0); } while (0)
; #define PG8_WAIT_V(n) asm volatile("s_waitcnt vmcnt(" #n ")" ::: "memory")
; #define PG8_WAIT_L(n) asm volatile("s_waitcnt lgkmcnt(" #n ")" ::: "memory")
; #define PG8_BAR __builtin_amdgcn_s_barrier()
; #define PG8_SCHED __builtin_amdgcn_sched_barrier(0)
; template <class Epi>
; __device__ __forceinline__ void gemm_phase(LAS unsigned char* lds, const Gemm g, const StaticOrder& S, const Epi& E) {
;     ...
;             PG8_LDB(B0, 1, 0); PG8_LDB(B1, 1, 1); PG8_SCHED; PG8_LDA(At, 1, 0); PG8_STAGE(PG8_SA(0, 1), a2 + hstepA, voffA);
;             PG8_WAIT_V(8); PG8_WAIT_L(0); PG8_BAR; PG8_MMA(0, 0, At, B0); PG8_MMA(0, 1, At, B1); PG8_BAR; PG8_SCHED;
;             PG8_LDA(At, 1, 1); PG8_STAGE(PG8_SB(1, 0), b3, voffB); PG8_STAGE(PG8_SB(1, 1), b3 + hstepB, voffB); PG8_STAGE(PG8_SA(1, 0), a3, voffA);
;             PG8_WAIT_V(8); PG8_WAIT_L(0); PG8_BAR; PG8_MMA(1, 0, At, B0); PG8_MMA(1, 1, At, B1); PG8_BAR; PG8_SCHED;
;         }
	s_add_i32 s62, 0, 0x18000
	v_add_u32_e32 v87, s62, v84
	ds_read_b128 v[88:91], v87
	ds_read_b128 v[92:95], v87 offset:1024
	ds_read_b128 v[96:99], v87 offset:2048
	ds_read_b128 v[100:103], v87 offset:3072
	s_add_u32 s30, s36, 0x18000
	s_addc_u32 s31, s37, 0
	s_mov_b32 m0, s44
	v_lshl_add_u64 v[144:145], s[30:31], 0, v[64:65]
	ds_read_b128 v[104:107], v86 offset:32768
	ds_read_b128 v[108:111], v86 offset:33792
	ds_read_b128 v[112:115], v86 offset:34816
	ds_read_b128 v[116:119], v86 offset:35840
	ds_read_b128 v[120:123], v86 offset:36864
	ds_read_b128 v[124:127], v86 offset:37888
	ds_read_b128 v[128:131], v86 offset:38912
	ds_read_b128 v[132:135], v86 offset:39936
	global_load_lds_dwordx4 v[144:145], off
	v_lshl_add_u64 v[144:145], s[30:31], 0, v[68:69]
	s_mov_b32 m0, s45
	s_nop 0
	global_load_lds_dwordx4 v[144:145], off
	s_waitcnt vmcnt(8)
	s_waitcnt lgkmcnt(0)
	s_barrier
	s_setprio 1
	s_waitcnt lgkmcnt(0)
	v_mfma_f32_16x16x32_bf16 v[60:63], v[88:91], v[104:107], v[60:63]
	v_mfma_f32_16x16x32_bf16 v[60:63], v[92:95], v[108:111], v[60:63]
	v_mfma_f32_16x16x32_bf16 v[56:59], v[100:103], v[108:111], v[56:59]
	v_mfma_f32_16x16x32_bf16 v[56:59], v[96:99], v[104:107], v[56:59]
	v_mfma_f32_16x16x32_bf16 v[48:51], v[96:99], v[112:115], v[48:51]
	v_mfma_f32_16x16x32_bf16 v[48:51], v[100:103], v[116:119], v[48:51]
	v_mfma_f32_16x16x32_bf16 v[52:55], v[92:95], v[116:119], v[52:55]
	v_mfma_f32_16x16x32_bf16 v[52:55], v[88:91], v[112:115], v[52:55]
	s_setprio 0
	s_setprio 1
	v_mfma_f32_16x16x32_bf16 v[44:47], v[88:91], v[120:123], v[44:47]
	v_mfma_f32_16x16x32_bf16 v[44:47], v[92:95], v[124:127], v[44:47]
	v_mfma_f32_16x16x32_bf16 v[40:43], v[100:103], v[124:127], v[40:43]
	v_mfma_f32_16x16x32_bf16 v[40:43], v[96:99], v[120:123], v[40:43]
	v_mfma_f32_16x16x32_bf16 v[32:35], v[96:99], v[128:131], v[32:35]
	v_mfma_f32_16x16x32_bf16 v[32:35], v[100:103], v[132:135], v[32:35]
	v_mfma_f32_16x16x32_bf16 v[36:39], v[92:95], v[132:135], v[36:39]
	v_mfma_f32_16x16x32_bf16 v[36:39], v[88:91], v[128:131], v[36:39]
	s_setprio 0
	s_setprio 1
	s_setprio 0
	s_barrier
	s_add_i32 s30, s62, s39
	v_lshl_add_u64 v[136:137], v[136:137], 0, s[10:11]
	s_mov_b32 m0, s30
	ds_read_b128 v[104:107], v86 offset:49152
	ds_read_b128 v[108:111], v86 offset:50176
	ds_read_b128 v[112:115], v86 offset:51200
	ds_read_b128 v[116:119], v86 offset:52224
	ds_read_b128 v[120:123], v86 offset:53248
	ds_read_b128 v[124:127], v86 offset:54272
	ds_read_b128 v[128:131], v86 offset:55296
	ds_read_b128 v[132:135], v86 offset:56320
	global_load_lds_dwordx4 v[136:137], off
	s_add_i32 m0, s30, 0x2000
	s_add_u32 s30, s34, 0x10080
	v_lshl_add_u64 v[136:137], v[138:139], 0, s[10:11]
	s_addc_u32 s31, s35, 0
	global_load_lds_dwordx4 v[136:137], off
	v_lshl_add_u64 v[136:137], s[30:31], 0, v[66:67]
	s_mov_b32 m0, s49
	s_nop 0
	global_load_lds_dwordx4 v[136:137], off
	v_lshl_add_u64 v[136:137], s[30:31], 0, v[70:71]
	s_mov_b32 m0, s52
	s_nop 0
	global_load_lds_dwordx4 v[136:137], off
	v_lshl_add_u64 v[136:137], v[140:141], 0, s[10:11]
	s_mov_b32 m0, s47
	s_nop 0
	global_load_lds_dwordx4 v[136:137], off
	v_lshl_add_u64 v[136:137], v[142:143], 0, s[10:11]
	s_mov_b32 m0, s48
	s_nop 0
	global_load_lds_dwordx4 v[136:137], off
	s_waitcnt vmcnt(8)
	s_waitcnt lgkmcnt(0)
	s_barrier
	s_setprio 1
	s_waitcnt lgkmcnt(0)
	v_mfma_f32_16x16x32_bf16 v[28:31], v[88:91], v[104:107], v[28:31]
	v_mfma_f32_16x16x32_bf16 v[28:31], v[92:95], v[108:111], v[28:31]
	v_mfma_f32_16x16x32_bf16 v[24:27], v[100:103], v[108:111], v[24:27]
	v_mfma_f32_16x16x32_bf16 v[24:27], v[96:99], v[104:107], v[24:27]
	v_mfma_f32_16x16x32_bf16 v[16:19], v[96:99], v[112:115], v[16:19]
	v_mfma_f32_16x16x32_bf16 v[16:19], v[100:103], v[116:119], v[16:19]
	v_mfma_f32_16x16x32_bf16 v[20:23], v[92:95], v[116:119], v[20:23]
	v_mfma_f32_16x16x32_bf16 v[20:23], v[88:91], v[112:115], v[20:23]
	s_setprio 0
	s_setprio 1
	v_mfma_f32_16x16x32_bf16 v[12:15], v[88:91], v[120:123], v[12:15]
	v_mfma_f32_16x16x32_bf16 v[12:15], v[92:95], v[124:127], v[12:15]
	v_mfma_f32_16x16x32_bf16 v[8:11], v[100:103], v[124:127], v[8:11]
	v_mfma_f32_16x16x32_bf16 v[8:11], v[96:99], v[120:123], v[8:11]
	v_mfma_f32_16x16x32_bf16 v[0:3], v[96:99], v[128:131], v[0:3]
	v_mfma_f32_16x16x32_bf16 v[0:3], v[100:103], v[132:135], v[0:3]
	v_mfma_f32_16x16x32_bf16 v[4:7], v[92:95], v[132:135], v[4:7]
	v_mfma_f32_16x16x32_bf16 v[4:7], v[88:91], v[128:131], v[4:7]
	s_setprio 0
	s_setprio 1
	s_setprio 0
	s_barrier
	s_add_u32 s59, s59, 0x100
	s_addc_u32 s60, s60, 0
	s_cmp_ge_i32 s61, s46
	s_mov_b64 s[30:31], s[8:9]
	s_mov_b32 s34, s61
	s_cbranch_scc0 .LBB0_685

; #define PG8_STAGE(bufoff, gbase, voff) do { _Pragma("unroll") for (int _i = 0; _i < 2; ++_i) \
;         __builtin_amdgcn_global_load_lds((const unsigned*)((const char*)(gbase) + (voff)[_i]), (LAS unsigned*)(lds + (bufoff) + ldsw + _i * 8192), 16, 0, 0); } while (0)
; #define PG8_LDA(dst, b, h) do { _Pragma("unroll") for (int m = 0; m < 4; ++m) _Pragma("unroll") for (int k = 0; k < 2; ++k) dst[m][k] = *(const LAS bf16x8*)(lds + PG8_SA(b, h) + aoff + m * 2048 + k * 1024); } while (0)
; #define PG8_LDB(dst, b, h) do { _Pragma("unroll") for (int n = 0; n < 2; ++n) _Pragma("unroll") for (int k = 0; k < 2; ++k) dst[n][k] = *(const LAS bf16x8*)(lds + PG8_SB(b, h) + boff + n * 2048 + k * 1024); } while (0)
; #define PG8_MMA(ai, bj, At, Bt) do { __builtin_amdgcn_s_setprio(1); _Pragma("unroll") for (int m = 0; m < 4; ++m) _Pragma("unroll") for (int n = 0; n < 2; ++n) _Pragma("unroll") for (int k = 0; k < 2; ++k) \
;         acc[ai][bj][m][n] = __builtin_amdgcn_mfma_f32_16x16x32_bf16(Bt[n][k], At[m][k], acc[ai][bj][m][n], 0, 0, 0); __builtin_amdgcn_s_setprio(0); } while (0)
; #define PG8_WAIT_V(n) asm volatile("s_waitcnt vmcnt(" #n ")" ::: "memory")
; #define PG8_WAIT_L(n) asm volatile("s_waitcnt lgkmcnt(" #n ")" ::: "memory")
; #define PG8_BAR __builtin_amdgcn_s_barrier()
; #define PG8_SCHED __builtin_amdgcn_sched_barrier(0)
; template <class Epi>
; __device__ __forceinline__ void gemm_phase(LAS unsigned char* lds, const Gemm g, const StaticOrder& S, const Epi& E) {
;     ...
;         for (int t = 0; t < nt; t += 2) {
;             const bool last = (t == nt - 2);
;             const char* a1 = cA + (size_t)(t + 1) * kstep;
;             const char* a2 = last ? nA : cA + (size_t)(t + 2) * kstep; const char* b2 = last ? nB : cB + (size_t)(t + 2) * kstep;
;             const char* a3 = a2 + kstep; const char* b3 = b2 + kstep;
;             PG8_LDB(B0, 0, 0); PG8_LDB(B1, 0, 1); PG8_SCHED; PG8_LDA(At, 0, 0); PG8_STAGE(PG8_SA(1, 1), a1 + hstepA, voffA);
;             PG8_WAIT_V(8); PG8_WAIT_L(0); PG8_BAR; PG8_MMA(0, 0, At, B0); PG8_MMA(0, 1, At, B1); PG8_BAR; PG8_SCHED;
;             PG8_LDA(At, 0, 1); PG8_STAGE(PG8_SB(0, 0), b2, voffB); PG8_STAGE(PG8_SB(0, 1), b2 + hstepB, voffB); PG8_STAGE(PG8_SA(0, 0), a2, voffA);
;             PG8_WAIT_V(8); PG8_WAIT_L(0); PG8_BAR; PG8_MMA(1, 0, At, B0); PG8_MMA(1, 1, At, B1); PG8_BAR; PG8_SCHED;
.LBB0_834:
	ds_read_b128 v[156:159], v152
	ds_read_b128 v[160:163], v152 offset:1024
	ds_read_b128 v[164:167], v152 offset:2048
	ds_read_b128 v[168:171], v152 offset:3072
	ds_read_b128 v[172:175], v153
	ds_read_b128 v[176:179], v153 offset:1024
	ds_read_b128 v[180:183], v153 offset:2048
	ds_read_b128 v[184:187], v153 offset:3072
	s_add_i32 s49, s22, 2
	s_add_u32 s4, s0, 0x100
	s_addc_u32 s5, s1, 0
	s_cmp_eq_u32 s40, s22
	s_cselect_b32 s22, s20, s47
	s_cselect_b32 s25, s11, s5
	s_cselect_b32 s24, s10, s4
	s_cselect_b32 s23, s21, s48
	v_lshl_add_u64 v[224:225], s[0:1], 0, v[138:139]
	s_add_i32 m0, s29, 0xc000
	ds_read_b128 v[188:191], v154
	ds_read_b128 v[192:195], v154 offset:1024
	ds_read_b128 v[196:199], v154 offset:2048
	ds_read_b128 v[200:203], v154 offset:3072
	ds_read_b128 v[208:211], v154 offset:4096
	ds_read_b128 v[212:215], v154 offset:5120
	ds_read_b128 v[216:219], v154 offset:6144
	ds_read_b128 v[220:223], v154 offset:7168
	global_load_lds_dwordx4 v[224:225], off
	v_lshl_add_u64 v[224:225], s[0:1], 0, v[140:141]
	s_add_i32 m0, s29, 0xe000
	s_nop 0
	global_load_lds_dwordx4 v[224:225], off
	s_waitcnt vmcnt(8)
	s_waitcnt lgkmcnt(0)
	s_barrier
	s_setprio 1
	s_waitcnt lgkmcnt(0)
	v_mfma_f32_16x16x32_bf16 v[124:127], v[156:159], v[188:191], v[124:127]
	v_mfma_f32_16x16x32_bf16 v[124:127], v[160:163], v[192:195], v[124:127]
	v_mfma_f32_16x16x32_bf16 v[120:123], v[168:171], v[192:195], v[120:123]
	v_mfma_f32_16x16x32_bf16 v[120:123], v[164:167], v[188:191], v[120:123]
	v_mfma_f32_16x16x32_bf16 v[116:119], v[172:175], v[188:191], v[116:119]
	v_mfma_f32_16x16x32_bf16 v[116:119], v[176:179], v[192:195], v[116:119]
	v_mfma_f32_16x16x32_bf16 v[112:115], v[184:187], v[192:195], v[112:115]
	v_mfma_f32_16x16x32_bf16 v[112:115], v[180:183], v[188:191], v[112:115]
	s_setprio 0
	s_setprio 1
	v_mfma_f32_16x16x32_bf16 v[96:99], v[180:183], v[196:199], v[96:99]
	v_mfma_f32_16x16x32_bf16 v[96:99], v[184:187], v[200:203], v[96:99]
	v_mfma_f32_16x16x32_bf16 v[100:103], v[176:179], v[200:203], v[100:103]
	v_mfma_f32_16x16x32_bf16 v[100:103], v[172:175], v[196:199], v[100:103]
	v_mfma_f32_16x16x32_bf16 v[104:107], v[164:167], v[196:199], v[104:107]
	v_mfma_f32_16x16x32_bf16 v[104:107], v[168:171], v[200:203], v[104:107]
	v_mfma_f32_16x16x32_bf16 v[108:111], v[160:163], v[200:203], v[108:111]
	v_mfma_f32_16x16x32_bf16 v[108:111], v[156:159], v[196:199], v[108:111]
	s_setprio 0
	s_setprio 1
	v_mfma_f32_16x16x32_bf16 v[92:95], v[156:159], v[208:211], v[92:95]
	v_mfma_f32_16x16x32_bf16 v[92:95], v[160:163], v[212:215], v[92:95]
	v_mfma_f32_16x16x32_bf16 v[88:91], v[168:171], v[212:215], v[88:91]
	v_mfma_f32_16x16x32_bf16 v[88:91], v[164:167], v[208:211], v[88:91]
	v_mfma_f32_16x16x32_bf16 v[84:87], v[172:175], v[208:211], v[84:87]
	v_mfma_f32_16x16x32_bf16 v[84:87], v[176:179], v[212:215], v[84:87]
	v_mfma_f32_16x16x32_bf16 v[80:83], v[184:187], v[212:215], v[80:83]
	v_mfma_f32_16x16x32_bf16 v[80:83], v[180:183], v[208:211], v[80:83]
	s_setprio 0
	s_setprio 1
	v_mfma_f32_16x16x32_bf16 v[64:67], v[180:183], v[216:219], v[64:67]
	v_mfma_f32_16x16x32_bf16 v[64:67], v[184:187], v[220:223], v[64:67]
	v_mfma_f32_16x16x32_bf16 v[68:71], v[176:179], v[220:223], v[68:71]
	v_mfma_f32_16x16x32_bf16 v[68:71], v[172:175], v[216:219], v[68:71]
	v_mfma_f32_16x16x32_bf16 v[72:75], v[164:167], v[216:219], v[72:75]
	v_mfma_f32_16x16x32_bf16 v[72:75], v[168:171], v[220:223], v[72:75]
	v_mfma_f32_16x16x32_bf16 v[76:79], v[160:163], v[220:223], v[76:79]
	v_mfma_f32_16x16x32_bf16 v[76:79], v[156:159], v[216:219], v[76:79]
	s_setprio 0
	s_barrier
	s_add_i32 s0, s43, s28
	v_lshl_add_u64 v[224:225], s[22:23], 0, v[130:131]
	s_mov_b32 m0, s0
	ds_read_b128 v[188:191], v154 offset:16384
	ds_read_b128 v[192:195], v154 offset:17408
	ds_read_b128 v[196:199], v154 offset:18432
	ds_read_b128 v[200:203], v154 offset:19456
	ds_read_b128 v[208:211], v154 offset:20480
	ds_read_b128 v[212:215], v154 offset:21504
	ds_read_b128 v[216:219], v154 offset:22528
	ds_read_b128 v[220:223], v154 offset:23552
	global_load_lds_dwordx4 v[224:225], off
	s_add_i32 m0, s0, 0x2000
	s_add_u32 s0, s22, 0x18000
	v_lshl_add_u64 v[226:227], s[22:23], 0, v[134:135]
	s_addc_u32 s1, s23, 0
	s_add_i32 s50, s44, s28
	global_load_lds_dwordx4 v[226:227], off
	v_lshl_add_u64 v[230:231], s[0:1], 0, v[130:131]
	s_mov_b32 m0, s50
	v_lshl_add_u64 v[232:233], s[24:25], 0, v[132:133]
	global_load_lds_dwordx4 v[230:231], off
	v_lshl_add_u64 v[230:231], s[0:1], 0, v[134:135]
	s_add_i32 m0, s50, 0x2000
	s_nop 0
	global_load_lds_dwordx4 v[230:231], off
	v_lshl_add_u64 v[230:231], s[24:25], 0, v[128:129]
	s_mov_b32 m0, s29
	s_nop 0
	global_load_lds_dwordx4 v[230:231], off
	s_mov_b32 m0, s30
	s_nop 0
	global_load_lds_dwordx4 v[232:233], off
	s_waitcnt vmcnt(8)
	s_waitcnt lgkmcnt(0)
	s_barrier
; #define PG8_STAGE(bufoff, gbase, voff) do { _Pragma("unroll") for (int _i = 0; _i < 2; ++_i) \
;         __builtin_amdgcn_global_load_lds((const unsigned*)((const char*)(gbase) + (voff)[_i]), (LAS unsigned*)(lds + (bufoff) + ldsw + _i * 8192), 16, 0, 0); } while (0)
; #define PG8_LDA(dst, b, h) do { _Pragma("unroll") for (int m = 0; m < 4; ++m) _Pragma("unroll") for (int k = 0; k < 2; ++k) dst[m][k] = *(const LAS bf16x8*)(lds + PG8_SA(b, h) + aoff + m * 2048 + k * 1024); } while (0)
; #define PG8_LDB(dst, b, h) do { _Pragma("unroll") for (int n = 0; n < 2; ++n) _Pragma("unroll") for (int k = 0; k < 2; ++k) dst[n][k] = *(const LAS bf16x8*)(lds + PG8_SB(b, h) + boff + n * 2048 + k * 1024); } while (0)
; #define PG8_MMA(ai, bj, At, Bt) do { __builtin_amdgcn_s_setprio(1); _Pragma("unroll") for (int m = 0; m < 4; ++m) _Pragma("unroll") for (int n = 0; n < 2; ++n) _Pragma("unroll") for (int k = 0; k < 2; ++k) \
;         acc[ai][bj][m][n] = __builtin_amdgcn_mfma_f32_16x16x32_bf16(Bt[n][k], At[m][k], acc[ai][bj][m][n], 0, 0, 0); __builtin_amdgcn_s_setprio(0); } while (0)
; #define PG8_WAIT_V(n) asm volatile("s_waitcnt vmcnt(" #n ")" ::: "memory")
; #define PG8_WAIT_L(n) asm volatile("s_waitcnt lgkmcnt(" #n ")" ::: "memory")
; #define PG8_BAR __builtin_amdgcn_s_barrier()
; #define PG8_SCHED __builtin_amdgcn_sched_barrier(0)
; template <class Epi>
; __device__ __forceinline__ void gemm_phase(LAS unsigned char* lds, const Gemm g, const StaticOrder& S, const Epi& E) {
;     ...
;             PG8_WAIT_V(8); PG8_WAIT_L(0); PG8_BAR; PG8_MMA(1, 0, At, B0); PG8_MMA(1, 1, At, B1); PG8_BAR; PG8_SCHED;
;             PG8_LDB(B0, 1, 0); PG8_LDB(B1, 1, 1); PG8_SCHED; PG8_LDA(At, 1, 0); PG8_STAGE(PG8_SA(0, 1), a2 + hstepA, voffA);
;             PG8_WAIT_V(8); PG8_WAIT_L(0); PG8_BAR; PG8_MMA(0, 0, At, B0); PG8_MMA(0, 1, At, B1); PG8_BAR; PG8_SCHED;
	s_setprio 1
	s_waitcnt lgkmcnt(0)
	v_mfma_f32_16x16x32_bf16 v[60:63], v[156:159], v[188:191], v[60:63]
	v_mfma_f32_16x16x32_bf16 v[60:63], v[160:163], v[192:195], v[60:63]
	v_mfma_f32_16x16x32_bf16 v[56:59], v[168:171], v[192:195], v[56:59]
	v_mfma_f32_16x16x32_bf16 v[56:59], v[164:167], v[188:191], v[56:59]
	v_mfma_f32_16x16x32_bf16 v[52:55], v[172:175], v[188:191], v[52:55]
	v_mfma_f32_16x16x32_bf16 v[52:55], v[176:179], v[192:195], v[52:55]
	v_mfma_f32_16x16x32_bf16 v[48:51], v[184:187], v[192:195], v[48:51]
	v_mfma_f32_16x16x32_bf16 v[48:51], v[180:183], v[188:191], v[48:51]
	s_setprio 0
	s_setprio 1
	v_mfma_f32_16x16x32_bf16 v[32:35], v[180:183], v[196:199], v[32:35]
	v_mfma_f32_16x16x32_bf16 v[32:35], v[184:187], v[200:203], v[32:35]
	v_mfma_f32_16x16x32_bf16 v[36:39], v[176:179], v[200:203], v[36:39]
	v_mfma_f32_16x16x32_bf16 v[36:39], v[172:175], v[196:199], v[36:39]
	v_mfma_f32_16x16x32_bf16 v[40:43], v[164:167], v[196:199], v[40:43]
	v_mfma_f32_16x16x32_bf16 v[40:43], v[168:171], v[200:203], v[40:43]
	v_mfma_f32_16x16x32_bf16 v[44:47], v[160:163], v[200:203], v[44:47]
	v_mfma_f32_16x16x32_bf16 v[44:47], v[156:159], v[196:199], v[44:47]
	s_setprio 0
	s_setprio 1
	v_mfma_f32_16x16x32_bf16 v[28:31], v[156:159], v[208:211], v[28:31]
	v_mfma_f32_16x16x32_bf16 v[28:31], v[160:163], v[212:215], v[28:31]
	v_mfma_f32_16x16x32_bf16 v[24:27], v[168:171], v[212:215], v[24:27]
	v_mfma_f32_16x16x32_bf16 v[24:27], v[164:167], v[208:211], v[24:27]
	v_mfma_f32_16x16x32_bf16 v[20:23], v[172:175], v[208:211], v[20:23]
	v_mfma_f32_16x16x32_bf16 v[20:23], v[176:179], v[212:215], v[20:23]
	v_mfma_f32_16x16x32_bf16 v[16:19], v[184:187], v[212:215], v[16:19]
	v_mfma_f32_16x16x32_bf16 v[16:19], v[180:183], v[208:211], v[16:19]
	s_setprio 0
	s_setprio 1
	v_mfma_f32_16x16x32_bf16 v[0:3], v[180:183], v[216:219], v[0:3]
	v_mfma_f32_16x16x32_bf16 v[0:3], v[184:187], v[220:223], v[0:3]
	v_mfma_f32_16x16x32_bf16 v[4:7], v[176:179], v[220:223], v[4:7]
	v_mfma_f32_16x16x32_bf16 v[4:7], v[172:175], v[216:219], v[4:7]
	v_mfma_f32_16x16x32_bf16 v[8:11], v[164:167], v[216:219], v[8:11]
	v_mfma_f32_16x16x32_bf16 v[8:11], v[168:171], v[220:223], v[8:11]
	v_mfma_f32_16x16x32_bf16 v[12:15], v[160:163], v[220:223], v[12:15]
	v_mfma_f32_16x16x32_bf16 v[12:15], v[156:159], v[216:219], v[12:15]
	s_setprio 0
	s_barrier
	s_add_i32 s50, 0, 0x18000
	v_add_u32_e32 v136, s50, v149
	s_add_i32 s51, 0, 0x1c000
	ds_read_b128 v[156:159], v136
	ds_read_b128 v[160:163], v136 offset:1024
	ds_read_b128 v[164:167], v136 offset:2048
	ds_read_b128 v[168:171], v136 offset:3072
	v_add_u32_e32 v136, s51, v149
	ds_read_b128 v[172:175], v136
	ds_read_b128 v[176:179], v136 offset:1024
	ds_read_b128 v[180:183], v136 offset:2048
	ds_read_b128 v[184:187], v136 offset:3072
	s_add_u32 s0, s24, 0x18000
	s_addc_u32 s1, s25, 0
	s_mov_b32 m0, s31
	v_lshl_add_u64 v[234:235], s[0:1], 0, v[128:129]
	ds_read_b128 v[188:191], v154 offset:32768
	ds_read_b128 v[192:195], v154 offset:33792
	ds_read_b128 v[196:199], v154 offset:34816
	ds_read_b128 v[200:203], v154 offset:35840
	ds_read_b128 v[208:211], v154 offset:36864
	ds_read_b128 v[212:215], v154 offset:37888
	ds_read_b128 v[216:219], v154 offset:38912
	ds_read_b128 v[220:223], v154 offset:39936
	global_load_lds_dwordx4 v[234:235], off
	v_lshl_add_u64 v[234:235], s[0:1], 0, v[132:133]
	s_mov_b32 m0, s34
	s_nop 0
	global_load_lds_dwordx4 v[234:235], off
	s_waitcnt vmcnt(8)
	s_waitcnt lgkmcnt(0)
	s_barrier
	s_setprio 1
	s_waitcnt lgkmcnt(0)
	v_mfma_f32_16x16x32_bf16 v[124:127], v[156:159], v[188:191], v[124:127]
	v_mfma_f32_16x16x32_bf16 v[124:127], v[160:163], v[192:195], v[124:127]
	v_mfma_f32_16x16x32_bf16 v[120:123], v[168:171], v[192:195], v[120:123]
	v_mfma_f32_16x16x32_bf16 v[120:123], v[164:167], v[188:191], v[120:123]
	v_mfma_f32_16x16x32_bf16 v[116:119], v[172:175], v[188:191], v[116:119]
	v_mfma_f32_16x16x32_bf16 v[116:119], v[176:179], v[192:195], v[116:119]
	v_mfma_f32_16x16x32_bf16 v[112:115], v[184:187], v[192:195], v[112:115]
	v_mfma_f32_16x16x32_bf16 v[112:115], v[180:183], v[188:191], v[112:115]
	s_setprio 0
	s_setprio 1
	v_mfma_f32_16x16x32_bf16 v[96:99], v[180:183], v[196:199], v[96:99]
	v_mfma_f32_16x16x32_bf16 v[96:99], v[184:187], v[200:203], v[96:99]
	v_mfma_f32_16x16x32_bf16 v[100:103], v[176:179], v[200:203], v[100:103]
	v_mfma_f32_16x16x32_bf16 v[100:103], v[172:175], v[196:199], v[100:103]
	v_mfma_f32_16x16x32_bf16 v[104:107], v[164:167], v[196:199], v[104:107]
	v_mfma_f32_16x16x32_bf16 v[104:107], v[168:171], v[200:203], v[104:107]
	v_mfma_f32_16x16x32_bf16 v[108:111], v[160:163], v[200:203], v[108:111]
	v_mfma_f32_16x16x32_bf16 v[108:111], v[156:159], v[196:199], v[108:111]
	s_setprio 0
	s_setprio 1
	v_mfma_f32_16x16x32_bf16 v[92:95], v[156:159], v[208:211], v[92:95]
	v_mfma_f32_16x16x32_bf16 v[92:95], v[160:163], v[212:215], v[92:95]
	v_mfma_f32_16x16x32_bf16 v[88:91], v[168:171], v[212:215], v[88:91]
	v_mfma_f32_16x16x32_bf16 v[88:91], v[164:167], v[208:211], v[88:91]
	v_mfma_f32_16x16x32_bf16 v[84:87], v[172:175], v[208:211], v[84:87]
	v_mfma_f32_16x16x32_bf16 v[84:87], v[176:179], v[212:215], v[84:87]
	v_mfma_f32_16x16x32_bf16 v[80:83], v[184:187], v[212:215], v[80:83]
	v_mfma_f32_16x16x32_bf16 v[80:83], v[180:183], v[208:211], v[80:83]
	s_setprio 0
	s_setprio 1
	v_mfma_f32_16x16x32_bf16 v[64:67], v[180:183], v[216:219], v[64:67]
	v_mfma_f32_16x16x32_bf16 v[64:67], v[184:187], v[220:223], v[64:67]
	v_mfma_f32_16x16x32_bf16 v[68:71], v[176:179], v[220:223], v[68:71]
	v_mfma_f32_16x16x32_bf16 v[68:71], v[172:175], v[216:219], v[68:71]
	v_mfma_f32_16x16x32_bf16 v[72:75], v[164:167], v[216:219], v[72:75]
	v_mfma_f32_16x16x32_bf16 v[72:75], v[168:171], v[220:223], v[72:75]
	v_mfma_f32_16x16x32_bf16 v[76:79], v[160:163], v[220:223], v[76:79]
	v_mfma_f32_16x16x32_bf16 v[76:79], v[156:159], v[216:219], v[76:79]
	s_setprio 0
	s_barrier
; #define PG8_STAGE(bufoff, gbase, voff) do { _Pragma("unroll") for (int _i = 0; _i < 2; ++_i) \
;         __builtin_amdgcn_global_load_lds((const unsigned*)((const char*)(gbase) + (voff)[_i]), (LAS unsigned*)(lds + (bufoff) + ldsw + _i * 8192), 16, 0, 0); } while (0)
; #define PG8_LDA(dst, b, h) do { _Pragma("unroll") for (int m = 0; m < 4; ++m) _Pragma("unroll") for (int k = 0; k < 2; ++k) dst[m][k] = *(const LAS bf16x8*)(lds + PG8_SA(b, h) + aoff + m * 2048 + k * 1024); } while (0)
; #define PG8_MMA(ai, bj, At, Bt) do { __builtin_amdgcn_s_setprio(1); _Pragma("unroll") for (int m = 0; m < 4; ++m) _Pragma("unroll") for (int n = 0; n < 2; ++n) _Pragma("unroll") for (int k = 0; k < 2; ++k) \
;         acc[ai][bj][m][n] = __builtin_amdgcn_mfma_f32_16x16x32_bf16(Bt[n][k], At[m][k], acc[ai][bj][m][n], 0, 0, 0); __builtin_amdgcn_s_setprio(0); } while (0)
; #define PG8_WAIT_V(n) asm volatile("s_waitcnt vmcnt(" #n ")" ::: "memory")
; #define PG8_WAIT_L(n) asm volatile("s_waitcnt lgkmcnt(" #n ")" ::: "memory")
; #define PG8_BAR __builtin_amdgcn_s_barrier()
; #define PG8_SCHED __builtin_amdgcn_sched_barrier(0)
; template <class Epi>
; __device__ __forceinline__ void gemm_phase(LAS unsigned char* lds, const Gemm g, const StaticOrder& S, const Epi& E) {
;     ...
;             PG8_LDA(At, 1, 1); PG8_STAGE(PG8_SB(1, 0), b3, voffB); PG8_STAGE(PG8_SB(1, 1), b3 + hstepB, voffB); PG8_STAGE(PG8_SA(1, 0), a3, voffA);
;             PG8_WAIT_V(8); PG8_WAIT_L(0); PG8_BAR; PG8_MMA(1, 0, At, B0); PG8_MMA(1, 1, At, B1); PG8_BAR; PG8_SCHED;
;         }
	s_add_i32 s0, s50, s28
	v_lshl_add_u64 v[224:225], v[224:225], 0, s[14:15]
	s_mov_b32 m0, s0
	ds_read_b128 v[188:191], v154 offset:49152
	ds_read_b128 v[192:195], v154 offset:50176
	ds_read_b128 v[196:199], v154 offset:51200
	ds_read_b128 v[200:203], v154 offset:52224
	ds_read_b128 v[208:211], v154 offset:53248
	ds_read_b128 v[212:215], v154 offset:54272
	ds_read_b128 v[216:219], v154 offset:55296
	ds_read_b128 v[220:223], v154 offset:56320
	global_load_lds_dwordx4 v[224:225], off
	s_add_i32 m0, s0, 0x2000
	s_add_u32 s0, s22, 0x18080
	v_lshl_add_u64 v[224:225], v[226:227], 0, s[14:15]
	s_addc_u32 s1, s23, 0
	s_add_i32 s22, s51, s28
	global_load_lds_dwordx4 v[224:225], off
	v_lshl_add_u64 v[224:225], s[0:1], 0, v[130:131]
	s_mov_b32 m0, s22
	s_nop 0
	global_load_lds_dwordx4 v[224:225], off
	v_lshl_add_u64 v[224:225], s[0:1], 0, v[134:135]
	s_add_i32 m0, s22, 0x2000
	s_nop 0
	global_load_lds_dwordx4 v[224:225], off
	v_lshl_add_u64 v[224:225], v[230:231], 0, s[14:15]
	s_mov_b32 m0, s38
	s_nop 0
	global_load_lds_dwordx4 v[224:225], off
	v_lshl_add_u64 v[224:225], v[232:233], 0, s[14:15]
	s_mov_b32 m0, s39
	s_nop 0
	global_load_lds_dwordx4 v[224:225], off
	s_waitcnt vmcnt(8)
	s_waitcnt lgkmcnt(0)
	s_barrier
	s_setprio 1
	s_waitcnt lgkmcnt(0)
	v_mfma_f32_16x16x32_bf16 v[60:63], v[156:159], v[188:191], v[60:63]
	v_mfma_f32_16x16x32_bf16 v[60:63], v[160:163], v[192:195], v[60:63]
	v_mfma_f32_16x16x32_bf16 v[56:59], v[168:171], v[192:195], v[56:59]
	v_mfma_f32_16x16x32_bf16 v[56:59], v[164:167], v[188:191], v[56:59]
	v_mfma_f32_16x16x32_bf16 v[52:55], v[172:175], v[188:191], v[52:55]
	v_mfma_f32_16x16x32_bf16 v[52:55], v[176:179], v[192:195], v[52:55]
	v_mfma_f32_16x16x32_bf16 v[48:51], v[184:187], v[192:195], v[48:51]
	v_mfma_f32_16x16x32_bf16 v[48:51], v[180:183], v[188:191], v[48:51]
	s_setprio 0
	s_setprio 1
	v_mfma_f32_16x16x32_bf16 v[32:35], v[180:183], v[196:199], v[32:35]
	v_mfma_f32_16x16x32_bf16 v[32:35], v[184:187], v[200:203], v[32:35]
	v_mfma_f32_16x16x32_bf16 v[36:39], v[176:179], v[200:203], v[36:39]
	v_mfma_f32_16x16x32_bf16 v[36:39], v[172:175], v[196:199], v[36:39]
	v_mfma_f32_16x16x32_bf16 v[40:43], v[164:167], v[196:199], v[40:43]
	v_mfma_f32_16x16x32_bf16 v[40:43], v[168:171], v[200:203], v[40:43]
	v_mfma_f32_16x16x32_bf16 v[44:47], v[160:163], v[200:203], v[44:47]
	v_mfma_f32_16x16x32_bf16 v[44:47], v[156:159], v[196:199], v[44:47]
	s_setprio 0
	s_setprio 1
	v_mfma_f32_16x16x32_bf16 v[28:31], v[156:159], v[208:211], v[28:31]
	v_mfma_f32_16x16x32_bf16 v[28:31], v[160:163], v[212:215], v[28:31]
	v_mfma_f32_16x16x32_bf16 v[24:27], v[168:171], v[212:215], v[24:27]
	v_mfma_f32_16x16x32_bf16 v[24:27], v[164:167], v[208:211], v[24:27]
	v_mfma_f32_16x16x32_bf16 v[20:23], v[172:175], v[208:211], v[20:23]
	v_mfma_f32_16x16x32_bf16 v[20:23], v[176:179], v[212:215], v[20:23]
	v_mfma_f32_16x16x32_bf16 v[16:19], v[184:187], v[212:215], v[16:19]
	v_mfma_f32_16x16x32_bf16 v[16:19], v[180:183], v[208:211], v[16:19]
	s_setprio 0
	s_setprio 1
	v_mfma_f32_16x16x32_bf16 v[0:3], v[180:183], v[216:219], v[0:3]
	v_mfma_f32_16x16x32_bf16 v[0:3], v[184:187], v[220:223], v[0:3]
	v_mfma_f32_16x16x32_bf16 v[4:7], v[176:179], v[220:223], v[4:7]
	v_mfma_f32_16x16x32_bf16 v[4:7], v[172:175], v[216:219], v[4:7]
	v_mfma_f32_16x16x32_bf16 v[8:11], v[164:167], v[216:219], v[8:11]
	v_mfma_f32_16x16x32_bf16 v[8:11], v[168:171], v[220:223], v[8:11]
	v_mfma_f32_16x16x32_bf16 v[12:15], v[160:163], v[220:223], v[12:15]
	v_mfma_f32_16x16x32_bf16 v[12:15], v[156:159], v[216:219], v[12:15]
	s_setprio 0
	s_barrier
	s_add_u32 s47, s47, 0x100
	s_addc_u32 s48, s48, 0
	s_cmp_ge_i32 s49, s36
	s_mov_b64 s[0:1], s[4:5]
	s_mov_b32 s22, s49
	s_cbranch_scc0 .LBB0_834

; #define PG8_STAGE(bufoff, gbase, voff) do { _Pragma("unroll") for (int _i = 0; _i < 2; ++_i) \
;         __builtin_amdgcn_global_load_lds((const unsigned*)((const char*)(gbase) + (voff)[_i]), (LAS unsigned*)(lds + (bufoff) + ldsw + _i * 8192), 16, 0, 0); } while (0)
; #define PG8_LDA(dst, b, h) do { _Pragma("unroll") for (int m = 0; m < 4; ++m) _Pragma("unroll") for (int k = 0; k < 2; ++k) dst[m][k] = *(const LAS bf16x8*)(lds + PG8_SA(b, h) + aoff + m * 2048 + k * 1024); } while (0)
; #define PG8_LDB(dst, b, h) do { _Pragma("unroll") for (int n = 0; n < 2; ++n) _Pragma("unroll") for (int k = 0; k < 2; ++k) dst[n][k] = *(const LAS bf16x8*)(lds + PG8_SB(b, h) + boff + n * 2048 + k * 1024); } while (0)
; #define PG8_MMA(ai, bj, At, Bt) do { __builtin_amdgcn_s_setprio(1); _Pragma("unroll") for (int m = 0; m < 4; ++m) _Pragma("unroll") for (int n = 0; n < 2; ++n) _Pragma("unroll") for (int k = 0; k < 2; ++k) \
;         acc[ai][bj][m][n] = __builtin_amdgcn_mfma_f32_16x16x32_bf16(Bt[n][k], At[m][k], acc[ai][bj][m][n], 0, 0, 0); __builtin_amdgcn_s_setprio(0); } while (0)
; #define PG8_WAIT_V(n) asm volatile("s_waitcnt vmcnt(" #n ")" ::: "memory")
; #define PG8_WAIT_L(n) asm volatile("s_waitcnt lgkmcnt(" #n ")" ::: "memory")
; #define PG8_BAR __builtin_amdgcn_s_barrier()
; #define PG8_SCHED __builtin_amdgcn_sched_barrier(0)
; template <class Epi>
; __device__ __forceinline__ void gemm_phase(LAS unsigned char* lds, const Gemm g, const StaticOrder& S, const Epi& E) {
;     ...
;         for (int t = 0; t < nt; t += 2) {
;             const bool last = (t == nt - 2);
;             const char* a1 = cA + (size_t)(t + 1) * kstep;
;             const char* a2 = last ? nA : cA + (size_t)(t + 2) * kstep; const char* b2 = last ? nB : cB + (size_t)(t + 2) * kstep;
;             const char* a3 = a2 + kstep; const char* b3 = b2 + kstep;
;             PG8_LDB(B0, 0, 0); PG8_LDB(B1, 0, 1); PG8_SCHED; PG8_LDA(At, 0, 0); PG8_STAGE(PG8_SA(1, 1), a1 + hstepA, voffA);
;             PG8_WAIT_V(8); PG8_WAIT_L(0); PG8_BAR; PG8_MMA(0, 0, At, B0); PG8_MMA(0, 1, At, B1); PG8_BAR; PG8_SCHED;
;             PG8_LDA(At, 0, 1); PG8_STAGE(PG8_SB(0, 0), b2, voffB); PG8_STAGE(PG8_SB(0, 1), b2 + hstepB, voffB); PG8_STAGE(PG8_SA(0, 0), a2, voffA);
;             PG8_WAIT_V(8); PG8_WAIT_L(0); PG8_BAR; PG8_MMA(1, 0, At, B0); PG8_MMA(1, 1, At, B1); PG8_BAR; PG8_SCHED;
.LBB0_912:
	ds_read_b128 v[96:99], v230
	ds_read_b128 v[100:103], v230 offset:1024
	ds_read_b128 v[104:107], v230 offset:2048
	ds_read_b128 v[116:119], v230 offset:3072
	ds_read_b128 v[120:123], v231
	ds_read_b128 v[124:127], v231 offset:1024
	ds_read_b128 v[136:139], v231 offset:2048
	ds_read_b128 v[148:151], v231 offset:3072
	s_add_i32 s56, s24, 2
	s_add_u32 s25, s4, 0xfffc0080
	s_addc_u32 s26, s5, -1
	s_cmp_eq_u32 s44, s24
	s_cselect_b32 s24, s53, s54
	s_cselect_b32 s27, s17, s26
	s_cselect_b32 s26, s19, s25
	s_cselect_b32 s25, s33, s55
	v_lshl_add_u64 v[192:193], s[4:5], 0, v[220:221]
	s_add_i32 m0, s31, 0xc000
	ds_read_b128 v[160:163], v232
	ds_read_b128 v[164:167], v232 offset:1024
	ds_read_b128 v[168:171], v232 offset:2048
	ds_read_b128 v[172:175], v232 offset:3072
	ds_read_b128 v[176:179], v232 offset:4096
	ds_read_b128 v[180:183], v232 offset:5120
	ds_read_b128 v[184:187], v232 offset:6144
	ds_read_b128 v[188:191], v232 offset:7168
	global_load_lds_dwordx4 v[192:193], off
	v_lshl_add_u64 v[192:193], s[4:5], 0, v[222:223]
	s_add_i32 m0, s31, 0xe000
	s_nop 0
	global_load_lds_dwordx4 v[192:193], off
	s_waitcnt vmcnt(8)
	s_waitcnt lgkmcnt(0)
	s_barrier
	s_setprio 1
	s_waitcnt lgkmcnt(0)
	v_mfma_f32_16x16x32_bf16 v[156:159], v[96:99], v[160:163], v[156:159]
	v_mfma_f32_16x16x32_bf16 v[156:159], v[100:103], v[164:167], v[156:159]
	v_mfma_f32_16x16x32_bf16 v[152:155], v[116:119], v[164:167], v[152:155]
	v_mfma_f32_16x16x32_bf16 v[152:155], v[104:107], v[160:163], v[152:155]
	v_mfma_f32_16x16x32_bf16 v[144:147], v[120:123], v[160:163], v[144:147]
	v_mfma_f32_16x16x32_bf16 v[144:147], v[124:127], v[164:167], v[144:147]
	v_mfma_f32_16x16x32_bf16 v[140:143], v[148:151], v[164:167], v[140:143]
	v_mfma_f32_16x16x32_bf16 v[140:143], v[136:139], v[160:163], v[140:143]
	s_setprio 0
	s_setprio 1
	v_mfma_f32_16x16x32_bf16 v[108:111], v[136:139], v[168:171], v[108:111]
	v_mfma_f32_16x16x32_bf16 v[108:111], v[148:151], v[172:175], v[108:111]
	v_mfma_f32_16x16x32_bf16 v[112:115], v[124:127], v[172:175], v[112:115]
	v_mfma_f32_16x16x32_bf16 v[112:115], v[120:123], v[168:171], v[112:115]
	v_mfma_f32_16x16x32_bf16 v[128:131], v[104:107], v[168:171], v[128:131]
	v_mfma_f32_16x16x32_bf16 v[128:131], v[116:119], v[172:175], v[128:131]
	v_mfma_f32_16x16x32_bf16 v[132:135], v[100:103], v[172:175], v[132:135]
	v_mfma_f32_16x16x32_bf16 v[132:135], v[96:99], v[168:171], v[132:135]
	s_setprio 0
	s_setprio 1
	v_mfma_f32_16x16x32_bf16 v[92:95], v[96:99], v[176:179], v[92:95]
	v_mfma_f32_16x16x32_bf16 v[92:95], v[100:103], v[180:183], v[92:95]
	v_mfma_f32_16x16x32_bf16 v[88:91], v[116:119], v[180:183], v[88:91]
	v_mfma_f32_16x16x32_bf16 v[88:91], v[104:107], v[176:179], v[88:91]
	v_mfma_f32_16x16x32_bf16 v[84:87], v[120:123], v[176:179], v[84:87]
	v_mfma_f32_16x16x32_bf16 v[84:87], v[124:127], v[180:183], v[84:87]
	v_mfma_f32_16x16x32_bf16 v[80:83], v[148:151], v[180:183], v[80:83]
	v_mfma_f32_16x16x32_bf16 v[80:83], v[136:139], v[176:179], v[80:83]
	s_setprio 0
	s_setprio 1
	v_mfma_f32_16x16x32_bf16 v[64:67], v[136:139], v[184:187], v[64:67]
	v_mfma_f32_16x16x32_bf16 v[64:67], v[148:151], v[188:191], v[64:67]
	v_mfma_f32_16x16x32_bf16 v[68:71], v[124:127], v[188:191], v[68:71]
	v_mfma_f32_16x16x32_bf16 v[68:71], v[120:123], v[184:187], v[68:71]
	v_mfma_f32_16x16x32_bf16 v[72:75], v[104:107], v[184:187], v[72:75]
	v_mfma_f32_16x16x32_bf16 v[72:75], v[116:119], v[188:191], v[72:75]
	v_mfma_f32_16x16x32_bf16 v[76:79], v[100:103], v[188:191], v[76:79]
	v_mfma_f32_16x16x32_bf16 v[76:79], v[96:99], v[184:187], v[76:79]
	s_setprio 0
	s_barrier
	s_add_i32 s57, s47, s30
	v_lshl_add_u64 v[192:193], s[24:25], 0, v[210:211]
	s_mov_b32 m0, s57
	ds_read_b128 v[160:163], v232 offset:16384
	ds_read_b128 v[164:167], v232 offset:17408
	ds_read_b128 v[168:171], v232 offset:18432
	ds_read_b128 v[172:175], v232 offset:19456
	ds_read_b128 v[176:179], v232 offset:20480
	ds_read_b128 v[180:183], v232 offset:21504
	ds_read_b128 v[184:187], v232 offset:22528
	ds_read_b128 v[188:191], v232 offset:23552
	global_load_lds_dwordx4 v[192:193], off
	s_add_i32 m0, s57, 0x2000
	s_add_u32 s58, s24, 0x40000
	v_lshl_add_u64 v[194:195], s[24:25], 0, v[214:215]
	s_addc_u32 s59, s25, 0
	s_add_i32 s57, s48, s30
	global_load_lds_dwordx4 v[194:195], off
	v_lshl_add_u64 v[196:197], s[58:59], 0, v[210:211]
	s_mov_b32 m0, s57
	v_lshl_add_u64 v[198:199], s[26:27], 0, v[212:213]
	global_load_lds_dwordx4 v[196:197], off
	v_lshl_add_u64 v[196:197], s[58:59], 0, v[214:215]
	s_add_i32 m0, s57, 0x2000
	s_nop 0
	global_load_lds_dwordx4 v[196:197], off
	v_lshl_add_u64 v[196:197], s[26:27], 0, v[208:209]
	s_mov_b32 m0, s31
	s_nop 0
	global_load_lds_dwordx4 v[196:197], off
	s_mov_b32 m0, s34
	s_nop 0
	global_load_lds_dwordx4 v[198:199], off
	s_waitcnt vmcnt(8)
	s_waitcnt lgkmcnt(0)
	s_barrier
; #define PG8_STAGE(bufoff, gbase, voff) do { _Pragma("unroll") for (int _i = 0; _i < 2; ++_i) \
;         __builtin_amdgcn_global_load_lds((const unsigned*)((const char*)(gbase) + (voff)[_i]), (LAS unsigned*)(lds + (bufoff) + ldsw + _i * 8192), 16, 0, 0); } while (0)
; #define PG8_LDA(dst, b, h) do { _Pragma("unroll") for (int m = 0; m < 4; ++m) _Pragma("unroll") for (int k = 0; k < 2; ++k) dst[m][k] = *(const LAS bf16x8*)(lds + PG8_SA(b, h) + aoff + m * 2048 + k * 1024); } while (0)
; #define PG8_LDB(dst, b, h) do { _Pragma("unroll") for (int n = 0; n < 2; ++n) _Pragma("unroll") for (int k = 0; k < 2; ++k) dst[n][k] = *(const LAS bf16x8*)(lds + PG8_SB(b, h) + boff + n * 2048 + k * 1024); } while (0)
; #define PG8_MMA(ai, bj, At, Bt) do { __builtin_amdgcn_s_setprio(1); _Pragma("unroll") for (int m = 0; m < 4; ++m) _Pragma("unroll") for (int n = 0; n < 2; ++n) _Pragma("unroll") for (int k = 0; k < 2; ++k) \
;         acc[ai][bj][m][n] = __builtin_amdgcn_mfma_f32_16x16x32_bf16(Bt[n][k], At[m][k], acc[ai][bj][m][n], 0, 0, 0); __builtin_amdgcn_s_setprio(0); } while (0)
; #define PG8_WAIT_V(n) asm volatile("s_waitcnt vmcnt(" #n ")" ::: "memory")
; #define PG8_WAIT_L(n) asm volatile("s_waitcnt lgkmcnt(" #n ")" ::: "memory")
; #define PG8_BAR __builtin_amdgcn_s_barrier()
; #define PG8_SCHED __builtin_amdgcn_sched_barrier(0)
; template <class Epi>
; __device__ __forceinline__ void gemm_phase(LAS unsigned char* lds, const Gemm g, const StaticOrder& S, const Epi& E) {
;     ...
;             PG8_WAIT_V(8); PG8_WAIT_L(0); PG8_BAR; PG8_MMA(1, 0, At, B0); PG8_MMA(1, 1, At, B1); PG8_BAR; PG8_SCHED;
;             PG8_LDB(B0, 1, 0); PG8_LDB(B1, 1, 1); PG8_SCHED; PG8_LDA(At, 1, 0); PG8_STAGE(PG8_SA(0, 1), a2 + hstepA, voffA);
;             PG8_WAIT_V(8); PG8_WAIT_L(0); PG8_BAR; PG8_MMA(0, 0, At, B0); PG8_MMA(0, 1, At, B1); PG8_BAR; PG8_SCHED;
	s_setprio 1
	s_waitcnt lgkmcnt(0)
	v_mfma_f32_16x16x32_bf16 v[60:63], v[96:99], v[160:163], v[60:63]
	v_mfma_f32_16x16x32_bf16 v[60:63], v[100:103], v[164:167], v[60:63]
	v_mfma_f32_16x16x32_bf16 v[56:59], v[116:119], v[164:167], v[56:59]
	v_mfma_f32_16x16x32_bf16 v[56:59], v[104:107], v[160:163], v[56:59]
	v_mfma_f32_16x16x32_bf16 v[52:55], v[120:123], v[160:163], v[52:55]
	v_mfma_f32_16x16x32_bf16 v[52:55], v[124:127], v[164:167], v[52:55]
	v_mfma_f32_16x16x32_bf16 v[48:51], v[148:151], v[164:167], v[48:51]
	v_mfma_f32_16x16x32_bf16 v[48:51], v[136:139], v[160:163], v[48:51]
	s_setprio 0
	s_setprio 1
	v_mfma_f32_16x16x32_bf16 v[32:35], v[136:139], v[168:171], v[32:35]
	v_mfma_f32_16x16x32_bf16 v[32:35], v[148:151], v[172:175], v[32:35]
	v_mfma_f32_16x16x32_bf16 v[36:39], v[124:127], v[172:175], v[36:39]
	v_mfma_f32_16x16x32_bf16 v[36:39], v[120:123], v[168:171], v[36:39]
	v_mfma_f32_16x16x32_bf16 v[40:43], v[104:107], v[168:171], v[40:43]
	v_mfma_f32_16x16x32_bf16 v[40:43], v[116:119], v[172:175], v[40:43]
	v_mfma_f32_16x16x32_bf16 v[44:47], v[100:103], v[172:175], v[44:47]
	v_mfma_f32_16x16x32_bf16 v[44:47], v[96:99], v[168:171], v[44:47]
	s_setprio 0
	s_setprio 1
	v_mfma_f32_16x16x32_bf16 v[28:31], v[96:99], v[176:179], v[28:31]
	v_mfma_f32_16x16x32_bf16 v[28:31], v[100:103], v[180:183], v[28:31]
	v_mfma_f32_16x16x32_bf16 v[24:27], v[116:119], v[180:183], v[24:27]
	v_mfma_f32_16x16x32_bf16 v[24:27], v[104:107], v[176:179], v[24:27]
	v_mfma_f32_16x16x32_bf16 v[20:23], v[120:123], v[176:179], v[20:23]
	v_mfma_f32_16x16x32_bf16 v[20:23], v[124:127], v[180:183], v[20:23]
	v_mfma_f32_16x16x32_bf16 v[16:19], v[148:151], v[180:183], v[16:19]
	v_mfma_f32_16x16x32_bf16 v[16:19], v[136:139], v[176:179], v[16:19]
	s_setprio 0
	s_setprio 1
	v_mfma_f32_16x16x32_bf16 v[0:3], v[136:139], v[184:187], v[0:3]
	v_mfma_f32_16x16x32_bf16 v[0:3], v[148:151], v[188:191], v[0:3]
	v_mfma_f32_16x16x32_bf16 v[4:7], v[124:127], v[188:191], v[4:7]
	v_mfma_f32_16x16x32_bf16 v[4:7], v[120:123], v[184:187], v[4:7]
	v_mfma_f32_16x16x32_bf16 v[8:11], v[104:107], v[184:187], v[8:11]
	v_mfma_f32_16x16x32_bf16 v[8:11], v[116:119], v[188:191], v[8:11]
	v_mfma_f32_16x16x32_bf16 v[12:15], v[100:103], v[188:191], v[12:15]
	v_mfma_f32_16x16x32_bf16 v[12:15], v[96:99], v[184:187], v[12:15]
	s_setprio 0
	s_barrier
	s_add_i32 s57, 0, 0x18000
	s_add_i32 s58, 0, 0x1c000
	v_add_u32_e32 v116, s57, v229
	v_add_u32_e32 v148, s58, v229
	ds_read_b128 v[96:99], v116
	ds_read_b128 v[100:103], v116 offset:1024
	ds_read_b128 v[104:107], v116 offset:2048
	ds_read_b128 v[116:119], v116 offset:3072
	ds_read_b128 v[120:123], v148
	ds_read_b128 v[124:127], v148 offset:1024
	ds_read_b128 v[136:139], v148 offset:2048
	ds_read_b128 v[148:151], v148 offset:3072
	s_add_u32 s26, s26, 0x40000
	s_addc_u32 s27, s27, 0
	s_mov_b32 m0, s35
	v_lshl_add_u64 v[200:201], s[26:27], 0, v[208:209]
	ds_read_b128 v[160:163], v232 offset:32768
	ds_read_b128 v[164:167], v232 offset:33792
	ds_read_b128 v[168:171], v232 offset:34816
	ds_read_b128 v[172:175], v232 offset:35840
	ds_read_b128 v[176:179], v232 offset:36864
	ds_read_b128 v[180:183], v232 offset:37888
	ds_read_b128 v[184:187], v232 offset:38912
	ds_read_b128 v[188:191], v232 offset:39936
	global_load_lds_dwordx4 v[200:201], off
	v_lshl_add_u64 v[200:201], s[26:27], 0, v[212:213]
	s_mov_b32 m0, s36
	s_nop 0
	global_load_lds_dwordx4 v[200:201], off
	s_waitcnt vmcnt(8)
	s_waitcnt lgkmcnt(0)
	s_barrier
	s_setprio 1
	s_waitcnt lgkmcnt(0)
	v_mfma_f32_16x16x32_bf16 v[156:159], v[96:99], v[160:163], v[156:159]
	v_mfma_f32_16x16x32_bf16 v[156:159], v[100:103], v[164:167], v[156:159]
	v_mfma_f32_16x16x32_bf16 v[152:155], v[116:119], v[164:167], v[152:155]
	v_mfma_f32_16x16x32_bf16 v[152:155], v[104:107], v[160:163], v[152:155]
	v_mfma_f32_16x16x32_bf16 v[144:147], v[120:123], v[160:163], v[144:147]
	v_mfma_f32_16x16x32_bf16 v[144:147], v[124:127], v[164:167], v[144:147]
	v_mfma_f32_16x16x32_bf16 v[140:143], v[148:151], v[164:167], v[140:143]
	v_mfma_f32_16x16x32_bf16 v[140:143], v[136:139], v[160:163], v[140:143]
	s_setprio 0
	s_setprio 1
	v_mfma_f32_16x16x32_bf16 v[108:111], v[136:139], v[168:171], v[108:111]
	v_mfma_f32_16x16x32_bf16 v[108:111], v[148:151], v[172:175], v[108:111]
	v_mfma_f32_16x16x32_bf16 v[112:115], v[124:127], v[172:175], v[112:115]
	v_mfma_f32_16x16x32_bf16 v[112:115], v[120:123], v[168:171], v[112:115]
	v_mfma_f32_16x16x32_bf16 v[128:131], v[104:107], v[168:171], v[128:131]
	v_mfma_f32_16x16x32_bf16 v[128:131], v[116:119], v[172:175], v[128:131]
	v_mfma_f32_16x16x32_bf16 v[132:135], v[100:103], v[172:175], v[132:135]
	v_mfma_f32_16x16x32_bf16 v[132:135], v[96:99], v[168:171], v[132:135]
	s_setprio 0
	s_setprio 1
	v_mfma_f32_16x16x32_bf16 v[92:95], v[96:99], v[176:179], v[92:95]
	v_mfma_f32_16x16x32_bf16 v[92:95], v[100:103], v[180:183], v[92:95]
	v_mfma_f32_16x16x32_bf16 v[88:91], v[116:119], v[180:183], v[88:91]
	v_mfma_f32_16x16x32_bf16 v[88:91], v[104:107], v[176:179], v[88:91]
	v_mfma_f32_16x16x32_bf16 v[84:87], v[120:123], v[176:179], v[84:87]
	v_mfma_f32_16x16x32_bf16 v[84:87], v[124:127], v[180:183], v[84:87]
	v_mfma_f32_16x16x32_bf16 v[80:83], v[148:151], v[180:183], v[80:83]
	v_mfma_f32_16x16x32_bf16 v[80:83], v[136:139], v[176:179], v[80:83]
	s_setprio 0
	s_setprio 1
	v_mfma_f32_16x16x32_bf16 v[64:67], v[136:139], v[184:187], v[64:67]
	v_mfma_f32_16x16x32_bf16 v[64:67], v[148:151], v[188:191], v[64:67]
	v_mfma_f32_16x16x32_bf16 v[68:71], v[124:127], v[188:191], v[68:71]
	v_mfma_f32_16x16x32_bf16 v[68:71], v[120:123], v[184:187], v[68:71]
	v_mfma_f32_16x16x32_bf16 v[72:75], v[104:107], v[184:187], v[72:75]
	v_mfma_f32_16x16x32_bf16 v[72:75], v[116:119], v[188:191], v[72:75]
	v_mfma_f32_16x16x32_bf16 v[76:79], v[100:103], v[188:191], v[76:79]
	v_mfma_f32_16x16x32_bf16 v[76:79], v[96:99], v[184:187], v[76:79]
	s_setprio 0
	s_barrier
; #define PG8_STAGE(bufoff, gbase, voff) do { _Pragma("unroll") for (int _i = 0; _i < 2; ++_i) \
;         __builtin_amdgcn_global_load_lds((const unsigned*)((const char*)(gbase) + (voff)[_i]), (LAS unsigned*)(lds + (bufoff) + ldsw + _i * 8192), 16, 0, 0); } while (0)
; #define PG8_LDA(dst, b, h) do { _Pragma("unroll") for (int m = 0; m < 4; ++m) _Pragma("unroll") for (int k = 0; k < 2; ++k) dst[m][k] = *(const LAS bf16x8*)(lds + PG8_SA(b, h) + aoff + m * 2048 + k * 1024); } while (0)
; #define PG8_MMA(ai, bj, At, Bt) do { __builtin_amdgcn_s_setprio(1); _Pragma("unroll") for (int m = 0; m < 4; ++m) _Pragma("unroll") for (int n = 0; n < 2; ++n) _Pragma("unroll") for (int k = 0; k < 2; ++k) \
;         acc[ai][bj][m][n] = __builtin_amdgcn_mfma_f32_16x16x32_bf16(Bt[n][k], At[m][k], acc[ai][bj][m][n], 0, 0, 0); __builtin_amdgcn_s_setprio(0); } while (0)
; #define PG8_WAIT_V(n) asm volatile("s_waitcnt vmcnt(" #n ")" ::: "memory")
; #define PG8_WAIT_L(n) asm volatile("s_waitcnt lgkmcnt(" #n ")" ::: "memory")
; #define PG8_BAR __builtin_amdgcn_s_barrier()
; #define PG8_SCHED __builtin_amdgcn_sched_barrier(0)
; template <class Epi>
; __device__ __forceinline__ void gemm_phase(LAS unsigned char* lds, const Gemm g, const StaticOrder& S, const Epi& E) {
;     ...
;             PG8_LDA(At, 1, 1); PG8_STAGE(PG8_SB(1, 0), b3, voffB); PG8_STAGE(PG8_SB(1, 1), b3 + hstepB, voffB); PG8_STAGE(PG8_SA(1, 0), a3, voffA);
;             PG8_WAIT_V(8); PG8_WAIT_L(0); PG8_BAR; PG8_MMA(1, 0, At, B0); PG8_MMA(1, 1, At, B1); PG8_BAR; PG8_SCHED;
;         }
	s_add_i32 s26, s57, s30
	v_lshl_add_u64 v[192:193], v[192:193], 0, s[10:11]
	s_mov_b32 m0, s26
	ds_read_b128 v[160:163], v232 offset:49152
	ds_read_b128 v[164:167], v232 offset:50176
	ds_read_b128 v[168:171], v232 offset:51200
	ds_read_b128 v[172:175], v232 offset:52224
	ds_read_b128 v[176:179], v232 offset:53248
	ds_read_b128 v[180:183], v232 offset:54272
	ds_read_b128 v[184:187], v232 offset:55296
	ds_read_b128 v[188:191], v232 offset:56320
	global_load_lds_dwordx4 v[192:193], off
	s_add_i32 m0, s26, 0x2000
	s_add_u32 s24, s24, 0x40080
	v_lshl_add_u64 v[192:193], v[194:195], 0, s[10:11]
	s_addc_u32 s25, s25, 0
	s_add_i32 s26, s58, s30
	global_load_lds_dwordx4 v[192:193], off
	v_lshl_add_u64 v[192:193], s[24:25], 0, v[210:211]
	s_mov_b32 m0, s26
	s_nop 0
	global_load_lds_dwordx4 v[192:193], off
	v_lshl_add_u64 v[192:193], s[24:25], 0, v[214:215]
	s_add_i32 m0, s26, 0x2000
	s_nop 0
	global_load_lds_dwordx4 v[192:193], off
	v_lshl_add_u64 v[192:193], v[196:197], 0, s[10:11]
	s_mov_b32 m0, s40
	s_nop 0
	global_load_lds_dwordx4 v[192:193], off
	v_lshl_add_u64 v[192:193], v[198:199], 0, s[10:11]
	s_mov_b32 m0, s41
	s_nop 0
	global_load_lds_dwordx4 v[192:193], off
	s_waitcnt vmcnt(8)
	s_waitcnt lgkmcnt(0)
	s_barrier
	s_setprio 1
	s_waitcnt lgkmcnt(0)
	v_mfma_f32_16x16x32_bf16 v[60:63], v[96:99], v[160:163], v[60:63]
	v_mfma_f32_16x16x32_bf16 v[60:63], v[100:103], v[164:167], v[60:63]
	v_mfma_f32_16x16x32_bf16 v[56:59], v[116:119], v[164:167], v[56:59]
	v_mfma_f32_16x16x32_bf16 v[56:59], v[104:107], v[160:163], v[56:59]
	v_mfma_f32_16x16x32_bf16 v[52:55], v[120:123], v[160:163], v[52:55]
	v_mfma_f32_16x16x32_bf16 v[52:55], v[124:127], v[164:167], v[52:55]
	v_mfma_f32_16x16x32_bf16 v[48:51], v[148:151], v[164:167], v[48:51]
	v_mfma_f32_16x16x32_bf16 v[48:51], v[136:139], v[160:163], v[48:51]
	s_setprio 0
	s_setprio 1
	v_mfma_f32_16x16x32_bf16 v[32:35], v[136:139], v[168:171], v[32:35]
	v_mfma_f32_16x16x32_bf16 v[32:35], v[148:151], v[172:175], v[32:35]
	v_mfma_f32_16x16x32_bf16 v[36:39], v[124:127], v[172:175], v[36:39]
	v_mfma_f32_16x16x32_bf16 v[36:39], v[120:123], v[168:171], v[36:39]
	v_mfma_f32_16x16x32_bf16 v[40:43], v[104:107], v[168:171], v[40:43]
	v_mfma_f32_16x16x32_bf16 v[40:43], v[116:119], v[172:175], v[40:43]
	v_mfma_f32_16x16x32_bf16 v[44:47], v[100:103], v[172:175], v[44:47]
	v_mfma_f32_16x16x32_bf16 v[44:47], v[96:99], v[168:171], v[44:47]
	s_setprio 0
	s_setprio 1
	v_mfma_f32_16x16x32_bf16 v[28:31], v[96:99], v[176:179], v[28:31]
	v_mfma_f32_16x16x32_bf16 v[28:31], v[100:103], v[180:183], v[28:31]
	v_mfma_f32_16x16x32_bf16 v[24:27], v[116:119], v[180:183], v[24:27]
	v_mfma_f32_16x16x32_bf16 v[24:27], v[104:107], v[176:179], v[24:27]
	v_mfma_f32_16x16x32_bf16 v[20:23], v[120:123], v[176:179], v[20:23]
	v_mfma_f32_16x16x32_bf16 v[20:23], v[124:127], v[180:183], v[20:23]
	v_mfma_f32_16x16x32_bf16 v[16:19], v[148:151], v[180:183], v[16:19]
	v_mfma_f32_16x16x32_bf16 v[16:19], v[136:139], v[176:179], v[16:19]
	s_setprio 0
	s_setprio 1
	v_mfma_f32_16x16x32_bf16 v[0:3], v[136:139], v[184:187], v[0:3]
	v_mfma_f32_16x16x32_bf16 v[0:3], v[148:151], v[188:191], v[0:3]
	v_mfma_f32_16x16x32_bf16 v[4:7], v[124:127], v[188:191], v[4:7]
	v_mfma_f32_16x16x32_bf16 v[4:7], v[120:123], v[184:187], v[4:7]
	v_mfma_f32_16x16x32_bf16 v[8:11], v[104:107], v[184:187], v[8:11]
	v_mfma_f32_16x16x32_bf16 v[8:11], v[116:119], v[188:191], v[8:11]
	v_mfma_f32_16x16x32_bf16 v[12:15], v[100:103], v[188:191], v[12:15]
	v_mfma_f32_16x16x32_bf16 v[12:15], v[96:99], v[184:187], v[12:15]
	s_setprio 0
	s_barrier
	s_add_u32 s4, s4, 0x100
	s_addc_u32 s5, s5, 0
	s_add_u32 s54, s54, 0x100
	s_addc_u32 s55, s55, 0
	s_cmp_ge_i32 s56, s39
	s_mov_b32 s24, s56
	s_cbranch_scc0 .LBB0_912

; #define PG8_STAGE(bufoff, gbase, voff) do { _Pragma("unroll") for (int _i = 0; _i < 2; ++_i) \
;         __builtin_amdgcn_global_load_lds((const unsigned*)((const char*)(gbase) + (voff)[_i]), (LAS unsigned*)(lds + (bufoff) + ldsw + _i * 8192), 16, 0, 0); } while (0)
; #define PG8_LDA(dst, b, h) do { _Pragma("unroll") for (int m = 0; m < 4; ++m) _Pragma("unroll") for (int k = 0; k < 2; ++k) dst[m][k] = *(const LAS bf16x8*)(lds + PG8_SA(b, h) + aoff + m * 2048 + k * 1024); } while (0)
; #define PG8_LDB(dst, b, h) do { _Pragma("unroll") for (int n = 0; n < 2; ++n) _Pragma("unroll") for (int k = 0; k < 2; ++k) dst[n][k] = *(const LAS bf16x8*)(lds + PG8_SB(b, h) + boff + n * 2048 + k * 1024); } while (0)
; #define PG8_MMA(ai, bj, At, Bt) do { __builtin_amdgcn_s_setprio(1); _Pragma("unroll") for (int m = 0; m < 4; ++m) _Pragma("unroll") for (int n = 0; n < 2; ++n) _Pragma("unroll") for (int k = 0; k < 2; ++k) \
;         acc[ai][bj][m][n] = __builtin_amdgcn_mfma_f32_16x16x32_bf16(Bt[n][k], At[m][k], acc[ai][bj][m][n], 0, 0, 0); __builtin_amdgcn_s_setprio(0); } while (0)
; #define PG8_WAIT_V(n) asm volatile("s_waitcnt vmcnt(" #n ")" ::: "memory")
; #define PG8_WAIT_L(n) asm volatile("s_waitcnt lgkmcnt(" #n ")" ::: "memory")
; #define PG8_BAR __builtin_amdgcn_s_barrier()
; #define PG8_SCHED __builtin_amdgcn_sched_barrier(0)
; template <class Epi>
; __device__ __forceinline__ void gemm_phase(LAS unsigned char* lds, const Gemm g, const StaticOrder& S, const Epi& E) {
;     ...
;         for (int t = 0; t < nt; t += 2) {
;             const bool last = (t == nt - 2);
;             const char* a1 = cA + (size_t)(t + 1) * kstep;
;             const char* a2 = last ? nA : cA + (size_t)(t + 2) * kstep; const char* b2 = last ? nB : cB + (size_t)(t + 2) * kstep;
;             const char* a3 = a2 + kstep; const char* b3 = b2 + kstep;
;             PG8_LDB(B0, 0, 0); PG8_LDB(B1, 0, 1); PG8_SCHED; PG8_LDA(At, 0, 0); PG8_STAGE(PG8_SA(1, 1), a1 + hstepA, voffA);
;             PG8_WAIT_V(8); PG8_WAIT_L(0); PG8_BAR; PG8_MMA(0, 0, At, B0); PG8_MMA(0, 1, At, B1); PG8_BAR; PG8_SCHED;
;             PG8_LDA(At, 0, 1); PG8_STAGE(PG8_SB(0, 0), b2, voffB); PG8_STAGE(PG8_SB(0, 1), b2 + hstepB, voffB); PG8_STAGE(PG8_SA(0, 0), a2, voffA);
;             PG8_WAIT_V(8); PG8_WAIT_L(0); PG8_BAR; PG8_MMA(1, 0, At, B0); PG8_MMA(1, 1, At, B1); PG8_BAR; PG8_SCHED;
.LBB0_1046:
	ds_read_b128 v[128:131], v185
	ds_read_b128 v[132:135], v185 offset:1024
	ds_read_b128 v[136:139], v185 offset:2048
	ds_read_b128 v[140:143], v185 offset:3072
	ds_read_b128 v[144:147], v186
	ds_read_b128 v[148:151], v186 offset:1024
	ds_read_b128 v[152:155], v186 offset:2048
	ds_read_b128 v[156:159], v186 offset:3072
	s_add_i32 s73, s46, 2
	s_add_u32 s47, s12, 0xfff80080
	s_addc_u32 s48, s13, -1
	s_cmp_eq_u32 s62, s46
	s_cselect_b32 s46, s41, s71
	s_cselect_b32 s49, s1, s48
	s_cselect_b32 s48, s33, s47
	s_cselect_b32 s47, s39, s72
	v_lshl_add_u64 v[182:183], s[12:13], 0, v[174:175]
	s_add_i32 m0, s5, 0xc000
	ds_read_b128 v[190:193], v187
	ds_read_b128 v[194:197], v187 offset:1024
	ds_read_b128 v[198:201], v187 offset:2048
	ds_read_b128 v[208:211], v187 offset:3072
	ds_read_b128 v[212:215], v187 offset:4096
	ds_read_b128 v[216:219], v187 offset:5120
	ds_read_b128 v[220:223], v187 offset:6144
	ds_read_b128 v[224:227], v187 offset:7168
	global_load_lds_dwordx4 v[182:183], off
	v_lshl_add_u64 v[182:183], s[12:13], 0, v[176:177]
	s_add_i32 m0, s5, 0xe000
	s_nop 0
	global_load_lds_dwordx4 v[182:183], off
	s_waitcnt vmcnt(8)
	s_waitcnt lgkmcnt(0)
	s_barrier
	s_setprio 1
	s_waitcnt lgkmcnt(0)
	v_mfma_f32_16x16x32_bf16 v[120:123], v[128:131], v[190:193], v[120:123]
	v_mfma_f32_16x16x32_bf16 v[120:123], v[132:135], v[194:197], v[120:123]
	v_mfma_f32_16x16x32_bf16 v[124:127], v[140:143], v[194:197], v[124:127]
	v_mfma_f32_16x16x32_bf16 v[124:127], v[136:139], v[190:193], v[124:127]
	v_mfma_f32_16x16x32_bf16 v[116:119], v[144:147], v[190:193], v[116:119]
	v_mfma_f32_16x16x32_bf16 v[116:119], v[148:151], v[194:197], v[116:119]
	v_mfma_f32_16x16x32_bf16 v[112:115], v[156:159], v[194:197], v[112:115]
	v_mfma_f32_16x16x32_bf16 v[112:115], v[152:155], v[190:193], v[112:115]
	s_setprio 0
	s_setprio 1
	v_mfma_f32_16x16x32_bf16 v[96:99], v[152:155], v[198:201], v[96:99]
	v_mfma_f32_16x16x32_bf16 v[96:99], v[156:159], v[208:211], v[96:99]
	v_mfma_f32_16x16x32_bf16 v[100:103], v[148:151], v[208:211], v[100:103]
	v_mfma_f32_16x16x32_bf16 v[100:103], v[144:147], v[198:201], v[100:103]
	v_mfma_f32_16x16x32_bf16 v[104:107], v[136:139], v[198:201], v[104:107]
	v_mfma_f32_16x16x32_bf16 v[104:107], v[140:143], v[208:211], v[104:107]
	v_mfma_f32_16x16x32_bf16 v[108:111], v[132:135], v[208:211], v[108:111]
	v_mfma_f32_16x16x32_bf16 v[108:111], v[128:131], v[198:201], v[108:111]
	s_setprio 0
	s_setprio 1
	v_mfma_f32_16x16x32_bf16 v[92:95], v[128:131], v[212:215], v[92:95]
	v_mfma_f32_16x16x32_bf16 v[92:95], v[132:135], v[216:219], v[92:95]
	v_mfma_f32_16x16x32_bf16 v[88:91], v[140:143], v[216:219], v[88:91]
	v_mfma_f32_16x16x32_bf16 v[88:91], v[136:139], v[212:215], v[88:91]
	v_mfma_f32_16x16x32_bf16 v[84:87], v[144:147], v[212:215], v[84:87]
	v_mfma_f32_16x16x32_bf16 v[84:87], v[148:151], v[216:219], v[84:87]
	v_mfma_f32_16x16x32_bf16 v[80:83], v[156:159], v[216:219], v[80:83]
	v_mfma_f32_16x16x32_bf16 v[80:83], v[152:155], v[212:215], v[80:83]
	s_setprio 0
	s_setprio 1
	v_mfma_f32_16x16x32_bf16 v[64:67], v[152:155], v[220:223], v[64:67]
	v_mfma_f32_16x16x32_bf16 v[64:67], v[156:159], v[224:227], v[64:67]
	v_mfma_f32_16x16x32_bf16 v[68:71], v[148:151], v[224:227], v[68:71]
	v_mfma_f32_16x16x32_bf16 v[68:71], v[144:147], v[220:223], v[68:71]
	v_mfma_f32_16x16x32_bf16 v[72:75], v[136:139], v[220:223], v[72:75]
	v_mfma_f32_16x16x32_bf16 v[72:75], v[140:143], v[224:227], v[72:75]
	v_mfma_f32_16x16x32_bf16 v[76:79], v[132:135], v[224:227], v[76:79]
	v_mfma_f32_16x16x32_bf16 v[76:79], v[128:131], v[220:223], v[76:79]
	s_setprio 0
	s_barrier
	s_add_i32 s76, s65, s54
	v_lshl_add_u64 v[182:183], s[46:47], 0, v[162:163]
	s_mov_b32 m0, s76
	ds_read_b128 v[190:193], v187 offset:16384
	ds_read_b128 v[194:197], v187 offset:17408
	ds_read_b128 v[198:201], v187 offset:18432
	ds_read_b128 v[208:211], v187 offset:19456
	ds_read_b128 v[212:215], v187 offset:20480
	ds_read_b128 v[216:219], v187 offset:21504
	ds_read_b128 v[220:223], v187 offset:22528
	ds_read_b128 v[224:227], v187 offset:23552
	global_load_lds_dwordx4 v[182:183], off
	s_add_i32 m0, s76, 0x2000
	s_add_u32 s76, s46, 0x80000
	v_lshl_add_u64 v[202:203], s[46:47], 0, v[166:167]
	s_addc_u32 s77, s47, 0
	s_add_i32 s78, s66, s54
	global_load_lds_dwordx4 v[202:203], off
	v_lshl_add_u64 v[230:231], s[76:77], 0, v[162:163]
	s_mov_b32 m0, s78
	v_lshl_add_u64 v[232:233], s[48:49], 0, v[164:165]
	global_load_lds_dwordx4 v[230:231], off
	v_lshl_add_u64 v[230:231], s[76:77], 0, v[166:167]
	s_add_i32 m0, s78, 0x2000
	s_nop 0
	global_load_lds_dwordx4 v[230:231], off
	v_lshl_add_u64 v[230:231], s[48:49], 0, v[160:161]
	s_mov_b32 m0, s5
	s_nop 0
	global_load_lds_dwordx4 v[230:231], off
	s_mov_b32 m0, s55
	s_nop 0
	global_load_lds_dwordx4 v[232:233], off
	s_waitcnt vmcnt(8)
	s_waitcnt lgkmcnt(0)
	s_barrier
; #define PG8_STAGE(bufoff, gbase, voff) do { _Pragma("unroll") for (int _i = 0; _i < 2; ++_i) \
;         __builtin_amdgcn_global_load_lds((const unsigned*)((const char*)(gbase) + (voff)[_i]), (LAS unsigned*)(lds + (bufoff) + ldsw + _i * 8192), 16, 0, 0); } while (0)
; #define PG8_LDA(dst, b, h) do { _Pragma("unroll") for (int m = 0; m < 4; ++m) _Pragma("unroll") for (int k = 0; k < 2; ++k) dst[m][k] = *(const LAS bf16x8*)(lds + PG8_SA(b, h) + aoff + m * 2048 + k * 1024); } while (0)
; #define PG8_LDB(dst, b, h) do { _Pragma("unroll") for (int n = 0; n < 2; ++n) _Pragma("unroll") for (int k = 0; k < 2; ++k) dst[n][k] = *(const LAS bf16x8*)(lds + PG8_SB(b, h) + boff + n * 2048 + k * 1024); } while (0)
; #define PG8_MMA(ai, bj, At, Bt) do { __builtin_amdgcn_s_setprio(1); _Pragma("unroll") for (int m = 0; m < 4; ++m) _Pragma("unroll") for (int n = 0; n < 2; ++n) _Pragma("unroll") for (int k = 0; k < 2; ++k) \
;         acc[ai][bj][m][n] = __builtin_amdgcn_mfma_f32_16x16x32_bf16(Bt[n][k], At[m][k], acc[ai][bj][m][n], 0, 0, 0); __builtin_amdgcn_s_setprio(0); } while (0)
; #define PG8_WAIT_V(n) asm volatile("s_waitcnt vmcnt(" #n ")" ::: "memory")
; #define PG8_WAIT_L(n) asm volatile("s_waitcnt lgkmcnt(" #n ")" ::: "memory")
; #define PG8_BAR __builtin_amdgcn_s_barrier()
; #define PG8_SCHED __builtin_amdgcn_sched_barrier(0)
; template <class Epi>
; __device__ __forceinline__ void gemm_phase(LAS unsigned char* lds, const Gemm g, const StaticOrder& S, const Epi& E) {
;     ...
;             PG8_WAIT_V(8); PG8_WAIT_L(0); PG8_BAR; PG8_MMA(1, 0, At, B0); PG8_MMA(1, 1, At, B1); PG8_BAR; PG8_SCHED;
;             PG8_LDB(B0, 1, 0); PG8_LDB(B1, 1, 1); PG8_SCHED; PG8_LDA(At, 1, 0); PG8_STAGE(PG8_SA(0, 1), a2 + hstepA, voffA);
;             PG8_WAIT_V(8); PG8_WAIT_L(0); PG8_BAR; PG8_MMA(0, 0, At, B0); PG8_MMA(0, 1, At, B1); PG8_BAR; PG8_SCHED;
	s_setprio 1
	s_waitcnt lgkmcnt(0)
	v_mfma_f32_16x16x32_bf16 v[60:63], v[128:131], v[190:193], v[60:63]
	v_mfma_f32_16x16x32_bf16 v[60:63], v[132:135], v[194:197], v[60:63]
	v_mfma_f32_16x16x32_bf16 v[56:59], v[140:143], v[194:197], v[56:59]
	v_mfma_f32_16x16x32_bf16 v[56:59], v[136:139], v[190:193], v[56:59]
	v_mfma_f32_16x16x32_bf16 v[52:55], v[144:147], v[190:193], v[52:55]
	v_mfma_f32_16x16x32_bf16 v[52:55], v[148:151], v[194:197], v[52:55]
	v_mfma_f32_16x16x32_bf16 v[48:51], v[156:159], v[194:197], v[48:51]
	v_mfma_f32_16x16x32_bf16 v[48:51], v[152:155], v[190:193], v[48:51]
	s_setprio 0
	s_setprio 1
	v_mfma_f32_16x16x32_bf16 v[32:35], v[152:155], v[198:201], v[32:35]
	v_mfma_f32_16x16x32_bf16 v[32:35], v[156:159], v[208:211], v[32:35]
	v_mfma_f32_16x16x32_bf16 v[36:39], v[148:151], v[208:211], v[36:39]
	v_mfma_f32_16x16x32_bf16 v[36:39], v[144:147], v[198:201], v[36:39]
	v_mfma_f32_16x16x32_bf16 v[40:43], v[136:139], v[198:201], v[40:43]
	v_mfma_f32_16x16x32_bf16 v[40:43], v[140:143], v[208:211], v[40:43]
	v_mfma_f32_16x16x32_bf16 v[44:47], v[132:135], v[208:211], v[44:47]
	v_mfma_f32_16x16x32_bf16 v[44:47], v[128:131], v[198:201], v[44:47]
	s_setprio 0
	s_setprio 1
	v_mfma_f32_16x16x32_bf16 v[28:31], v[128:131], v[212:215], v[28:31]
	v_mfma_f32_16x16x32_bf16 v[28:31], v[132:135], v[216:219], v[28:31]
	v_mfma_f32_16x16x32_bf16 v[24:27], v[140:143], v[216:219], v[24:27]
	v_mfma_f32_16x16x32_bf16 v[24:27], v[136:139], v[212:215], v[24:27]
	v_mfma_f32_16x16x32_bf16 v[20:23], v[144:147], v[212:215], v[20:23]
	v_mfma_f32_16x16x32_bf16 v[20:23], v[148:151], v[216:219], v[20:23]
	v_mfma_f32_16x16x32_bf16 v[16:19], v[156:159], v[216:219], v[16:19]
	v_mfma_f32_16x16x32_bf16 v[16:19], v[152:155], v[212:215], v[16:19]
	s_setprio 0
	s_setprio 1
	v_mfma_f32_16x16x32_bf16 v[0:3], v[152:155], v[220:223], v[0:3]
	v_mfma_f32_16x16x32_bf16 v[0:3], v[156:159], v[224:227], v[0:3]
	v_mfma_f32_16x16x32_bf16 v[4:7], v[148:151], v[224:227], v[4:7]
	v_mfma_f32_16x16x32_bf16 v[4:7], v[144:147], v[220:223], v[4:7]
	v_mfma_f32_16x16x32_bf16 v[8:11], v[136:139], v[220:223], v[8:11]
	v_mfma_f32_16x16x32_bf16 v[8:11], v[140:143], v[224:227], v[8:11]
	v_mfma_f32_16x16x32_bf16 v[12:15], v[132:135], v[224:227], v[12:15]
	v_mfma_f32_16x16x32_bf16 v[12:15], v[128:131], v[220:223], v[12:15]
	s_setprio 0
	s_barrier
	s_add_i32 s76, 0, 0x18000
	s_add_i32 s77, 0, 0x1c000
	v_add_u32_e32 v140, s76, v184
	v_add_u32_e32 v156, s77, v184
	ds_read_b128 v[128:131], v140
	ds_read_b128 v[132:135], v140 offset:1024
	ds_read_b128 v[136:139], v140 offset:2048
	ds_read_b128 v[140:143], v140 offset:3072
	ds_read_b128 v[144:147], v156
	ds_read_b128 v[148:151], v156 offset:1024
	ds_read_b128 v[152:155], v156 offset:2048
	ds_read_b128 v[156:159], v156 offset:3072
	s_add_u32 s48, s48, 0x80000
	s_addc_u32 s49, s49, 0
	s_mov_b32 m0, s56
	v_lshl_add_u64 v[234:235], s[48:49], 0, v[160:161]
	ds_read_b128 v[190:193], v187 offset:32768
	ds_read_b128 v[194:197], v187 offset:33792
	ds_read_b128 v[198:201], v187 offset:34816
	ds_read_b128 v[208:211], v187 offset:35840
	ds_read_b128 v[212:215], v187 offset:36864
	ds_read_b128 v[216:219], v187 offset:37888
	ds_read_b128 v[220:223], v187 offset:38912
	ds_read_b128 v[224:227], v187 offset:39936
	global_load_lds_dwordx4 v[234:235], off
	v_lshl_add_u64 v[234:235], s[48:49], 0, v[164:165]
	s_mov_b32 m0, s57
	s_nop 0
	global_load_lds_dwordx4 v[234:235], off
	s_waitcnt vmcnt(8)
	s_waitcnt lgkmcnt(0)
	s_barrier
	s_setprio 1
	s_waitcnt lgkmcnt(0)
	v_mfma_f32_16x16x32_bf16 v[120:123], v[128:131], v[190:193], v[120:123]
	v_mfma_f32_16x16x32_bf16 v[120:123], v[132:135], v[194:197], v[120:123]
	v_mfma_f32_16x16x32_bf16 v[124:127], v[140:143], v[194:197], v[124:127]
	v_mfma_f32_16x16x32_bf16 v[124:127], v[136:139], v[190:193], v[124:127]
	v_mfma_f32_16x16x32_bf16 v[116:119], v[144:147], v[190:193], v[116:119]
	v_mfma_f32_16x16x32_bf16 v[116:119], v[148:151], v[194:197], v[116:119]
	v_mfma_f32_16x16x32_bf16 v[112:115], v[156:159], v[194:197], v[112:115]
	v_mfma_f32_16x16x32_bf16 v[112:115], v[152:155], v[190:193], v[112:115]
	s_setprio 0
	s_setprio 1
	v_mfma_f32_16x16x32_bf16 v[96:99], v[152:155], v[198:201], v[96:99]
	v_mfma_f32_16x16x32_bf16 v[96:99], v[156:159], v[208:211], v[96:99]
	v_mfma_f32_16x16x32_bf16 v[100:103], v[148:151], v[208:211], v[100:103]
	v_mfma_f32_16x16x32_bf16 v[100:103], v[144:147], v[198:201], v[100:103]
	v_mfma_f32_16x16x32_bf16 v[104:107], v[136:139], v[198:201], v[104:107]
	v_mfma_f32_16x16x32_bf16 v[104:107], v[140:143], v[208:211], v[104:107]
	v_mfma_f32_16x16x32_bf16 v[108:111], v[132:135], v[208:211], v[108:111]
	v_mfma_f32_16x16x32_bf16 v[108:111], v[128:131], v[198:201], v[108:111]
	s_setprio 0
	s_setprio 1
	v_mfma_f32_16x16x32_bf16 v[92:95], v[128:131], v[212:215], v[92:95]
	v_mfma_f32_16x16x32_bf16 v[92:95], v[132:135], v[216:219], v[92:95]
	v_mfma_f32_16x16x32_bf16 v[88:91], v[140:143], v[216:219], v[88:91]
	v_mfma_f32_16x16x32_bf16 v[88:91], v[136:139], v[212:215], v[88:91]
	v_mfma_f32_16x16x32_bf16 v[84:87], v[144:147], v[212:215], v[84:87]
	v_mfma_f32_16x16x32_bf16 v[84:87], v[148:151], v[216:219], v[84:87]
	v_mfma_f32_16x16x32_bf16 v[80:83], v[156:159], v[216:219], v[80:83]
	v_mfma_f32_16x16x32_bf16 v[80:83], v[152:155], v[212:215], v[80:83]
	s_setprio 0
	s_setprio 1
	v_mfma_f32_16x16x32_bf16 v[64:67], v[152:155], v[220:223], v[64:67]
	v_mfma_f32_16x16x32_bf16 v[64:67], v[156:159], v[224:227], v[64:67]
	v_mfma_f32_16x16x32_bf16 v[68:71], v[148:151], v[224:227], v[68:71]
	v_mfma_f32_16x16x32_bf16 v[68:71], v[144:147], v[220:223], v[68:71]
	v_mfma_f32_16x16x32_bf16 v[72:75], v[136:139], v[220:223], v[72:75]
	v_mfma_f32_16x16x32_bf16 v[72:75], v[140:143], v[224:227], v[72:75]
	v_mfma_f32_16x16x32_bf16 v[76:79], v[132:135], v[224:227], v[76:79]
	v_mfma_f32_16x16x32_bf16 v[76:79], v[128:131], v[220:223], v[76:79]
	s_setprio 0
	s_barrier
; #define PG8_STAGE(bufoff, gbase, voff) do { _Pragma("unroll") for (int _i = 0; _i < 2; ++_i) \
;         __builtin_amdgcn_global_load_lds((const unsigned*)((const char*)(gbase) + (voff)[_i]), (LAS unsigned*)(lds + (bufoff) + ldsw + _i * 8192), 16, 0, 0); } while (0)
; #define PG8_LDA(dst, b, h) do { _Pragma("unroll") for (int m = 0; m < 4; ++m) _Pragma("unroll") for (int k = 0; k < 2; ++k) dst[m][k] = *(const LAS bf16x8*)(lds + PG8_SA(b, h) + aoff + m * 2048 + k * 1024); } while (0)
; #define PG8_MMA(ai, bj, At, Bt) do { __builtin_amdgcn_s_setprio(1); _Pragma("unroll") for (int m = 0; m < 4; ++m) _Pragma("unroll") for (int n = 0; n < 2; ++n) _Pragma("unroll") for (int k = 0; k < 2; ++k) \
;         acc[ai][bj][m][n] = __builtin_amdgcn_mfma_f32_16x16x32_bf16(Bt[n][k], At[m][k], acc[ai][bj][m][n], 0, 0, 0); __builtin_amdgcn_s_setprio(0); } while (0)
; #define PG8_WAIT_V(n) asm volatile("s_waitcnt vmcnt(" #n ")" ::: "memory")
; #define PG8_WAIT_L(n) asm volatile("s_waitcnt lgkmcnt(" #n ")" ::: "memory")
; #define PG8_BAR __builtin_amdgcn_s_barrier()
; #define PG8_SCHED __builtin_amdgcn_sched_barrier(0)
; template <class Epi>
; __device__ __forceinline__ void gemm_phase(LAS unsigned char* lds, const Gemm g, const StaticOrder& S, const Epi& E) {
;     ...
;             PG8_LDA(At, 1, 1); PG8_STAGE(PG8_SB(1, 0), b3, voffB); PG8_STAGE(PG8_SB(1, 1), b3 + hstepB, voffB); PG8_STAGE(PG8_SA(1, 0), a3, voffA);
;             PG8_WAIT_V(8); PG8_WAIT_L(0); PG8_BAR; PG8_MMA(1, 0, At, B0); PG8_MMA(1, 1, At, B1); PG8_BAR; PG8_SCHED;
;         }
	s_add_i32 s48, s76, s54
	v_lshl_add_u64 v[182:183], v[182:183], 0, s[16:17]
	s_mov_b32 m0, s48
	ds_read_b128 v[190:193], v187 offset:49152
	ds_read_b128 v[194:197], v187 offset:50176
	ds_read_b128 v[198:201], v187 offset:51200
	ds_read_b128 v[208:211], v187 offset:52224
	ds_read_b128 v[212:215], v187 offset:53248
	ds_read_b128 v[216:219], v187 offset:54272
	ds_read_b128 v[220:223], v187 offset:55296
	ds_read_b128 v[224:227], v187 offset:56320
	global_load_lds_dwordx4 v[182:183], off
	s_add_i32 m0, s48, 0x2000
	s_add_u32 s46, s46, 0x80080
	v_lshl_add_u64 v[182:183], v[202:203], 0, s[16:17]
	s_addc_u32 s47, s47, 0
	s_add_i32 s48, s77, s54
	global_load_lds_dwordx4 v[182:183], off
	v_lshl_add_u64 v[182:183], s[46:47], 0, v[162:163]
	s_mov_b32 m0, s48
	s_nop 0
	global_load_lds_dwordx4 v[182:183], off
	v_lshl_add_u64 v[182:183], s[46:47], 0, v[166:167]
	s_add_i32 m0, s48, 0x2000
	s_nop 0
	global_load_lds_dwordx4 v[182:183], off
	v_lshl_add_u64 v[182:183], v[230:231], 0, s[16:17]
	s_mov_b32 m0, s60
	s_nop 0
	global_load_lds_dwordx4 v[182:183], off
	v_lshl_add_u64 v[182:183], v[232:233], 0, s[16:17]
	s_mov_b32 m0, s61
	s_nop 0
	global_load_lds_dwordx4 v[182:183], off
	s_waitcnt vmcnt(8)
	s_waitcnt lgkmcnt(0)
	s_barrier
	s_setprio 1
	s_waitcnt lgkmcnt(0)
	v_mfma_f32_16x16x32_bf16 v[60:63], v[128:131], v[190:193], v[60:63]
	v_mfma_f32_16x16x32_bf16 v[60:63], v[132:135], v[194:197], v[60:63]
	v_mfma_f32_16x16x32_bf16 v[56:59], v[140:143], v[194:197], v[56:59]
	v_mfma_f32_16x16x32_bf16 v[56:59], v[136:139], v[190:193], v[56:59]
	v_mfma_f32_16x16x32_bf16 v[52:55], v[144:147], v[190:193], v[52:55]
	v_mfma_f32_16x16x32_bf16 v[52:55], v[148:151], v[194:197], v[52:55]
	v_mfma_f32_16x16x32_bf16 v[48:51], v[156:159], v[194:197], v[48:51]
	v_mfma_f32_16x16x32_bf16 v[48:51], v[152:155], v[190:193], v[48:51]
	s_setprio 0
	s_setprio 1
	v_mfma_f32_16x16x32_bf16 v[32:35], v[152:155], v[198:201], v[32:35]
	v_mfma_f32_16x16x32_bf16 v[32:35], v[156:159], v[208:211], v[32:35]
	v_mfma_f32_16x16x32_bf16 v[36:39], v[148:151], v[208:211], v[36:39]
	v_mfma_f32_16x16x32_bf16 v[36:39], v[144:147], v[198:201], v[36:39]
	v_mfma_f32_16x16x32_bf16 v[40:43], v[136:139], v[198:201], v[40:43]
	v_mfma_f32_16x16x32_bf16 v[40:43], v[140:143], v[208:211], v[40:43]
	v_mfma_f32_16x16x32_bf16 v[44:47], v[132:135], v[208:211], v[44:47]
	v_mfma_f32_16x16x32_bf16 v[44:47], v[128:131], v[198:201], v[44:47]
	s_setprio 0
	s_setprio 1
	v_mfma_f32_16x16x32_bf16 v[28:31], v[128:131], v[212:215], v[28:31]
	v_mfma_f32_16x16x32_bf16 v[28:31], v[132:135], v[216:219], v[28:31]
	v_mfma_f32_16x16x32_bf16 v[24:27], v[140:143], v[216:219], v[24:27]
	v_mfma_f32_16x16x32_bf16 v[24:27], v[136:139], v[212:215], v[24:27]
	v_mfma_f32_16x16x32_bf16 v[20:23], v[144:147], v[212:215], v[20:23]
	v_mfma_f32_16x16x32_bf16 v[20:23], v[148:151], v[216:219], v[20:23]
	v_mfma_f32_16x16x32_bf16 v[16:19], v[156:159], v[216:219], v[16:19]
	v_mfma_f32_16x16x32_bf16 v[16:19], v[152:155], v[212:215], v[16:19]
	s_setprio 0
	s_setprio 1
	v_mfma_f32_16x16x32_bf16 v[0:3], v[152:155], v[220:223], v[0:3]
	v_mfma_f32_16x16x32_bf16 v[0:3], v[156:159], v[224:227], v[0:3]
	v_mfma_f32_16x16x32_bf16 v[4:7], v[148:151], v[224:227], v[4:7]
	v_mfma_f32_16x16x32_bf16 v[4:7], v[144:147], v[220:223], v[4:7]
	v_mfma_f32_16x16x32_bf16 v[8:11], v[136:139], v[220:223], v[8:11]
	v_mfma_f32_16x16x32_bf16 v[8:11], v[140:143], v[224:227], v[8:11]
	v_mfma_f32_16x16x32_bf16 v[12:15], v[132:135], v[224:227], v[12:15]
	v_mfma_f32_16x16x32_bf16 v[12:15], v[128:131], v[220:223], v[12:15]
	s_setprio 0
	s_barrier
	s_add_u32 s12, s12, 0x100
	s_addc_u32 s13, s13, 0
	s_add_u32 s71, s71, 0x100
	s_addc_u32 s72, s72, 0
	s_cmp_ge_i32 s73, s59
	s_mov_b32 s46, s73
	s_cbranch_scc0 .LBB0_1046

; #define PG8_STAGE(bufoff, gbase, voff) do { _Pragma("unroll") for (int _i = 0; _i < 2; ++_i) \
;         __builtin_amdgcn_global_load_lds((const unsigned*)((const char*)(gbase) + (voff)[_i]), (LAS unsigned*)(lds + (bufoff) + ldsw + _i * 8192), 16, 0, 0); } while (0)
; #define PG8_LDA(dst, b, h) do { _Pragma("unroll") for (int m = 0; m < 4; ++m) _Pragma("unroll") for (int k = 0; k < 2; ++k) dst[m][k] = *(const LAS bf16x8*)(lds + PG8_SA(b, h) + aoff + m * 2048 + k * 1024); } while (0)
; #define PG8_LDB(dst, b, h) do { _Pragma("unroll") for (int n = 0; n < 2; ++n) _Pragma("unroll") for (int k = 0; k < 2; ++k) dst[n][k] = *(const LAS bf16x8*)(lds + PG8_SB(b, h) + boff + n * 2048 + k * 1024); } while (0)
; #define PG8_MMA(ai, bj, At, Bt) do { __builtin_amdgcn_s_setprio(1); _Pragma("unroll") for (int m = 0; m < 4; ++m) _Pragma("unroll") for (int n = 0; n < 2; ++n) _Pragma("unroll") for (int k = 0; k < 2; ++k) \
;         acc[ai][bj][m][n] = __builtin_amdgcn_mfma_f32_16x16x32_bf16(Bt[n][k], At[m][k], acc[ai][bj][m][n], 0, 0, 0); __builtin_amdgcn_s_setprio(0); } while (0)
; #define PG8_WAIT_V(n) asm volatile("s_waitcnt vmcnt(" #n ")" ::: "memory")
; #define PG8_WAIT_L(n) asm volatile("s_waitcnt lgkmcnt(" #n ")" ::: "memory")
; #define PG8_BAR __builtin_amdgcn_s_barrier()
; #define PG8_SCHED __builtin_amdgcn_sched_barrier(0)
; template <class Epi>
; __device__ __forceinline__ void gemm_phase(LAS unsigned char* lds, const Gemm g, const StaticOrder& S, const Epi& E) {
;     ...
;         for (int t = 0; t < nt; t += 2) {
;             const bool last = (t == nt - 2);
;             const char* a1 = cA + (size_t)(t + 1) * kstep;
;             const char* a2 = last ? nA : cA + (size_t)(t + 2) * kstep; const char* b2 = last ? nB : cB + (size_t)(t + 2) * kstep;
;             const char* a3 = a2 + kstep; const char* b3 = b2 + kstep;
;             PG8_LDB(B0, 0, 0); PG8_LDB(B1, 0, 1); PG8_SCHED; PG8_LDA(At, 0, 0); PG8_STAGE(PG8_SA(1, 1), a1 + hstepA, voffA);
;             PG8_WAIT_V(8); PG8_WAIT_L(0); PG8_BAR; PG8_MMA(0, 0, At, B0); PG8_MMA(0, 1, At, B1); PG8_BAR; PG8_SCHED;
;             PG8_LDA(At, 0, 1); PG8_STAGE(PG8_SB(0, 0), b2, voffB); PG8_STAGE(PG8_SB(0, 1), b2 + hstepB, voffB); PG8_STAGE(PG8_SA(0, 0), a2, voffA);
;             PG8_WAIT_V(8); PG8_WAIT_L(0); PG8_BAR; PG8_MMA(1, 0, At, B0); PG8_MMA(1, 1, At, B1); PG8_BAR; PG8_SCHED;
.LBB0_1131:
	ds_read_b128 v[164:167], v182
	ds_read_b128 v[168:171], v182 offset:1024
	ds_read_b128 v[172:175], v182 offset:2048
	ds_read_b128 v[176:179], v182 offset:3072
	ds_read_b128 v[186:189], v183
	ds_read_b128 v[190:193], v183 offset:1024
	ds_read_b128 v[194:197], v183 offset:2048
	ds_read_b128 v[198:201], v183 offset:3072
	s_add_i32 s22, s12, 2
	s_add_u32 s13, s10, 0xfff80080
	s_addc_u32 s14, s11, -1
	s_cmp_eq_u32 s58, s12
	s_cselect_b32 s12, s19, s20
	s_cselect_b32 s15, s16, s14
	s_cselect_b32 s14, s17, s13
	s_cselect_b32 s13, s18, s21
	v_lshl_add_u64 v[202:203], s[10:11], 0, v[140:141]
	s_add_i32 m0, s33, 0xc000
	ds_read_b128 v[208:211], v184
	ds_read_b128 v[212:215], v184 offset:1024
	ds_read_b128 v[216:219], v184 offset:2048
	ds_read_b128 v[220:223], v184 offset:3072
	ds_read_b128 v[224:227], v184 offset:4096
	ds_read_b128 v[230:233], v184 offset:5120
	ds_read_b128 v[234:237], v184 offset:6144
	ds_read_b128 v[238:241], v184 offset:7168
	global_load_lds_dwordx4 v[202:203], off
	v_lshl_add_u64 v[202:203], s[10:11], 0, v[142:143]
	s_add_i32 m0, s33, 0xe000
	s_nop 0
	global_load_lds_dwordx4 v[202:203], off
	s_waitcnt vmcnt(8)
	s_waitcnt lgkmcnt(0)
	s_barrier
	s_setprio 1
	s_waitcnt lgkmcnt(0)
	v_mfma_f32_16x16x32_bf16 v[120:123], v[164:167], v[208:211], v[120:123]
	v_mfma_f32_16x16x32_bf16 v[120:123], v[168:171], v[212:215], v[120:123]
	v_mfma_f32_16x16x32_bf16 v[116:119], v[176:179], v[212:215], v[116:119]
	v_mfma_f32_16x16x32_bf16 v[116:119], v[172:175], v[208:211], v[116:119]
	v_mfma_f32_16x16x32_bf16 v[124:127], v[186:189], v[208:211], v[124:127]
	v_mfma_f32_16x16x32_bf16 v[124:127], v[190:193], v[212:215], v[124:127]
	v_mfma_f32_16x16x32_bf16 v[112:115], v[198:201], v[212:215], v[112:115]
	v_mfma_f32_16x16x32_bf16 v[112:115], v[194:197], v[208:211], v[112:115]
	s_setprio 0
	s_setprio 1
	v_mfma_f32_16x16x32_bf16 v[96:99], v[194:197], v[216:219], v[96:99]
	v_mfma_f32_16x16x32_bf16 v[96:99], v[198:201], v[220:223], v[96:99]
	v_mfma_f32_16x16x32_bf16 v[104:107], v[190:193], v[220:223], v[104:107]
	v_mfma_f32_16x16x32_bf16 v[104:107], v[186:189], v[216:219], v[104:107]
	v_mfma_f32_16x16x32_bf16 v[100:103], v[172:175], v[216:219], v[100:103]
	v_mfma_f32_16x16x32_bf16 v[100:103], v[176:179], v[220:223], v[100:103]
	v_mfma_f32_16x16x32_bf16 v[108:111], v[168:171], v[220:223], v[108:111]
	v_mfma_f32_16x16x32_bf16 v[108:111], v[164:167], v[216:219], v[108:111]
	s_setprio 0
	s_setprio 1
	v_mfma_f32_16x16x32_bf16 v[92:95], v[164:167], v[224:227], v[92:95]
	v_mfma_f32_16x16x32_bf16 v[92:95], v[168:171], v[230:233], v[92:95]
	v_mfma_f32_16x16x32_bf16 v[84:87], v[176:179], v[230:233], v[84:87]
	v_mfma_f32_16x16x32_bf16 v[84:87], v[172:175], v[224:227], v[84:87]
	v_mfma_f32_16x16x32_bf16 v[88:91], v[186:189], v[224:227], v[88:91]
	v_mfma_f32_16x16x32_bf16 v[88:91], v[190:193], v[230:233], v[88:91]
	v_mfma_f32_16x16x32_bf16 v[80:83], v[198:201], v[230:233], v[80:83]
	v_mfma_f32_16x16x32_bf16 v[80:83], v[194:197], v[224:227], v[80:83]
	s_setprio 0
	s_setprio 1
	v_mfma_f32_16x16x32_bf16 v[64:67], v[194:197], v[234:237], v[64:67]
	v_mfma_f32_16x16x32_bf16 v[64:67], v[198:201], v[238:241], v[64:67]
	v_mfma_f32_16x16x32_bf16 v[72:75], v[190:193], v[238:241], v[72:75]
	v_mfma_f32_16x16x32_bf16 v[72:75], v[186:189], v[234:237], v[72:75]
	v_mfma_f32_16x16x32_bf16 v[68:71], v[172:175], v[234:237], v[68:71]
	v_mfma_f32_16x16x32_bf16 v[68:71], v[176:179], v[238:241], v[68:71]
	v_mfma_f32_16x16x32_bf16 v[76:79], v[168:171], v[238:241], v[76:79]
	v_mfma_f32_16x16x32_bf16 v[76:79], v[164:167], v[234:237], v[76:79]
	s_setprio 0
	s_barrier
	s_add_i32 s23, s62, s37
	v_lshl_add_u64 v[202:203], s[12:13], 0, v[132:133]
	s_mov_b32 m0, s23
	ds_read_b128 v[208:211], v184 offset:16384
	ds_read_b128 v[212:215], v184 offset:17408
	ds_read_b128 v[216:219], v184 offset:18432
	ds_read_b128 v[220:223], v184 offset:19456
	ds_read_b128 v[224:227], v184 offset:20480
	ds_read_b128 v[230:233], v184 offset:21504
	ds_read_b128 v[234:237], v184 offset:22528
	ds_read_b128 v[238:241], v184 offset:23552
	global_load_lds_dwordx4 v[202:203], off
	s_add_i32 m0, s23, 0x2000
	s_add_u32 s50, s12, 0x80000
	v_lshl_add_u64 v[242:243], s[12:13], 0, v[128:129]
	s_addc_u32 s51, s13, 0
	s_add_i32 s23, s63, s37
	global_load_lds_dwordx4 v[242:243], off
	v_lshl_add_u64 v[244:245], s[50:51], 0, v[132:133]
	s_mov_b32 m0, s23
	v_lshl_add_u64 v[246:247], s[14:15], 0, v[130:131]
	global_load_lds_dwordx4 v[244:245], off
	v_lshl_add_u64 v[244:245], s[50:51], 0, v[128:129]
	s_add_i32 m0, s23, 0x2000
	s_nop 0
	global_load_lds_dwordx4 v[244:245], off
	v_lshl_add_u64 v[244:245], s[14:15], 0, v[134:135]
	s_mov_b32 m0, s33
	s_nop 0
	global_load_lds_dwordx4 v[244:245], off
	s_mov_b32 m0, s52
	s_nop 0
	global_load_lds_dwordx4 v[246:247], off
	s_waitcnt vmcnt(8)
	s_waitcnt lgkmcnt(0)
	s_barrier
; #define PG8_STAGE(bufoff, gbase, voff) do { _Pragma("unroll") for (int _i = 0; _i < 2; ++_i) \
;         __builtin_amdgcn_global_load_lds((const unsigned*)((const char*)(gbase) + (voff)[_i]), (LAS unsigned*)(lds + (bufoff) + ldsw + _i * 8192), 16, 0, 0); } while (0)
; #define PG8_LDA(dst, b, h) do { _Pragma("unroll") for (int m = 0; m < 4; ++m) _Pragma("unroll") for (int k = 0; k < 2; ++k) dst[m][k] = *(const LAS bf16x8*)(lds + PG8_SA(b, h) + aoff + m * 2048 + k * 1024); } while (0)
; #define PG8_LDB(dst, b, h) do { _Pragma("unroll") for (int n = 0; n < 2; ++n) _Pragma("unroll") for (int k = 0; k < 2; ++k) dst[n][k] = *(const LAS bf16x8*)(lds + PG8_SB(b, h) + boff + n * 2048 + k * 1024); } while (0)
; #define PG8_MMA(ai, bj, At, Bt) do { __builtin_amdgcn_s_setprio(1); _Pragma("unroll") for (int m = 0; m < 4; ++m) _Pragma("unroll") for (int n = 0; n < 2; ++n) _Pragma("unroll") for (int k = 0; k < 2; ++k) \
;         acc[ai][bj][m][n] = __builtin_amdgcn_mfma_f32_16x16x32_bf16(Bt[n][k], At[m][k], acc[ai][bj][m][n], 0, 0, 0); __builtin_amdgcn_s_setprio(0); } while (0)
; #define PG8_WAIT_V(n) asm volatile("s_waitcnt vmcnt(" #n ")" ::: "memory")
; #define PG8_WAIT_L(n) asm volatile("s_waitcnt lgkmcnt(" #n ")" ::: "memory")
; #define PG8_BAR __builtin_amdgcn_s_barrier()
; #define PG8_SCHED __builtin_amdgcn_sched_barrier(0)
; template <class Epi>
; __device__ __forceinline__ void gemm_phase(LAS unsigned char* lds, const Gemm g, const StaticOrder& S, const Epi& E) {
;     ...
;             PG8_WAIT_V(8); PG8_WAIT_L(0); PG8_BAR; PG8_MMA(1, 0, At, B0); PG8_MMA(1, 1, At, B1); PG8_BAR; PG8_SCHED;
;             PG8_LDB(B0, 1, 0); PG8_LDB(B1, 1, 1); PG8_SCHED; PG8_LDA(At, 1, 0); PG8_STAGE(PG8_SA(0, 1), a2 + hstepA, voffA);
;             PG8_WAIT_V(8); PG8_WAIT_L(0); PG8_BAR; PG8_MMA(0, 0, At, B0); PG8_MMA(0, 1, At, B1); PG8_BAR; PG8_SCHED;
	s_setprio 1
	s_waitcnt lgkmcnt(0)
	v_mfma_f32_16x16x32_bf16 v[60:63], v[164:167], v[208:211], v[60:63]
	v_mfma_f32_16x16x32_bf16 v[60:63], v[168:171], v[212:215], v[60:63]
	v_mfma_f32_16x16x32_bf16 v[52:55], v[176:179], v[212:215], v[52:55]
	v_mfma_f32_16x16x32_bf16 v[52:55], v[172:175], v[208:211], v[52:55]
	v_mfma_f32_16x16x32_bf16 v[56:59], v[186:189], v[208:211], v[56:59]
	v_mfma_f32_16x16x32_bf16 v[56:59], v[190:193], v[212:215], v[56:59]
	v_mfma_f32_16x16x32_bf16 v[48:51], v[198:201], v[212:215], v[48:51]
	v_mfma_f32_16x16x32_bf16 v[48:51], v[194:197], v[208:211], v[48:51]
	s_setprio 0
	s_setprio 1
	v_mfma_f32_16x16x32_bf16 v[32:35], v[194:197], v[216:219], v[32:35]
	v_mfma_f32_16x16x32_bf16 v[32:35], v[198:201], v[220:223], v[32:35]
	v_mfma_f32_16x16x32_bf16 v[40:43], v[190:193], v[220:223], v[40:43]
	v_mfma_f32_16x16x32_bf16 v[40:43], v[186:189], v[216:219], v[40:43]
	v_mfma_f32_16x16x32_bf16 v[36:39], v[172:175], v[216:219], v[36:39]
	v_mfma_f32_16x16x32_bf16 v[36:39], v[176:179], v[220:223], v[36:39]
	v_mfma_f32_16x16x32_bf16 v[44:47], v[168:171], v[220:223], v[44:47]
	v_mfma_f32_16x16x32_bf16 v[44:47], v[164:167], v[216:219], v[44:47]
	s_setprio 0
	s_setprio 1
	v_mfma_f32_16x16x32_bf16 v[28:31], v[164:167], v[224:227], v[28:31]
	v_mfma_f32_16x16x32_bf16 v[28:31], v[168:171], v[230:233], v[28:31]
	v_mfma_f32_16x16x32_bf16 v[20:23], v[176:179], v[230:233], v[20:23]
	v_mfma_f32_16x16x32_bf16 v[20:23], v[172:175], v[224:227], v[20:23]
	v_mfma_f32_16x16x32_bf16 v[24:27], v[186:189], v[224:227], v[24:27]
	v_mfma_f32_16x16x32_bf16 v[24:27], v[190:193], v[230:233], v[24:27]
	v_mfma_f32_16x16x32_bf16 v[16:19], v[198:201], v[230:233], v[16:19]
	v_mfma_f32_16x16x32_bf16 v[16:19], v[194:197], v[224:227], v[16:19]
	s_setprio 0
	s_setprio 1
	v_mfma_f32_16x16x32_bf16 v[0:3], v[194:197], v[234:237], v[0:3]
	v_mfma_f32_16x16x32_bf16 v[0:3], v[198:201], v[238:241], v[0:3]
	v_mfma_f32_16x16x32_bf16 v[8:11], v[190:193], v[238:241], v[8:11]
	v_mfma_f32_16x16x32_bf16 v[8:11], v[186:189], v[234:237], v[8:11]
	v_mfma_f32_16x16x32_bf16 v[4:7], v[172:175], v[234:237], v[4:7]
	v_mfma_f32_16x16x32_bf16 v[4:7], v[176:179], v[238:241], v[4:7]
	v_mfma_f32_16x16x32_bf16 v[12:15], v[168:171], v[238:241], v[12:15]
	v_mfma_f32_16x16x32_bf16 v[12:15], v[164:167], v[234:237], v[12:15]
	s_setprio 0
	s_barrier
	s_add_i32 s23, 0, 0x18000
	s_add_i32 s25, 0, 0x1c000
	v_add_u32_e32 v176, s23, v180
	v_add_u32_e32 v185, s25, v180
	ds_read_b128 v[164:167], v176
	ds_read_b128 v[168:171], v176 offset:1024
	ds_read_b128 v[172:175], v176 offset:2048
	ds_read_b128 v[176:179], v176 offset:3072
	ds_read_b128 v[186:189], v185
	ds_read_b128 v[190:193], v185 offset:1024
	ds_read_b128 v[194:197], v185 offset:2048
	ds_read_b128 v[198:201], v185 offset:3072
	s_add_u32 s14, s14, 0x80000
	s_addc_u32 s15, s15, 0
	s_mov_b32 m0, s53
	v_lshl_add_u64 v[248:249], s[14:15], 0, v[134:135]
	ds_read_b128 v[208:211], v184 offset:32768
	ds_read_b128 v[212:215], v184 offset:33792
	ds_read_b128 v[216:219], v184 offset:34816
	ds_read_b128 v[220:223], v184 offset:35840
	ds_read_b128 v[224:227], v184 offset:36864
	ds_read_b128 v[230:233], v184 offset:37888
	ds_read_b128 v[234:237], v184 offset:38912
	ds_read_b128 v[238:241], v184 offset:39936
	global_load_lds_dwordx4 v[248:249], off
	v_lshl_add_u64 v[248:249], s[14:15], 0, v[130:131]
	s_mov_b32 m0, s54
	s_nop 0
	global_load_lds_dwordx4 v[248:249], off
	s_waitcnt vmcnt(8)
	s_waitcnt lgkmcnt(0)
	s_barrier
	s_setprio 1
	s_waitcnt lgkmcnt(0)
	v_mfma_f32_16x16x32_bf16 v[120:123], v[164:167], v[208:211], v[120:123]
	v_mfma_f32_16x16x32_bf16 v[120:123], v[168:171], v[212:215], v[120:123]
	v_mfma_f32_16x16x32_bf16 v[116:119], v[176:179], v[212:215], v[116:119]
	v_mfma_f32_16x16x32_bf16 v[116:119], v[172:175], v[208:211], v[116:119]
	v_mfma_f32_16x16x32_bf16 v[124:127], v[186:189], v[208:211], v[124:127]
	v_mfma_f32_16x16x32_bf16 v[124:127], v[190:193], v[212:215], v[124:127]
	v_mfma_f32_16x16x32_bf16 v[112:115], v[198:201], v[212:215], v[112:115]
	v_mfma_f32_16x16x32_bf16 v[112:115], v[194:197], v[208:211], v[112:115]
	s_setprio 0
	s_setprio 1
	v_mfma_f32_16x16x32_bf16 v[96:99], v[194:197], v[216:219], v[96:99]
	v_mfma_f32_16x16x32_bf16 v[96:99], v[198:201], v[220:223], v[96:99]
	v_mfma_f32_16x16x32_bf16 v[104:107], v[190:193], v[220:223], v[104:107]
	v_mfma_f32_16x16x32_bf16 v[104:107], v[186:189], v[216:219], v[104:107]
	v_mfma_f32_16x16x32_bf16 v[100:103], v[172:175], v[216:219], v[100:103]
	v_mfma_f32_16x16x32_bf16 v[100:103], v[176:179], v[220:223], v[100:103]
	v_mfma_f32_16x16x32_bf16 v[108:111], v[168:171], v[220:223], v[108:111]
	v_mfma_f32_16x16x32_bf16 v[108:111], v[164:167], v[216:219], v[108:111]
	s_setprio 0
	s_setprio 1
	v_mfma_f32_16x16x32_bf16 v[92:95], v[164:167], v[224:227], v[92:95]
	v_mfma_f32_16x16x32_bf16 v[92:95], v[168:171], v[230:233], v[92:95]
	v_mfma_f32_16x16x32_bf16 v[84:87], v[176:179], v[230:233], v[84:87]
	v_mfma_f32_16x16x32_bf16 v[84:87], v[172:175], v[224:227], v[84:87]
	v_mfma_f32_16x16x32_bf16 v[88:91], v[186:189], v[224:227], v[88:91]
	v_mfma_f32_16x16x32_bf16 v[88:91], v[190:193], v[230:233], v[88:91]
	v_mfma_f32_16x16x32_bf16 v[80:83], v[198:201], v[230:233], v[80:83]
	v_mfma_f32_16x16x32_bf16 v[80:83], v[194:197], v[224:227], v[80:83]
	s_setprio 0
	s_setprio 1
	v_mfma_f32_16x16x32_bf16 v[64:67], v[194:197], v[234:237], v[64:67]
	v_mfma_f32_16x16x32_bf16 v[64:67], v[198:201], v[238:241], v[64:67]
	v_mfma_f32_16x16x32_bf16 v[72:75], v[190:193], v[238:241], v[72:75]
	v_mfma_f32_16x16x32_bf16 v[72:75], v[186:189], v[234:237], v[72:75]
	v_mfma_f32_16x16x32_bf16 v[68:71], v[172:175], v[234:237], v[68:71]
	v_mfma_f32_16x16x32_bf16 v[68:71], v[176:179], v[238:241], v[68:71]
	v_mfma_f32_16x16x32_bf16 v[76:79], v[168:171], v[238:241], v[76:79]
	v_mfma_f32_16x16x32_bf16 v[76:79], v[164:167], v[234:237], v[76:79]
	s_setprio 0
	s_barrier
; #define PG8_STAGE(bufoff, gbase, voff) do { _Pragma("unroll") for (int _i = 0; _i < 2; ++_i) \
;         __builtin_amdgcn_global_load_lds((const unsigned*)((const char*)(gbase) + (voff)[_i]), (LAS unsigned*)(lds + (bufoff) + ldsw + _i * 8192), 16, 0, 0); } while (0)
; #define PG8_LDA(dst, b, h) do { _Pragma("unroll") for (int m = 0; m < 4; ++m) _Pragma("unroll") for (int k = 0; k < 2; ++k) dst[m][k] = *(const LAS bf16x8*)(lds + PG8_SA(b, h) + aoff + m * 2048 + k * 1024); } while (0)
; #define PG8_MMA(ai, bj, At, Bt) do { __builtin_amdgcn_s_setprio(1); _Pragma("unroll") for (int m = 0; m < 4; ++m) _Pragma("unroll") for (int n = 0; n < 2; ++n) _Pragma("unroll") for (int k = 0; k < 2; ++k) \
;         acc[ai][bj][m][n] = __builtin_amdgcn_mfma_f32_16x16x32_bf16(Bt[n][k], At[m][k], acc[ai][bj][m][n], 0, 0, 0); __builtin_amdgcn_s_setprio(0); } while (0)
; #define PG8_WAIT_V(n) asm volatile("s_waitcnt vmcnt(" #n ")" ::: "memory")
; #define PG8_WAIT_L(n) asm volatile("s_waitcnt lgkmcnt(" #n ")" ::: "memory")
; #define PG8_BAR __builtin_amdgcn_s_barrier()
; #define PG8_SCHED __builtin_amdgcn_sched_barrier(0)
; template <class Epi>
; __device__ __forceinline__ void gemm_phase(LAS unsigned char* lds, const Gemm g, const StaticOrder& S, const Epi& E) {
;     ...
;             PG8_LDA(At, 1, 1); PG8_STAGE(PG8_SB(1, 0), b3, voffB); PG8_STAGE(PG8_SB(1, 1), b3 + hstepB, voffB); PG8_STAGE(PG8_SA(1, 0), a3, voffA);
;             PG8_WAIT_V(8); PG8_WAIT_L(0); PG8_BAR; PG8_MMA(1, 0, At, B0); PG8_MMA(1, 1, At, B1); PG8_BAR; PG8_SCHED;
;         }
	s_add_i32 s14, s23, s37
	v_lshl_add_u64 v[202:203], v[202:203], 0, s[4:5]
	s_mov_b32 m0, s14
	ds_read_b128 v[208:211], v184 offset:49152
	ds_read_b128 v[212:215], v184 offset:50176
	ds_read_b128 v[216:219], v184 offset:51200
	ds_read_b128 v[220:223], v184 offset:52224
	ds_read_b128 v[224:227], v184 offset:53248
	ds_read_b128 v[230:233], v184 offset:54272
	ds_read_b128 v[234:237], v184 offset:55296
	ds_read_b128 v[238:241], v184 offset:56320
	global_load_lds_dwordx4 v[202:203], off
	s_add_i32 m0, s14, 0x2000
	s_add_u32 s12, s12, 0x80080
	v_lshl_add_u64 v[202:203], v[242:243], 0, s[4:5]
	s_addc_u32 s13, s13, 0
	s_add_i32 s14, s25, s37
	global_load_lds_dwordx4 v[202:203], off
	v_lshl_add_u64 v[202:203], s[12:13], 0, v[132:133]
	s_mov_b32 m0, s14
	s_nop 0
	global_load_lds_dwordx4 v[202:203], off
	v_lshl_add_u64 v[202:203], s[12:13], 0, v[128:129]
	s_add_i32 m0, s14, 0x2000
	s_nop 0
	global_load_lds_dwordx4 v[202:203], off
	v_lshl_add_u64 v[202:203], v[244:245], 0, s[4:5]
	s_mov_b32 m0, s56
	s_nop 0
	global_load_lds_dwordx4 v[202:203], off
	v_lshl_add_u64 v[202:203], v[246:247], 0, s[4:5]
	s_mov_b32 m0, s57
	s_nop 0
	global_load_lds_dwordx4 v[202:203], off
	s_waitcnt vmcnt(8)
	s_waitcnt lgkmcnt(0)
	s_barrier
	s_setprio 1
	s_waitcnt lgkmcnt(0)
	v_mfma_f32_16x16x32_bf16 v[60:63], v[164:167], v[208:211], v[60:63]
	v_mfma_f32_16x16x32_bf16 v[60:63], v[168:171], v[212:215], v[60:63]
	v_mfma_f32_16x16x32_bf16 v[52:55], v[176:179], v[212:215], v[52:55]
	v_mfma_f32_16x16x32_bf16 v[52:55], v[172:175], v[208:211], v[52:55]
	v_mfma_f32_16x16x32_bf16 v[56:59], v[186:189], v[208:211], v[56:59]
	v_mfma_f32_16x16x32_bf16 v[56:59], v[190:193], v[212:215], v[56:59]
	v_mfma_f32_16x16x32_bf16 v[48:51], v[198:201], v[212:215], v[48:51]
	v_mfma_f32_16x16x32_bf16 v[48:51], v[194:197], v[208:211], v[48:51]
	s_setprio 0
	s_setprio 1
	v_mfma_f32_16x16x32_bf16 v[32:35], v[194:197], v[216:219], v[32:35]
	v_mfma_f32_16x16x32_bf16 v[32:35], v[198:201], v[220:223], v[32:35]
	v_mfma_f32_16x16x32_bf16 v[40:43], v[190:193], v[220:223], v[40:43]
	v_mfma_f32_16x16x32_bf16 v[40:43], v[186:189], v[216:219], v[40:43]
	v_mfma_f32_16x16x32_bf16 v[36:39], v[172:175], v[216:219], v[36:39]
	v_mfma_f32_16x16x32_bf16 v[36:39], v[176:179], v[220:223], v[36:39]
	v_mfma_f32_16x16x32_bf16 v[44:47], v[168:171], v[220:223], v[44:47]
	v_mfma_f32_16x16x32_bf16 v[44:47], v[164:167], v[216:219], v[44:47]
	s_setprio 0
	s_setprio 1
	v_mfma_f32_16x16x32_bf16 v[28:31], v[164:167], v[224:227], v[28:31]
	v_mfma_f32_16x16x32_bf16 v[28:31], v[168:171], v[230:233], v[28:31]
	v_mfma_f32_16x16x32_bf16 v[20:23], v[176:179], v[230:233], v[20:23]
	v_mfma_f32_16x16x32_bf16 v[20:23], v[172:175], v[224:227], v[20:23]
	v_mfma_f32_16x16x32_bf16 v[24:27], v[186:189], v[224:227], v[24:27]
	v_mfma_f32_16x16x32_bf16 v[24:27], v[190:193], v[230:233], v[24:27]
	v_mfma_f32_16x16x32_bf16 v[16:19], v[198:201], v[230:233], v[16:19]
	v_mfma_f32_16x16x32_bf16 v[16:19], v[194:197], v[224:227], v[16:19]
	s_setprio 0
	s_setprio 1
	v_mfma_f32_16x16x32_bf16 v[0:3], v[194:197], v[234:237], v[0:3]
	v_mfma_f32_16x16x32_bf16 v[0:3], v[198:201], v[238:241], v[0:3]
	v_mfma_f32_16x16x32_bf16 v[8:11], v[190:193], v[238:241], v[8:11]
	v_mfma_f32_16x16x32_bf16 v[8:11], v[186:189], v[234:237], v[8:11]
	v_mfma_f32_16x16x32_bf16 v[4:7], v[172:175], v[234:237], v[4:7]
	v_mfma_f32_16x16x32_bf16 v[4:7], v[176:179], v[238:241], v[4:7]
	v_mfma_f32_16x16x32_bf16 v[12:15], v[168:171], v[238:241], v[12:15]
	v_mfma_f32_16x16x32_bf16 v[12:15], v[164:167], v[234:237], v[12:15]
	s_setprio 0
	s_barrier
	s_add_u32 s10, s10, 0x100
	s_addc_u32 s11, s11, 0
	s_add_u32 s20, s20, 0x100
	s_addc_u32 s21, s21, 0
	s_cmp_ge_i32 s22, s55
	s_mov_b32 s12, s22
	s_cbranch_scc0 .LBB0_1131

; #define PG8_STAGE(bufoff, gbase, voff) do { _Pragma("unroll") for (int _i = 0; _i < 2; ++_i) \
;         __builtin_amdgcn_global_load_lds((const unsigned*)((const char*)(gbase) + (voff)[_i]), (LAS unsigned*)(lds + (bufoff) + ldsw + _i * 8192), 16, 0, 0); } while (0)
; #define PG8_LDA(dst, b, h) do { _Pragma("unroll") for (int m = 0; m < 4; ++m) _Pragma("unroll") for (int k = 0; k < 2; ++k) dst[m][k] = *(const LAS bf16x8*)(lds + PG8_SA(b, h) + aoff + m * 2048 + k * 1024); } while (0)
; #define PG8_LDB(dst, b, h) do { _Pragma("unroll") for (int n = 0; n < 2; ++n) _Pragma("unroll") for (int k = 0; k < 2; ++k) dst[n][k] = *(const LAS bf16x8*)(lds + PG8_SB(b, h) + boff + n * 2048 + k * 1024); } while (0)
; #define PG8_MMA(ai, bj, At, Bt) do { __builtin_amdgcn_s_setprio(1); _Pragma("unroll") for (int m = 0; m < 4; ++m) _Pragma("unroll") for (int n = 0; n < 2; ++n) _Pragma("unroll") for (int k = 0; k < 2; ++k) \
;         acc[ai][bj][m][n] = __builtin_amdgcn_mfma_f32_16x16x32_bf16(Bt[n][k], At[m][k], acc[ai][bj][m][n], 0, 0, 0); __builtin_amdgcn_s_setprio(0); } while (0)
; #define PG8_WAIT_V(n) asm volatile("s_waitcnt vmcnt(" #n ")" ::: "memory")
; #define PG8_WAIT_L(n) asm volatile("s_waitcnt lgkmcnt(" #n ")" ::: "memory")
; #define PG8_BAR __builtin_amdgcn_s_barrier()
; #define PG8_SCHED __builtin_amdgcn_sched_barrier(0)
; template <class Epi>
; __device__ __forceinline__ void gemm_phase(LAS unsigned char* lds, const Gemm g, const StaticOrder& S, const Epi& E) {
;     ...
;         for (int t = 0; t < nt; t += 2) {
;             const bool last = (t == nt - 2);
;             const char* a1 = cA + (size_t)(t + 1) * kstep;
;             const char* a2 = last ? nA : cA + (size_t)(t + 2) * kstep; const char* b2 = last ? nB : cB + (size_t)(t + 2) * kstep;
;             const char* a3 = a2 + kstep; const char* b3 = b2 + kstep;
;             PG8_LDB(B0, 0, 0); PG8_LDB(B1, 0, 1); PG8_SCHED; PG8_LDA(At, 0, 0); PG8_STAGE(PG8_SA(1, 1), a1 + hstepA, voffA);
;             PG8_WAIT_V(8); PG8_WAIT_L(0); PG8_BAR; PG8_MMA(0, 0, At, B0); PG8_MMA(0, 1, At, B1); PG8_BAR; PG8_SCHED;
;             PG8_LDA(At, 0, 1); PG8_STAGE(PG8_SB(0, 0), b2, voffB); PG8_STAGE(PG8_SB(0, 1), b2 + hstepB, voffB); PG8_STAGE(PG8_SA(0, 0), a2, voffA);
;             PG8_WAIT_V(8); PG8_WAIT_L(0); PG8_BAR; PG8_MMA(1, 0, At, B0); PG8_MMA(1, 1, At, B1); PG8_BAR; PG8_SCHED;
.LBB0_1161:
	ds_read_b128 v[152:155], v149
	ds_read_b128 v[156:159], v149 offset:1024
	ds_read_b128 v[160:163], v149 offset:2048
	ds_read_b128 v[164:167], v149 offset:3072
	ds_read_b128 v[168:171], v150
	ds_read_b128 v[172:175], v150 offset:1024
	ds_read_b128 v[176:179], v150 offset:2048
	ds_read_b128 v[180:183], v150 offset:3072
	s_add_i32 s83, s46, 2
	s_add_u32 s47, s44, 0xffff0080
	s_addc_u32 s48, s45, -1
	s_cmp_eq_u32 s65, s46
	s_cselect_b32 s46, s78, s79
	s_cselect_b32 s49, s35, s48
	s_cselect_b32 s48, s37, s47
	s_cselect_b32 s47, s39, s82
	v_lshl_add_u64 v[220:221], s[44:45], 0, v[140:141]
	s_add_i32 m0, s56, 0xc000
	ds_read_b128 v[184:187], v151
	ds_read_b128 v[188:191], v151 offset:1024
	ds_read_b128 v[192:195], v151 offset:2048
	ds_read_b128 v[196:199], v151 offset:3072
	ds_read_b128 v[200:203], v151 offset:4096
	ds_read_b128 v[208:211], v151 offset:5120
	ds_read_b128 v[212:215], v151 offset:6144
	ds_read_b128 v[216:219], v151 offset:7168
	global_load_lds_dwordx4 v[220:221], off
	v_lshl_add_u64 v[220:221], s[44:45], 0, v[142:143]
	s_add_i32 m0, s56, 0xe000
	s_nop 0
	global_load_lds_dwordx4 v[220:221], off
	s_waitcnt vmcnt(8)
	s_waitcnt lgkmcnt(0)
	s_barrier
	s_setprio 1
	s_waitcnt lgkmcnt(0)
	v_mfma_f32_16x16x32_bf16 v[120:123], v[152:155], v[184:187], v[120:123]
	v_mfma_f32_16x16x32_bf16 v[120:123], v[156:159], v[188:191], v[120:123]
	v_mfma_f32_16x16x32_bf16 v[124:127], v[164:167], v[188:191], v[124:127]
	v_mfma_f32_16x16x32_bf16 v[124:127], v[160:163], v[184:187], v[124:127]
	v_mfma_f32_16x16x32_bf16 v[116:119], v[168:171], v[184:187], v[116:119]
	v_mfma_f32_16x16x32_bf16 v[116:119], v[172:175], v[188:191], v[116:119]
	v_mfma_f32_16x16x32_bf16 v[112:115], v[180:183], v[188:191], v[112:115]
	v_mfma_f32_16x16x32_bf16 v[112:115], v[176:179], v[184:187], v[112:115]
	s_setprio 0
	s_setprio 1
	v_mfma_f32_16x16x32_bf16 v[96:99], v[176:179], v[192:195], v[96:99]
	v_mfma_f32_16x16x32_bf16 v[96:99], v[180:183], v[196:199], v[96:99]
	v_mfma_f32_16x16x32_bf16 v[100:103], v[172:175], v[196:199], v[100:103]
	v_mfma_f32_16x16x32_bf16 v[100:103], v[168:171], v[192:195], v[100:103]
	v_mfma_f32_16x16x32_bf16 v[104:107], v[160:163], v[192:195], v[104:107]
	v_mfma_f32_16x16x32_bf16 v[104:107], v[164:167], v[196:199], v[104:107]
	v_mfma_f32_16x16x32_bf16 v[108:111], v[156:159], v[196:199], v[108:111]
	v_mfma_f32_16x16x32_bf16 v[108:111], v[152:155], v[192:195], v[108:111]
	s_setprio 0
	s_setprio 1
	v_mfma_f32_16x16x32_bf16 v[92:95], v[152:155], v[200:203], v[92:95]
	v_mfma_f32_16x16x32_bf16 v[92:95], v[156:159], v[208:211], v[92:95]
	v_mfma_f32_16x16x32_bf16 v[88:91], v[164:167], v[208:211], v[88:91]
	v_mfma_f32_16x16x32_bf16 v[88:91], v[160:163], v[200:203], v[88:91]
	v_mfma_f32_16x16x32_bf16 v[84:87], v[168:171], v[200:203], v[84:87]
	v_mfma_f32_16x16x32_bf16 v[84:87], v[172:175], v[208:211], v[84:87]
	v_mfma_f32_16x16x32_bf16 v[80:83], v[180:183], v[208:211], v[80:83]
	v_mfma_f32_16x16x32_bf16 v[80:83], v[176:179], v[200:203], v[80:83]
	s_setprio 0
	s_setprio 1
	v_mfma_f32_16x16x32_bf16 v[64:67], v[176:179], v[212:215], v[64:67]
	v_mfma_f32_16x16x32_bf16 v[64:67], v[180:183], v[216:219], v[64:67]
	v_mfma_f32_16x16x32_bf16 v[68:71], v[172:175], v[216:219], v[68:71]
	v_mfma_f32_16x16x32_bf16 v[68:71], v[168:171], v[212:215], v[68:71]
	v_mfma_f32_16x16x32_bf16 v[72:75], v[160:163], v[212:215], v[72:75]
	v_mfma_f32_16x16x32_bf16 v[72:75], v[164:167], v[216:219], v[72:75]
	v_mfma_f32_16x16x32_bf16 v[76:79], v[156:159], v[216:219], v[76:79]
	v_mfma_f32_16x16x32_bf16 v[76:79], v[152:155], v[212:215], v[76:79]
	s_setprio 0
	s_barrier
	s_add_i32 s84, s67, s51
	v_lshl_add_u64 v[220:221], s[46:47], 0, v[130:131]
	s_mov_b32 m0, s84
	ds_read_b128 v[184:187], v151 offset:16384
	ds_read_b128 v[188:191], v151 offset:17408
	ds_read_b128 v[192:195], v151 offset:18432
	ds_read_b128 v[196:199], v151 offset:19456
	ds_read_b128 v[200:203], v151 offset:20480
	ds_read_b128 v[208:211], v151 offset:21504
	ds_read_b128 v[212:215], v151 offset:22528
	ds_read_b128 v[216:219], v151 offset:23552
	global_load_lds_dwordx4 v[220:221], off
	s_add_i32 m0, s84, 0x2000
	s_add_u32 s84, s46, 0x10000
	v_lshl_add_u64 v[222:223], s[46:47], 0, v[134:135]
	s_addc_u32 s85, s47, 0
	s_add_i32 s86, s68, s51
	global_load_lds_dwordx4 v[222:223], off
	v_lshl_add_u64 v[224:225], s[84:85], 0, v[130:131]
	s_mov_b32 m0, s86
	v_lshl_add_u64 v[226:227], s[48:49], 0, v[132:133]
	global_load_lds_dwordx4 v[224:225], off
	v_lshl_add_u64 v[224:225], s[84:85], 0, v[134:135]
	s_add_i32 m0, s86, 0x2000
	s_nop 0
	global_load_lds_dwordx4 v[224:225], off
	v_lshl_add_u64 v[224:225], s[48:49], 0, v[128:129]
	s_mov_b32 m0, s56
	s_nop 0
	global_load_lds_dwordx4 v[224:225], off
	s_mov_b32 m0, s57
	s_nop 0
	global_load_lds_dwordx4 v[226:227], off
	s_waitcnt vmcnt(8)
	s_waitcnt lgkmcnt(0)
	s_barrier
; #define PG8_STAGE(bufoff, gbase, voff) do { _Pragma("unroll") for (int _i = 0; _i < 2; ++_i) \
;         __builtin_amdgcn_global_load_lds((const unsigned*)((const char*)(gbase) + (voff)[_i]), (LAS unsigned*)(lds + (bufoff) + ldsw + _i * 8192), 16, 0, 0); } while (0)
; #define PG8_LDA(dst, b, h) do { _Pragma("unroll") for (int m = 0; m < 4; ++m) _Pragma("unroll") for (int k = 0; k < 2; ++k) dst[m][k] = *(const LAS bf16x8*)(lds + PG8_SA(b, h) + aoff + m * 2048 + k * 1024); } while (0)
; #define PG8_LDB(dst, b, h) do { _Pragma("unroll") for (int n = 0; n < 2; ++n) _Pragma("unroll") for (int k = 0; k < 2; ++k) dst[n][k] = *(const LAS bf16x8*)(lds + PG8_SB(b, h) + boff + n * 2048 + k * 1024); } while (0)
; #define PG8_MMA(ai, bj, At, Bt) do { __builtin_amdgcn_s_setprio(1); _Pragma("unroll") for (int m = 0; m < 4; ++m) _Pragma("unroll") for (int n = 0; n < 2; ++n) _Pragma("unroll") for (int k = 0; k < 2; ++k) \
;         acc[ai][bj][m][n] = __builtin_amdgcn_mfma_f32_16x16x32_bf16(Bt[n][k], At[m][k], acc[ai][bj][m][n], 0, 0, 0); __builtin_amdgcn_s_setprio(0); } while (0)
; #define PG8_WAIT_V(n) asm volatile("s_waitcnt vmcnt(" #n ")" ::: "memory")
; #define PG8_WAIT_L(n) asm volatile("s_waitcnt lgkmcnt(" #n ")" ::: "memory")
; #define PG8_BAR __builtin_amdgcn_s_barrier()
; #define PG8_SCHED __builtin_amdgcn_sched_barrier(0)
; template <class Epi>
; __device__ __forceinline__ void gemm_phase(LAS unsigned char* lds, const Gemm g, const StaticOrder& S, const Epi& E) {
;     ...
;             PG8_WAIT_V(8); PG8_WAIT_L(0); PG8_BAR; PG8_MMA(1, 0, At, B0); PG8_MMA(1, 1, At, B1); PG8_BAR; PG8_SCHED;
;             PG8_LDB(B0, 1, 0); PG8_LDB(B1, 1, 1); PG8_SCHED; PG8_LDA(At, 1, 0); PG8_STAGE(PG8_SA(0, 1), a2 + hstepA, voffA);
;             PG8_WAIT_V(8); PG8_WAIT_L(0); PG8_BAR; PG8_MMA(0, 0, At, B0); PG8_MMA(0, 1, At, B1); PG8_BAR; PG8_SCHED;
	s_setprio 1
	s_waitcnt lgkmcnt(0)
	v_mfma_f32_16x16x32_bf16 v[60:63], v[152:155], v[184:187], v[60:63]
	v_mfma_f32_16x16x32_bf16 v[60:63], v[156:159], v[188:191], v[60:63]
	v_mfma_f32_16x16x32_bf16 v[56:59], v[164:167], v[188:191], v[56:59]
	v_mfma_f32_16x16x32_bf16 v[56:59], v[160:163], v[184:187], v[56:59]
	v_mfma_f32_16x16x32_bf16 v[52:55], v[168:171], v[184:187], v[52:55]
	v_mfma_f32_16x16x32_bf16 v[52:55], v[172:175], v[188:191], v[52:55]
	v_mfma_f32_16x16x32_bf16 v[48:51], v[180:183], v[188:191], v[48:51]
	v_mfma_f32_16x16x32_bf16 v[48:51], v[176:179], v[184:187], v[48:51]
	s_setprio 0
	s_setprio 1
	v_mfma_f32_16x16x32_bf16 v[32:35], v[176:179], v[192:195], v[32:35]
	v_mfma_f32_16x16x32_bf16 v[32:35], v[180:183], v[196:199], v[32:35]
	v_mfma_f32_16x16x32_bf16 v[36:39], v[172:175], v[196:199], v[36:39]
	v_mfma_f32_16x16x32_bf16 v[36:39], v[168:171], v[192:195], v[36:39]
	v_mfma_f32_16x16x32_bf16 v[40:43], v[160:163], v[192:195], v[40:43]
	v_mfma_f32_16x16x32_bf16 v[40:43], v[164:167], v[196:199], v[40:43]
	v_mfma_f32_16x16x32_bf16 v[44:47], v[156:159], v[196:199], v[44:47]
	v_mfma_f32_16x16x32_bf16 v[44:47], v[152:155], v[192:195], v[44:47]
	s_setprio 0
	s_setprio 1
	v_mfma_f32_16x16x32_bf16 v[28:31], v[152:155], v[200:203], v[28:31]
	v_mfma_f32_16x16x32_bf16 v[28:31], v[156:159], v[208:211], v[28:31]
	v_mfma_f32_16x16x32_bf16 v[24:27], v[164:167], v[208:211], v[24:27]
	v_mfma_f32_16x16x32_bf16 v[24:27], v[160:163], v[200:203], v[24:27]
	v_mfma_f32_16x16x32_bf16 v[20:23], v[168:171], v[200:203], v[20:23]
	v_mfma_f32_16x16x32_bf16 v[20:23], v[172:175], v[208:211], v[20:23]
	v_mfma_f32_16x16x32_bf16 v[16:19], v[180:183], v[208:211], v[16:19]
	v_mfma_f32_16x16x32_bf16 v[16:19], v[176:179], v[200:203], v[16:19]
	s_setprio 0
	s_setprio 1
	v_mfma_f32_16x16x32_bf16 v[0:3], v[176:179], v[212:215], v[0:3]
	v_mfma_f32_16x16x32_bf16 v[0:3], v[180:183], v[216:219], v[0:3]
	v_mfma_f32_16x16x32_bf16 v[4:7], v[172:175], v[216:219], v[4:7]
	v_mfma_f32_16x16x32_bf16 v[4:7], v[168:171], v[212:215], v[4:7]
	v_mfma_f32_16x16x32_bf16 v[8:11], v[160:163], v[212:215], v[8:11]
	v_mfma_f32_16x16x32_bf16 v[8:11], v[164:167], v[216:219], v[8:11]
	v_mfma_f32_16x16x32_bf16 v[12:15], v[156:159], v[216:219], v[12:15]
	v_mfma_f32_16x16x32_bf16 v[12:15], v[152:155], v[212:215], v[12:15]
	s_setprio 0
	s_barrier
	s_add_i32 s84, 0, 0x18000
	s_add_i32 s85, 0, 0x1c000
	v_add_u32_e32 v164, s84, v148
	v_add_u32_e32 v180, s85, v148
	ds_read_b128 v[152:155], v164
	ds_read_b128 v[156:159], v164 offset:1024
	ds_read_b128 v[160:163], v164 offset:2048
	ds_read_b128 v[164:167], v164 offset:3072
	ds_read_b128 v[168:171], v180
	ds_read_b128 v[172:175], v180 offset:1024
	ds_read_b128 v[176:179], v180 offset:2048
	ds_read_b128 v[180:183], v180 offset:3072
	s_add_u32 s48, s48, 0x10000
	s_addc_u32 s49, s49, 0
	s_mov_b32 m0, s58
	v_lshl_add_u64 v[230:231], s[48:49], 0, v[128:129]
	ds_read_b128 v[184:187], v151 offset:32768
	ds_read_b128 v[188:191], v151 offset:33792
	ds_read_b128 v[192:195], v151 offset:34816
	ds_read_b128 v[196:199], v151 offset:35840
	ds_read_b128 v[200:203], v151 offset:36864
	ds_read_b128 v[208:211], v151 offset:37888
	ds_read_b128 v[212:215], v151 offset:38912
	ds_read_b128 v[216:219], v151 offset:39936
	global_load_lds_dwordx4 v[230:231], off
	v_lshl_add_u64 v[230:231], s[48:49], 0, v[132:133]
	s_mov_b32 m0, s59
	s_nop 0
	global_load_lds_dwordx4 v[230:231], off
	s_waitcnt vmcnt(8)
	s_waitcnt lgkmcnt(0)
	s_barrier
	s_setprio 1
	s_waitcnt lgkmcnt(0)
	v_mfma_f32_16x16x32_bf16 v[120:123], v[152:155], v[184:187], v[120:123]
	v_mfma_f32_16x16x32_bf16 v[120:123], v[156:159], v[188:191], v[120:123]
	v_mfma_f32_16x16x32_bf16 v[124:127], v[164:167], v[188:191], v[124:127]
	v_mfma_f32_16x16x32_bf16 v[124:127], v[160:163], v[184:187], v[124:127]
	v_mfma_f32_16x16x32_bf16 v[116:119], v[168:171], v[184:187], v[116:119]
	v_mfma_f32_16x16x32_bf16 v[116:119], v[172:175], v[188:191], v[116:119]
	v_mfma_f32_16x16x32_bf16 v[112:115], v[180:183], v[188:191], v[112:115]
	v_mfma_f32_16x16x32_bf16 v[112:115], v[176:179], v[184:187], v[112:115]
	s_setprio 0
	s_setprio 1
	v_mfma_f32_16x16x32_bf16 v[96:99], v[176:179], v[192:195], v[96:99]
	v_mfma_f32_16x16x32_bf16 v[96:99], v[180:183], v[196:199], v[96:99]
	v_mfma_f32_16x16x32_bf16 v[100:103], v[172:175], v[196:199], v[100:103]
	v_mfma_f32_16x16x32_bf16 v[100:103], v[168:171], v[192:195], v[100:103]
	v_mfma_f32_16x16x32_bf16 v[104:107], v[160:163], v[192:195], v[104:107]
	v_mfma_f32_16x16x32_bf16 v[104:107], v[164:167], v[196:199], v[104:107]
	v_mfma_f32_16x16x32_bf16 v[108:111], v[156:159], v[196:199], v[108:111]
	v_mfma_f32_16x16x32_bf16 v[108:111], v[152:155], v[192:195], v[108:111]
	s_setprio 0
	s_setprio 1
	v_mfma_f32_16x16x32_bf16 v[92:95], v[152:155], v[200:203], v[92:95]
	v_mfma_f32_16x16x32_bf16 v[92:95], v[156:159], v[208:211], v[92:95]
	v_mfma_f32_16x16x32_bf16 v[88:91], v[164:167], v[208:211], v[88:91]
	v_mfma_f32_16x16x32_bf16 v[88:91], v[160:163], v[200:203], v[88:91]
	v_mfma_f32_16x16x32_bf16 v[84:87], v[168:171], v[200:203], v[84:87]
	v_mfma_f32_16x16x32_bf16 v[84:87], v[172:175], v[208:211], v[84:87]
	v_mfma_f32_16x16x32_bf16 v[80:83], v[180:183], v[208:211], v[80:83]
	v_mfma_f32_16x16x32_bf16 v[80:83], v[176:179], v[200:203], v[80:83]
	s_setprio 0
	s_setprio 1
	v_mfma_f32_16x16x32_bf16 v[64:67], v[176:179], v[212:215], v[64:67]
	v_mfma_f32_16x16x32_bf16 v[64:67], v[180:183], v[216:219], v[64:67]
	v_mfma_f32_16x16x32_bf16 v[68:71], v[172:175], v[216:219], v[68:71]
	v_mfma_f32_16x16x32_bf16 v[68:71], v[168:171], v[212:215], v[68:71]
	v_mfma_f32_16x16x32_bf16 v[72:75], v[160:163], v[212:215], v[72:75]
	v_mfma_f32_16x16x32_bf16 v[72:75], v[164:167], v[216:219], v[72:75]
	v_mfma_f32_16x16x32_bf16 v[76:79], v[156:159], v[216:219], v[76:79]
	v_mfma_f32_16x16x32_bf16 v[76:79], v[152:155], v[212:215], v[76:79]
	s_setprio 0
	s_barrier
; #define PG8_STAGE(bufoff, gbase, voff) do { _Pragma("unroll") for (int _i = 0; _i < 2; ++_i) \
;         __builtin_amdgcn_global_load_lds((const unsigned*)((const char*)(gbase) + (voff)[_i]), (LAS unsigned*)(lds + (bufoff) + ldsw + _i * 8192), 16, 0, 0); } while (0)
; #define PG8_LDA(dst, b, h) do { _Pragma("unroll") for (int m = 0; m < 4; ++m) _Pragma("unroll") for (int k = 0; k < 2; ++k) dst[m][k] = *(const LAS bf16x8*)(lds + PG8_SA(b, h) + aoff + m * 2048 + k * 1024); } while (0)
; #define PG8_MMA(ai, bj, At, Bt) do { __builtin_amdgcn_s_setprio(1); _Pragma("unroll") for (int m = 0; m < 4; ++m) _Pragma("unroll") for (int n = 0; n < 2; ++n) _Pragma("unroll") for (int k = 0; k < 2; ++k) \
;         acc[ai][bj][m][n] = __builtin_amdgcn_mfma_f32_16x16x32_bf16(Bt[n][k], At[m][k], acc[ai][bj][m][n], 0, 0, 0); __builtin_amdgcn_s_setprio(0); } while (0)
; #define PG8_WAIT_V(n) asm volatile("s_waitcnt vmcnt(" #n ")" ::: "memory")
; #define PG8_WAIT_L(n) asm volatile("s_waitcnt lgkmcnt(" #n ")" ::: "memory")
; #define PG8_BAR __builtin_amdgcn_s_barrier()
; #define PG8_SCHED __builtin_amdgcn_sched_barrier(0)
; template <class Epi>
; __device__ __forceinline__ void gemm_phase(LAS unsigned char* lds, const Gemm g, const StaticOrder& S, const Epi& E) {
;     ...
;             PG8_LDA(At, 1, 1); PG8_STAGE(PG8_SB(1, 0), b3, voffB); PG8_STAGE(PG8_SB(1, 1), b3 + hstepB, voffB); PG8_STAGE(PG8_SA(1, 0), a3, voffA);
;             PG8_WAIT_V(8); PG8_WAIT_L(0); PG8_BAR; PG8_MMA(1, 0, At, B0); PG8_MMA(1, 1, At, B1); PG8_BAR; PG8_SCHED;
;         }
	s_add_i32 s48, s84, s51
	v_lshl_add_u64 v[220:221], v[220:221], 0, s[12:13]
	s_mov_b32 m0, s48
	ds_read_b128 v[184:187], v151 offset:49152
	ds_read_b128 v[188:191], v151 offset:50176
	ds_read_b128 v[192:195], v151 offset:51200
	ds_read_b128 v[196:199], v151 offset:52224
	ds_read_b128 v[200:203], v151 offset:53248
	ds_read_b128 v[208:211], v151 offset:54272
	ds_read_b128 v[212:215], v151 offset:55296
	ds_read_b128 v[216:219], v151 offset:56320
	global_load_lds_dwordx4 v[220:221], off
	s_add_i32 m0, s48, 0x2000
	s_add_u32 s46, s46, 0x10080
	v_lshl_add_u64 v[220:221], v[222:223], 0, s[12:13]
	s_addc_u32 s47, s47, 0
	s_add_i32 s48, s85, s51
	global_load_lds_dwordx4 v[220:221], off
	v_lshl_add_u64 v[220:221], s[46:47], 0, v[130:131]
	s_mov_b32 m0, s48
	s_nop 0
	global_load_lds_dwordx4 v[220:221], off
	v_lshl_add_u64 v[220:221], s[46:47], 0, v[134:135]
	s_add_i32 m0, s48, 0x2000
	s_nop 0
	global_load_lds_dwordx4 v[220:221], off
	v_lshl_add_u64 v[220:221], v[224:225], 0, s[12:13]
	s_mov_b32 m0, s63
	s_nop 0
	global_load_lds_dwordx4 v[220:221], off
	v_lshl_add_u64 v[220:221], v[226:227], 0, s[12:13]
	s_mov_b32 m0, s64
	s_nop 0
	global_load_lds_dwordx4 v[220:221], off
	s_waitcnt vmcnt(8)
	s_waitcnt lgkmcnt(0)
	s_barrier
	s_setprio 1
	s_waitcnt lgkmcnt(0)
	v_mfma_f32_16x16x32_bf16 v[60:63], v[152:155], v[184:187], v[60:63]
	v_mfma_f32_16x16x32_bf16 v[60:63], v[156:159], v[188:191], v[60:63]
	v_mfma_f32_16x16x32_bf16 v[56:59], v[164:167], v[188:191], v[56:59]
	v_mfma_f32_16x16x32_bf16 v[56:59], v[160:163], v[184:187], v[56:59]
	v_mfma_f32_16x16x32_bf16 v[52:55], v[168:171], v[184:187], v[52:55]
	v_mfma_f32_16x16x32_bf16 v[52:55], v[172:175], v[188:191], v[52:55]
	v_mfma_f32_16x16x32_bf16 v[48:51], v[180:183], v[188:191], v[48:51]
	v_mfma_f32_16x16x32_bf16 v[48:51], v[176:179], v[184:187], v[48:51]
	s_setprio 0
	s_setprio 1
	v_mfma_f32_16x16x32_bf16 v[32:35], v[176:179], v[192:195], v[32:35]
	v_mfma_f32_16x16x32_bf16 v[32:35], v[180:183], v[196:199], v[32:35]
	v_mfma_f32_16x16x32_bf16 v[36:39], v[172:175], v[196:199], v[36:39]
	v_mfma_f32_16x16x32_bf16 v[36:39], v[168:171], v[192:195], v[36:39]
	v_mfma_f32_16x16x32_bf16 v[40:43], v[160:163], v[192:195], v[40:43]
	v_mfma_f32_16x16x32_bf16 v[40:43], v[164:167], v[196:199], v[40:43]
	v_mfma_f32_16x16x32_bf16 v[44:47], v[156:159], v[196:199], v[44:47]
	v_mfma_f32_16x16x32_bf16 v[44:47], v[152:155], v[192:195], v[44:47]
	s_setprio 0
	s_setprio 1
	v_mfma_f32_16x16x32_bf16 v[28:31], v[152:155], v[200:203], v[28:31]
	v_mfma_f32_16x16x32_bf16 v[28:31], v[156:159], v[208:211], v[28:31]
	v_mfma_f32_16x16x32_bf16 v[24:27], v[164:167], v[208:211], v[24:27]
	v_mfma_f32_16x16x32_bf16 v[24:27], v[160:163], v[200:203], v[24:27]
	v_mfma_f32_16x16x32_bf16 v[20:23], v[168:171], v[200:203], v[20:23]
	v_mfma_f32_16x16x32_bf16 v[20:23], v[172:175], v[208:211], v[20:23]
	v_mfma_f32_16x16x32_bf16 v[16:19], v[180:183], v[208:211], v[16:19]
	v_mfma_f32_16x16x32_bf16 v[16:19], v[176:179], v[200:203], v[16:19]
	s_setprio 0
	s_setprio 1
	v_mfma_f32_16x16x32_bf16 v[0:3], v[176:179], v[212:215], v[0:3]
	v_mfma_f32_16x16x32_bf16 v[0:3], v[180:183], v[216:219], v[0:3]
	v_mfma_f32_16x16x32_bf16 v[4:7], v[172:175], v[216:219], v[4:7]
	v_mfma_f32_16x16x32_bf16 v[4:7], v[168:171], v[212:215], v[4:7]
	v_mfma_f32_16x16x32_bf16 v[8:11], v[160:163], v[212:215], v[8:11]
	v_mfma_f32_16x16x32_bf16 v[8:11], v[164:167], v[216:219], v[8:11]
	v_mfma_f32_16x16x32_bf16 v[12:15], v[156:159], v[216:219], v[12:15]
	v_mfma_f32_16x16x32_bf16 v[12:15], v[152:155], v[212:215], v[12:15]
	s_setprio 0
	s_barrier
	s_add_u32 s44, s44, 0x100
	s_addc_u32 s45, s45, 0
	s_add_u32 s79, s79, 0x100
	s_addc_u32 s82, s82, 0
	s_cmp_ge_i32 s83, s61
	s_mov_b32 s46, s83
	s_cbranch_scc0 .LBB0_1161

; #define PG8_STAGE(bufoff, gbase, voff) do { _Pragma("unroll") for (int _i = 0; _i < 2; ++_i) \
;         __builtin_amdgcn_global_load_lds((const unsigned*)((const char*)(gbase) + (voff)[_i]), (LAS unsigned*)(lds + (bufoff) + ldsw + _i * 8192), 16, 0, 0); } while (0)
; #define PG8_LDA(dst, b, h) do { _Pragma("unroll") for (int m = 0; m < 4; ++m) _Pragma("unroll") for (int k = 0; k < 2; ++k) dst[m][k] = *(const LAS bf16x8*)(lds + PG8_SA(b, h) + aoff + m * 2048 + k * 1024); } while (0)
; #define PG8_LDB(dst, b, h) do { _Pragma("unroll") for (int n = 0; n < 2; ++n) _Pragma("unroll") for (int k = 0; k < 2; ++k) dst[n][k] = *(const LAS bf16x8*)(lds + PG8_SB(b, h) + boff + n * 2048 + k * 1024); } while (0)
; #define PG8_MMA(ai, bj, At, Bt) do { __builtin_amdgcn_s_setprio(1); _Pragma("unroll") for (int m = 0; m < 4; ++m) _Pragma("unroll") for (int n = 0; n < 2; ++n) _Pragma("unroll") for (int k = 0; k < 2; ++k) \
;         acc[ai][bj][m][n] = __builtin_amdgcn_mfma_f32_16x16x32_bf16(Bt[n][k], At[m][k], acc[ai][bj][m][n], 0, 0, 0); __builtin_amdgcn_s_setprio(0); } while (0)
; #define PG8_WAIT_V(n) asm volatile("s_waitcnt vmcnt(" #n ")" ::: "memory")
; #define PG8_WAIT_L(n) asm volatile("s_waitcnt lgkmcnt(" #n ")" ::: "memory")
; #define PG8_BAR __builtin_amdgcn_s_barrier()
; #define PG8_SCHED __builtin_amdgcn_sched_barrier(0)
; template <class Epi>
; __device__ __forceinline__ void gemm_phase(LAS unsigned char* lds, const Gemm g, const StaticOrder& S, const Epi& E) {
;     ...
;         for (int t = 0; t < nt; t += 2) {
;             const bool last = (t == nt - 2);
;             const char* a1 = cA + (size_t)(t + 1) * kstep;
;             const char* a2 = last ? nA : cA + (size_t)(t + 2) * kstep; const char* b2 = last ? nB : cB + (size_t)(t + 2) * kstep;
;             const char* a3 = a2 + kstep; const char* b3 = b2 + kstep;
;             PG8_LDB(B0, 0, 0); PG8_LDB(B1, 0, 1); PG8_SCHED; PG8_LDA(At, 0, 0); PG8_STAGE(PG8_SA(1, 1), a1 + hstepA, voffA);
;             PG8_WAIT_V(8); PG8_WAIT_L(0); PG8_BAR; PG8_MMA(0, 0, At, B0); PG8_MMA(0, 1, At, B1); PG8_BAR; PG8_SCHED;
;             PG8_LDA(At, 0, 1); PG8_STAGE(PG8_SB(0, 0), b2, voffB); PG8_STAGE(PG8_SB(0, 1), b2 + hstepB, voffB); PG8_STAGE(PG8_SA(0, 0), a2, voffA);
;             PG8_WAIT_V(8); PG8_WAIT_L(0); PG8_BAR; PG8_MMA(1, 0, At, B0); PG8_MMA(1, 1, At, B1); PG8_BAR; PG8_SCHED;
.LBB0_1244:
	ds_read_b128 v[150:153], v187
	ds_read_b128 v[154:157], v187 offset:1024
	ds_read_b128 v[158:161], v187 offset:2048
	ds_read_b128 v[162:165], v187 offset:3072
	ds_read_b128 v[166:169], v188
	ds_read_b128 v[170:173], v188 offset:1024
	ds_read_b128 v[174:177], v188 offset:2048
	ds_read_b128 v[178:181], v188 offset:3072
	s_add_i32 s84, s52, 2
	s_add_u32 s12, s4, 0x100
	s_addc_u32 s13, s5, 0
	s_cmp_eq_u32 s67, s52
	s_cselect_b32 s52, s50, s1
	s_cselect_b32 s55, s49, s13
	s_cselect_b32 s54, s48, s12
	s_cselect_b32 s53, s51, s77
	v_lshl_add_u64 v[224:225], s[4:5], 0, v[142:143]
	s_add_i32 m0, s59, 0xc000
	ds_read_b128 v[182:185], v189
	ds_read_b128 v[192:195], v189 offset:1024
	ds_read_b128 v[196:199], v189 offset:2048
	ds_read_b128 v[200:203], v189 offset:3072
	ds_read_b128 v[208:211], v189 offset:4096
	ds_read_b128 v[212:215], v189 offset:5120
	ds_read_b128 v[216:219], v189 offset:6144
	ds_read_b128 v[220:223], v189 offset:7168
	global_load_lds_dwordx4 v[224:225], off
	v_lshl_add_u64 v[224:225], s[4:5], 0, v[144:145]
	s_add_i32 m0, s59, 0xe000
	s_nop 0
	global_load_lds_dwordx4 v[224:225], off
	s_waitcnt vmcnt(8)
	s_waitcnt lgkmcnt(0)
	s_barrier
	s_setprio 1
	s_waitcnt lgkmcnt(0)
	v_mfma_f32_16x16x32_bf16 v[124:127], v[150:153], v[182:185], v[124:127]
	v_mfma_f32_16x16x32_bf16 v[124:127], v[154:157], v[192:195], v[124:127]
	v_mfma_f32_16x16x32_bf16 v[120:123], v[162:165], v[192:195], v[120:123]
	v_mfma_f32_16x16x32_bf16 v[120:123], v[158:161], v[182:185], v[120:123]
	v_mfma_f32_16x16x32_bf16 v[108:111], v[166:169], v[182:185], v[108:111]
	v_mfma_f32_16x16x32_bf16 v[108:111], v[170:173], v[192:195], v[108:111]
	v_mfma_f32_16x16x32_bf16 v[100:103], v[178:181], v[192:195], v[100:103]
	v_mfma_f32_16x16x32_bf16 v[100:103], v[174:177], v[182:185], v[100:103]
	s_setprio 0
	s_setprio 1
	v_mfma_f32_16x16x32_bf16 v[84:87], v[174:177], v[196:199], v[84:87]
	v_mfma_f32_16x16x32_bf16 v[84:87], v[178:181], v[200:203], v[84:87]
	v_mfma_f32_16x16x32_bf16 v[92:95], v[170:173], v[200:203], v[92:95]
	v_mfma_f32_16x16x32_bf16 v[92:95], v[166:169], v[196:199], v[92:95]
	v_mfma_f32_16x16x32_bf16 v[112:115], v[158:161], v[196:199], v[112:115]
	v_mfma_f32_16x16x32_bf16 v[112:115], v[162:165], v[200:203], v[112:115]
	v_mfma_f32_16x16x32_bf16 v[116:119], v[154:157], v[200:203], v[116:119]
	v_mfma_f32_16x16x32_bf16 v[116:119], v[150:153], v[196:199], v[116:119]
	s_setprio 0
	s_setprio 1
	v_mfma_f32_16x16x32_bf16 v[104:107], v[150:153], v[208:211], v[104:107]
	v_mfma_f32_16x16x32_bf16 v[104:107], v[154:157], v[212:215], v[104:107]
	v_mfma_f32_16x16x32_bf16 v[96:99], v[162:165], v[212:215], v[96:99]
	v_mfma_f32_16x16x32_bf16 v[96:99], v[158:161], v[208:211], v[96:99]
	v_mfma_f32_16x16x32_bf16 v[76:79], v[166:169], v[208:211], v[76:79]
	v_mfma_f32_16x16x32_bf16 v[76:79], v[170:173], v[212:215], v[76:79]
	v_mfma_f32_16x16x32_bf16 v[72:75], v[178:181], v[212:215], v[72:75]
	v_mfma_f32_16x16x32_bf16 v[72:75], v[174:177], v[208:211], v[72:75]
	s_setprio 0
	s_setprio 1
	v_mfma_f32_16x16x32_bf16 v[64:67], v[174:177], v[216:219], v[64:67]
	v_mfma_f32_16x16x32_bf16 v[64:67], v[178:181], v[220:223], v[64:67]
	v_mfma_f32_16x16x32_bf16 v[68:71], v[170:173], v[220:223], v[68:71]
	v_mfma_f32_16x16x32_bf16 v[68:71], v[166:169], v[216:219], v[68:71]
	v_mfma_f32_16x16x32_bf16 v[80:83], v[158:161], v[216:219], v[80:83]
	v_mfma_f32_16x16x32_bf16 v[80:83], v[162:165], v[220:223], v[80:83]
	v_mfma_f32_16x16x32_bf16 v[88:91], v[154:157], v[220:223], v[88:91]
	v_mfma_f32_16x16x32_bf16 v[88:91], v[150:153], v[216:219], v[88:91]
	s_setprio 0
	s_barrier
	s_add_i32 s4, s70, s58
	v_lshl_add_u64 v[224:225], s[52:53], 0, v[130:131]
	s_mov_b32 m0, s4
	ds_read_b128 v[182:185], v189 offset:16384
	ds_read_b128 v[192:195], v189 offset:17408
	ds_read_b128 v[196:199], v189 offset:18432
	ds_read_b128 v[200:203], v189 offset:19456
	ds_read_b128 v[208:211], v189 offset:20480
	ds_read_b128 v[212:215], v189 offset:21504
	ds_read_b128 v[216:219], v189 offset:22528
	ds_read_b128 v[220:223], v189 offset:23552
	global_load_lds_dwordx4 v[224:225], off
	s_add_i32 m0, s4, 0x2000
	s_add_u32 s4, s52, 0x158000
	v_lshl_add_u64 v[226:227], s[52:53], 0, v[134:135]
	s_addc_u32 s5, s53, 0
	s_add_i32 s85, s71, s58
	global_load_lds_dwordx4 v[226:227], off
	v_lshl_add_u64 v[230:231], s[4:5], 0, v[130:131]
	s_mov_b32 m0, s85
	v_lshl_add_u64 v[232:233], s[54:55], 0, v[132:133]
	global_load_lds_dwordx4 v[230:231], off
	v_lshl_add_u64 v[230:231], s[4:5], 0, v[134:135]
	s_add_i32 m0, s85, 0x2000
	s_nop 0
	global_load_lds_dwordx4 v[230:231], off
	v_lshl_add_u64 v[230:231], s[54:55], 0, v[128:129]
	s_mov_b32 m0, s59
	s_nop 0
	global_load_lds_dwordx4 v[230:231], off
	s_mov_b32 m0, s60
	s_nop 0
	global_load_lds_dwordx4 v[232:233], off
	s_waitcnt vmcnt(8)
	s_waitcnt lgkmcnt(0)
	s_barrier
; #define PG8_STAGE(bufoff, gbase, voff) do { _Pragma("unroll") for (int _i = 0; _i < 2; ++_i) \
;         __builtin_amdgcn_global_load_lds((const unsigned*)((const char*)(gbase) + (voff)[_i]), (LAS unsigned*)(lds + (bufoff) + ldsw + _i * 8192), 16, 0, 0); } while (0)
; #define PG8_LDA(dst, b, h) do { _Pragma("unroll") for (int m = 0; m < 4; ++m) _Pragma("unroll") for (int k = 0; k < 2; ++k) dst[m][k] = *(const LAS bf16x8*)(lds + PG8_SA(b, h) + aoff + m * 2048 + k * 1024); } while (0)
; #define PG8_LDB(dst, b, h) do { _Pragma("unroll") for (int n = 0; n < 2; ++n) _Pragma("unroll") for (int k = 0; k < 2; ++k) dst[n][k] = *(const LAS bf16x8*)(lds + PG8_SB(b, h) + boff + n * 2048 + k * 1024); } while (0)
; #define PG8_MMA(ai, bj, At, Bt) do { __builtin_amdgcn_s_setprio(1); _Pragma("unroll") for (int m = 0; m < 4; ++m) _Pragma("unroll") for (int n = 0; n < 2; ++n) _Pragma("unroll") for (int k = 0; k < 2; ++k) \
;         acc[ai][bj][m][n] = __builtin_amdgcn_mfma_f32_16x16x32_bf16(Bt[n][k], At[m][k], acc[ai][bj][m][n], 0, 0, 0); __builtin_amdgcn_s_setprio(0); } while (0)
; #define PG8_WAIT_V(n) asm volatile("s_waitcnt vmcnt(" #n ")" ::: "memory")
; #define PG8_WAIT_L(n) asm volatile("s_waitcnt lgkmcnt(" #n ")" ::: "memory")
; #define PG8_BAR __builtin_amdgcn_s_barrier()
; #define PG8_SCHED __builtin_amdgcn_sched_barrier(0)
; template <class Epi>
; __device__ __forceinline__ void gemm_phase(LAS unsigned char* lds, const Gemm g, const StaticOrder& S, const Epi& E) {
;     ...
;             PG8_WAIT_V(8); PG8_WAIT_L(0); PG8_BAR; PG8_MMA(1, 0, At, B0); PG8_MMA(1, 1, At, B1); PG8_BAR; PG8_SCHED;
;             PG8_LDB(B0, 1, 0); PG8_LDB(B1, 1, 1); PG8_SCHED; PG8_LDA(At, 1, 0); PG8_STAGE(PG8_SA(0, 1), a2 + hstepA, voffA);
;             PG8_WAIT_V(8); PG8_WAIT_L(0); PG8_BAR; PG8_MMA(0, 0, At, B0); PG8_MMA(0, 1, At, B1); PG8_BAR; PG8_SCHED;
	s_setprio 1
	s_waitcnt lgkmcnt(0)
	v_mfma_f32_16x16x32_bf16 v[60:63], v[150:153], v[182:185], v[60:63]
	v_mfma_f32_16x16x32_bf16 v[60:63], v[154:157], v[192:195], v[60:63]
	v_mfma_f32_16x16x32_bf16 v[56:59], v[162:165], v[192:195], v[56:59]
	v_mfma_f32_16x16x32_bf16 v[56:59], v[158:161], v[182:185], v[56:59]
	v_mfma_f32_16x16x32_bf16 v[44:47], v[166:169], v[182:185], v[44:47]
	v_mfma_f32_16x16x32_bf16 v[44:47], v[170:173], v[192:195], v[44:47]
	v_mfma_f32_16x16x32_bf16 v[36:39], v[178:181], v[192:195], v[36:39]
	v_mfma_f32_16x16x32_bf16 v[36:39], v[174:177], v[182:185], v[36:39]
	s_setprio 0
	s_setprio 1
	v_mfma_f32_16x16x32_bf16 v[20:23], v[174:177], v[196:199], v[20:23]
	v_mfma_f32_16x16x32_bf16 v[20:23], v[178:181], v[200:203], v[20:23]
	v_mfma_f32_16x16x32_bf16 v[28:31], v[170:173], v[200:203], v[28:31]
	v_mfma_f32_16x16x32_bf16 v[28:31], v[166:169], v[196:199], v[28:31]
	v_mfma_f32_16x16x32_bf16 v[48:51], v[158:161], v[196:199], v[48:51]
	v_mfma_f32_16x16x32_bf16 v[48:51], v[162:165], v[200:203], v[48:51]
	v_mfma_f32_16x16x32_bf16 v[52:55], v[154:157], v[200:203], v[52:55]
	v_mfma_f32_16x16x32_bf16 v[52:55], v[150:153], v[196:199], v[52:55]
	s_setprio 0
	s_setprio 1
	v_mfma_f32_16x16x32_bf16 v[40:43], v[150:153], v[208:211], v[40:43]
	v_mfma_f32_16x16x32_bf16 v[40:43], v[154:157], v[212:215], v[40:43]
	v_mfma_f32_16x16x32_bf16 v[32:35], v[162:165], v[212:215], v[32:35]
	v_mfma_f32_16x16x32_bf16 v[32:35], v[158:161], v[208:211], v[32:35]
	v_mfma_f32_16x16x32_bf16 v[12:15], v[166:169], v[208:211], v[12:15]
	v_mfma_f32_16x16x32_bf16 v[12:15], v[170:173], v[212:215], v[12:15]
	v_mfma_f32_16x16x32_bf16 v[8:11], v[178:181], v[212:215], v[8:11]
	v_mfma_f32_16x16x32_bf16 v[8:11], v[174:177], v[208:211], v[8:11]
	s_setprio 0
	s_setprio 1
	v_mfma_f32_16x16x32_bf16 v[0:3], v[174:177], v[216:219], v[0:3]
	v_mfma_f32_16x16x32_bf16 v[0:3], v[178:181], v[220:223], v[0:3]
	v_mfma_f32_16x16x32_bf16 v[4:7], v[170:173], v[220:223], v[4:7]
	v_mfma_f32_16x16x32_bf16 v[4:7], v[166:169], v[216:219], v[4:7]
	v_mfma_f32_16x16x32_bf16 v[16:19], v[158:161], v[216:219], v[16:19]
	v_mfma_f32_16x16x32_bf16 v[16:19], v[162:165], v[220:223], v[16:19]
	v_mfma_f32_16x16x32_bf16 v[24:27], v[154:157], v[220:223], v[24:27]
	v_mfma_f32_16x16x32_bf16 v[24:27], v[150:153], v[216:219], v[24:27]
	s_setprio 0
	s_barrier
	s_add_i32 s85, 0, 0x18000
	s_add_i32 s86, 0, 0x1c000
	v_add_u32_e32 v162, s85, v186
	v_add_u32_e32 v178, s86, v186
	ds_read_b128 v[150:153], v162
	ds_read_b128 v[154:157], v162 offset:1024
	ds_read_b128 v[158:161], v162 offset:2048
	ds_read_b128 v[162:165], v162 offset:3072
	ds_read_b128 v[166:169], v178
	ds_read_b128 v[170:173], v178 offset:1024
	ds_read_b128 v[174:177], v178 offset:2048
	ds_read_b128 v[178:181], v178 offset:3072
	s_add_u32 s4, s54, 0x158000
	s_addc_u32 s5, s55, 0
	s_mov_b32 m0, s61
	v_lshl_add_u64 v[234:235], s[4:5], 0, v[128:129]
	ds_read_b128 v[182:185], v189 offset:32768
	ds_read_b128 v[192:195], v189 offset:33792
	ds_read_b128 v[196:199], v189 offset:34816
	ds_read_b128 v[200:203], v189 offset:35840
	ds_read_b128 v[208:211], v189 offset:36864
	ds_read_b128 v[212:215], v189 offset:37888
	ds_read_b128 v[216:219], v189 offset:38912
	ds_read_b128 v[220:223], v189 offset:39936
	global_load_lds_dwordx4 v[234:235], off
	v_lshl_add_u64 v[234:235], s[4:5], 0, v[132:133]
	s_mov_b32 m0, s62
	s_nop 0
	global_load_lds_dwordx4 v[234:235], off
	s_waitcnt vmcnt(8)
	s_waitcnt lgkmcnt(0)
	s_barrier
	s_setprio 1
	s_waitcnt lgkmcnt(0)
	v_mfma_f32_16x16x32_bf16 v[124:127], v[150:153], v[182:185], v[124:127]
	v_mfma_f32_16x16x32_bf16 v[124:127], v[154:157], v[192:195], v[124:127]
	v_mfma_f32_16x16x32_bf16 v[120:123], v[162:165], v[192:195], v[120:123]
	v_mfma_f32_16x16x32_bf16 v[120:123], v[158:161], v[182:185], v[120:123]
	v_mfma_f32_16x16x32_bf16 v[108:111], v[166:169], v[182:185], v[108:111]
	v_mfma_f32_16x16x32_bf16 v[108:111], v[170:173], v[192:195], v[108:111]
	v_mfma_f32_16x16x32_bf16 v[100:103], v[178:181], v[192:195], v[100:103]
	v_mfma_f32_16x16x32_bf16 v[100:103], v[174:177], v[182:185], v[100:103]
	s_setprio 0
	s_setprio 1
	v_mfma_f32_16x16x32_bf16 v[84:87], v[174:177], v[196:199], v[84:87]
	v_mfma_f32_16x16x32_bf16 v[84:87], v[178:181], v[200:203], v[84:87]
	v_mfma_f32_16x16x32_bf16 v[92:95], v[170:173], v[200:203], v[92:95]
	v_mfma_f32_16x16x32_bf16 v[92:95], v[166:169], v[196:199], v[92:95]
	v_mfma_f32_16x16x32_bf16 v[112:115], v[158:161], v[196:199], v[112:115]
	v_mfma_f32_16x16x32_bf16 v[112:115], v[162:165], v[200:203], v[112:115]
	v_mfma_f32_16x16x32_bf16 v[116:119], v[154:157], v[200:203], v[116:119]
	v_mfma_f32_16x16x32_bf16 v[116:119], v[150:153], v[196:199], v[116:119]
	s_setprio 0
	s_setprio 1
	v_mfma_f32_16x16x32_bf16 v[104:107], v[150:153], v[208:211], v[104:107]
	v_mfma_f32_16x16x32_bf16 v[104:107], v[154:157], v[212:215], v[104:107]
	v_mfma_f32_16x16x32_bf16 v[96:99], v[162:165], v[212:215], v[96:99]
	v_mfma_f32_16x16x32_bf16 v[96:99], v[158:161], v[208:211], v[96:99]
	v_mfma_f32_16x16x32_bf16 v[76:79], v[166:169], v[208:211], v[76:79]
	v_mfma_f32_16x16x32_bf16 v[76:79], v[170:173], v[212:215], v[76:79]
	v_mfma_f32_16x16x32_bf16 v[72:75], v[178:181], v[212:215], v[72:75]
	v_mfma_f32_16x16x32_bf16 v[72:75], v[174:177], v[208:211], v[72:75]
	s_setprio 0
	s_setprio 1
	v_mfma_f32_16x16x32_bf16 v[64:67], v[174:177], v[216:219], v[64:67]
	v_mfma_f32_16x16x32_bf16 v[64:67], v[178:181], v[220:223], v[64:67]
	v_mfma_f32_16x16x32_bf16 v[68:71], v[170:173], v[220:223], v[68:71]
	v_mfma_f32_16x16x32_bf16 v[68:71], v[166:169], v[216:219], v[68:71]
	v_mfma_f32_16x16x32_bf16 v[80:83], v[158:161], v[216:219], v[80:83]
	v_mfma_f32_16x16x32_bf16 v[80:83], v[162:165], v[220:223], v[80:83]
	v_mfma_f32_16x16x32_bf16 v[88:91], v[154:157], v[220:223], v[88:91]
	v_mfma_f32_16x16x32_bf16 v[88:91], v[150:153], v[216:219], v[88:91]
	s_setprio 0
	s_barrier
; #define PG8_STAGE(bufoff, gbase, voff) do { _Pragma("unroll") for (int _i = 0; _i < 2; ++_i) \
;         __builtin_amdgcn_global_load_lds((const unsigned*)((const char*)(gbase) + (voff)[_i]), (LAS unsigned*)(lds + (bufoff) + ldsw + _i * 8192), 16, 0, 0); } while (0)
; #define PG8_LDA(dst, b, h) do { _Pragma("unroll") for (int m = 0; m < 4; ++m) _Pragma("unroll") for (int k = 0; k < 2; ++k) dst[m][k] = *(const LAS bf16x8*)(lds + PG8_SA(b, h) + aoff + m * 2048 + k * 1024); } while (0)
; #define PG8_MMA(ai, bj, At, Bt) do { __builtin_amdgcn_s_setprio(1); _Pragma("unroll") for (int m = 0; m < 4; ++m) _Pragma("unroll") for (int n = 0; n < 2; ++n) _Pragma("unroll") for (int k = 0; k < 2; ++k) \
;         acc[ai][bj][m][n] = __builtin_amdgcn_mfma_f32_16x16x32_bf16(Bt[n][k], At[m][k], acc[ai][bj][m][n], 0, 0, 0); __builtin_amdgcn_s_setprio(0); } while (0)
; #define PG8_WAIT_V(n) asm volatile("s_waitcnt vmcnt(" #n ")" ::: "memory")
; #define PG8_WAIT_L(n) asm volatile("s_waitcnt lgkmcnt(" #n ")" ::: "memory")
; #define PG8_BAR __builtin_amdgcn_s_barrier()
; #define PG8_SCHED __builtin_amdgcn_sched_barrier(0)
; template <class Epi>
; __device__ __forceinline__ void gemm_phase(LAS unsigned char* lds, const Gemm g, const StaticOrder& S, const Epi& E) {
;     ...
;             PG8_LDA(At, 1, 1); PG8_STAGE(PG8_SB(1, 0), b3, voffB); PG8_STAGE(PG8_SB(1, 1), b3 + hstepB, voffB); PG8_STAGE(PG8_SA(1, 0), a3, voffA);
;             PG8_WAIT_V(8); PG8_WAIT_L(0); PG8_BAR; PG8_MMA(1, 0, At, B0); PG8_MMA(1, 1, At, B1); PG8_BAR; PG8_SCHED;
;         }
	s_add_i32 s4, s85, s58
	v_lshl_add_u64 v[224:225], v[224:225], 0, s[16:17]
	s_mov_b32 m0, s4
	ds_read_b128 v[182:185], v189 offset:49152
	ds_read_b128 v[192:195], v189 offset:50176
	ds_read_b128 v[196:199], v189 offset:51200
	ds_read_b128 v[200:203], v189 offset:52224
	ds_read_b128 v[208:211], v189 offset:53248
	ds_read_b128 v[212:215], v189 offset:54272
	ds_read_b128 v[216:219], v189 offset:55296
	ds_read_b128 v[220:223], v189 offset:56320
	global_load_lds_dwordx4 v[224:225], off
	s_add_i32 m0, s4, 0x2000
	s_add_u32 s4, s52, 0x158080
	v_lshl_add_u64 v[224:225], v[226:227], 0, s[16:17]
	s_addc_u32 s5, s53, 0
	s_add_i32 s52, s86, s58
	global_load_lds_dwordx4 v[224:225], off
	v_lshl_add_u64 v[224:225], s[4:5], 0, v[130:131]
	s_mov_b32 m0, s52
	s_nop 0
	global_load_lds_dwordx4 v[224:225], off
	v_lshl_add_u64 v[224:225], s[4:5], 0, v[134:135]
	s_add_i32 m0, s52, 0x2000
	s_nop 0
	global_load_lds_dwordx4 v[224:225], off
	v_lshl_add_u64 v[224:225], v[230:231], 0, s[16:17]
	s_mov_b32 m0, s65
	s_nop 0
	global_load_lds_dwordx4 v[224:225], off
	v_lshl_add_u64 v[224:225], v[232:233], 0, s[16:17]
	s_mov_b32 m0, s66
	s_nop 0
	global_load_lds_dwordx4 v[224:225], off
	s_waitcnt vmcnt(8)
	s_waitcnt lgkmcnt(0)
	s_barrier
	s_setprio 1
	s_waitcnt lgkmcnt(0)
	v_mfma_f32_16x16x32_bf16 v[60:63], v[150:153], v[182:185], v[60:63]
	v_mfma_f32_16x16x32_bf16 v[60:63], v[154:157], v[192:195], v[60:63]
	v_mfma_f32_16x16x32_bf16 v[56:59], v[162:165], v[192:195], v[56:59]
	v_mfma_f32_16x16x32_bf16 v[56:59], v[158:161], v[182:185], v[56:59]
	v_mfma_f32_16x16x32_bf16 v[44:47], v[166:169], v[182:185], v[44:47]
	v_mfma_f32_16x16x32_bf16 v[44:47], v[170:173], v[192:195], v[44:47]
	v_mfma_f32_16x16x32_bf16 v[36:39], v[178:181], v[192:195], v[36:39]
	v_mfma_f32_16x16x32_bf16 v[36:39], v[174:177], v[182:185], v[36:39]
	s_setprio 0
	s_setprio 1
	v_mfma_f32_16x16x32_bf16 v[20:23], v[174:177], v[196:199], v[20:23]
	v_mfma_f32_16x16x32_bf16 v[20:23], v[178:181], v[200:203], v[20:23]
	v_mfma_f32_16x16x32_bf16 v[28:31], v[170:173], v[200:203], v[28:31]
	v_mfma_f32_16x16x32_bf16 v[28:31], v[166:169], v[196:199], v[28:31]
	v_mfma_f32_16x16x32_bf16 v[48:51], v[158:161], v[196:199], v[48:51]
	v_mfma_f32_16x16x32_bf16 v[48:51], v[162:165], v[200:203], v[48:51]
	v_mfma_f32_16x16x32_bf16 v[52:55], v[154:157], v[200:203], v[52:55]
	v_mfma_f32_16x16x32_bf16 v[52:55], v[150:153], v[196:199], v[52:55]
	s_setprio 0
	s_setprio 1
	v_mfma_f32_16x16x32_bf16 v[40:43], v[150:153], v[208:211], v[40:43]
	v_mfma_f32_16x16x32_bf16 v[40:43], v[154:157], v[212:215], v[40:43]
	v_mfma_f32_16x16x32_bf16 v[32:35], v[162:165], v[212:215], v[32:35]
	v_mfma_f32_16x16x32_bf16 v[32:35], v[158:161], v[208:211], v[32:35]
	v_mfma_f32_16x16x32_bf16 v[12:15], v[166:169], v[208:211], v[12:15]
	v_mfma_f32_16x16x32_bf16 v[12:15], v[170:173], v[212:215], v[12:15]
	v_mfma_f32_16x16x32_bf16 v[8:11], v[178:181], v[212:215], v[8:11]
	v_mfma_f32_16x16x32_bf16 v[8:11], v[174:177], v[208:211], v[8:11]
	s_setprio 0
	s_setprio 1
	v_mfma_f32_16x16x32_bf16 v[0:3], v[174:177], v[216:219], v[0:3]
	v_mfma_f32_16x16x32_bf16 v[0:3], v[178:181], v[220:223], v[0:3]
	v_mfma_f32_16x16x32_bf16 v[4:7], v[170:173], v[220:223], v[4:7]
	v_mfma_f32_16x16x32_bf16 v[4:7], v[166:169], v[216:219], v[4:7]
	v_mfma_f32_16x16x32_bf16 v[16:19], v[158:161], v[216:219], v[16:19]
	v_mfma_f32_16x16x32_bf16 v[16:19], v[162:165], v[220:223], v[16:19]
	v_mfma_f32_16x16x32_bf16 v[24:27], v[154:157], v[220:223], v[24:27]
	v_mfma_f32_16x16x32_bf16 v[24:27], v[150:153], v[216:219], v[24:27]
	s_setprio 0
	s_barrier
; #define PG8_MMA(ai, bj, At, Bt) do { __builtin_amdgcn_s_setprio(1); _Pragma("unroll") for (int m = 0; m < 4; ++m) _Pragma("unroll") for (int n = 0; n < 2; ++n) _Pragma("unroll") for (int k = 0; k < 2; ++k) \
;         acc[ai][bj][m][n] = __builtin_amdgcn_mfma_f32_16x16x32_bf16(Bt[n][k], At[m][k], acc[ai][bj][m][n], 0, 0, 0); __builtin_amdgcn_s_setprio(0); } while (0)
; #define PG8_WAIT_V(n) asm volatile("s_waitcnt vmcnt(" #n ")" ::: "memory")
; #define PG8_WAIT_L(n) asm volatile("s_waitcnt lgkmcnt(" #n ")" ::: "memory")
; #define PG8_BAR __builtin_amdgcn_s_barrier()
; #define PG8_SCHED __builtin_amdgcn_sched_barrier(0)
; template <class Epi>
; __device__ __forceinline__ void gemm_phase(LAS unsigned char* lds, const Gemm g, const StaticOrder& S, const Epi& E) {
;     ...
;             PG8_WAIT_V(8); PG8_WAIT_L(0); PG8_BAR; PG8_MMA(1, 0, At, B0); PG8_MMA(1, 1, At, B1); PG8_BAR; PG8_SCHED;
;         }
	s_add_u32 s1, s1, 0x100
	s_addc_u32 s77, s77, 0
	s_cmp_ge_i32 s84, s64
	s_mov_b64 s[4:5], s[12:13]
	s_mov_b32 s52, s84
	s_cbranch_scc0 .LBB0_1244
	v_pk_mul_f32 v[170:171], v[126:127], 0.5 op_sel_hi:[1,0]
	v_pk_mul_f32 v[172:173], v[124:125], 0.5 op_sel_hi:[1,0]
	v_pk_mul_f32 v[174:175], v[122:123], 0.5 op_sel_hi:[1,0]
	v_pk_mul_f32 v[176:177], v[120:121], 0.5 op_sel_hi:[1,0]
	v_pk_mul_f32 v[178:179], v[110:111], 0.5 op_sel_hi:[1,0]
	v_pk_mul_f32 v[180:181], v[108:109], 0.5 op_sel_hi:[1,0]
	v_pk_mul_f32 v[182:183], v[102:103], 0.5 op_sel_hi:[1,0]
	v_pk_mul_f32 v[184:185], v[100:101], 0.5 op_sel_hi:[1,0]
	v_pk_mul_f32 v[160:161], v[118:119], 0.5 op_sel_hi:[1,0]
	v_pk_mul_f32 v[158:159], v[116:117], 0.5 op_sel_hi:[1,0]
	v_pk_mul_f32 v[156:157], v[114:115], 0.5 op_sel_hi:[1,0]
	v_pk_mul_f32 v[154:155], v[112:113], 0.5 op_sel_hi:[1,0]
	v_pk_mul_f32 v[168:169], v[94:95], 0.5 op_sel_hi:[1,0]
	v_pk_mul_f32 v[166:167], v[92:93], 0.5 op_sel_hi:[1,0]
	v_pk_mul_f32 v[164:165], v[86:87], 0.5 op_sel_hi:[1,0]
	v_pk_mul_f32 v[162:163], v[84:85], 0.5 op_sel_hi:[1,0]
	v_pk_mul_f32 v[116:117], v[106:107], 0.5 op_sel_hi:[1,0]
	v_pk_mul_f32 v[118:119], v[104:105], 0.5 op_sel_hi:[1,0]
	v_pk_mul_f32 v[120:121], v[98:99], 0.5 op_sel_hi:[1,0]
	v_pk_mul_f32 v[122:123], v[96:97], 0.5 op_sel_hi:[1,0]
	v_pk_mul_f32 v[124:125], v[78:79], 0.5 op_sel_hi:[1,0]
	v_pk_mul_f32 v[126:127], v[76:77], 0.5 op_sel_hi:[1,0]
	v_pk_mul_f32 v[150:151], v[74:75], 0.5 op_sel_hi:[1,0]
	v_pk_mul_f32 v[152:153], v[72:73], 0.5 op_sel_hi:[1,0]
	v_pk_mul_f32 v[104:105], v[90:91], 0.5 op_sel_hi:[1,0]
	v_pk_mul_f32 v[102:103], v[88:89], 0.5 op_sel_hi:[1,0]
	v_pk_mul_f32 v[100:101], v[82:83], 0.5 op_sel_hi:[1,0]
	v_pk_mul_f32 v[98:99], v[80:81], 0.5 op_sel_hi:[1,0]
	v_pk_mul_f32 v[112:113], v[70:71], 0.5 op_sel_hi:[1,0]
	v_pk_mul_f32 v[110:111], v[68:69], 0.5 op_sel_hi:[1,0]
	v_pk_mul_f32 v[108:109], v[66:67], 0.5 op_sel_hi:[1,0]
	v_pk_mul_f32 v[106:107], v[64:65], 0.5 op_sel_hi:[1,0]
	v_pk_mul_f32 v[80:81], v[62:63], 0.5 op_sel_hi:[1,0]
	v_pk_mul_f32 v[82:83], v[60:61], 0.5 op_sel_hi:[1,0]
	v_pk_mul_f32 v[84:85], v[58:59], 0.5 op_sel_hi:[1,0]
	v_pk_mul_f32 v[86:87], v[56:57], 0.5 op_sel_hi:[1,0]
	v_pk_mul_f32 v[88:89], v[46:47], 0.5 op_sel_hi:[1,0]
	v_pk_mul_f32 v[90:91], v[44:45], 0.5 op_sel_hi:[1,0]
	v_pk_mul_f32 v[92:93], v[38:39], 0.5 op_sel_hi:[1,0]
	v_pk_mul_f32 v[94:95], v[36:37], 0.5 op_sel_hi:[1,0]
	v_pk_mul_f32 v[70:71], v[54:55], 0.5 op_sel_hi:[1,0]
	v_pk_mul_f32 v[68:69], v[52:53], 0.5 op_sel_hi:[1,0]
	v_pk_mul_f32 v[66:67], v[50:51], 0.5 op_sel_hi:[1,0]
	v_pk_mul_f32 v[64:65], v[48:49], 0.5 op_sel_hi:[1,0]
	v_pk_mul_f32 v[78:79], v[30:31], 0.5 op_sel_hi:[1,0]
	v_pk_mul_f32 v[76:77], v[28:29], 0.5 op_sel_hi:[1,0]
	v_pk_mul_f32 v[74:75], v[22:23], 0.5 op_sel_hi:[1,0]
	v_pk_mul_f32 v[72:73], v[20:21], 0.5 op_sel_hi:[1,0]
	v_pk_mul_f32 v[54:55], v[42:43], 0.5 op_sel_hi:[1,0]
	v_pk_mul_f32 v[52:53], v[40:41], 0.5 op_sel_hi:[1,0]
	v_pk_mul_f32 v[50:51], v[34:35], 0.5 op_sel_hi:[1,0]
	v_pk_mul_f32 v[48:49], v[32:33], 0.5 op_sel_hi:[1,0]
	v_pk_mul_f32 v[62:63], v[14:15], 0.5 op_sel_hi:[1,0]
	v_pk_mul_f32 v[60:61], v[12:13], 0.5 op_sel_hi:[1,0]
	v_pk_mul_f32 v[58:59], v[10:11], 0.5 op_sel_hi:[1,0]
	v_pk_mul_f32 v[56:57], v[8:9], 0.5 op_sel_hi:[1,0]
	v_pk_mul_f32 v[38:39], v[26:27], 0.5 op_sel_hi:[1,0]
	v_pk_mul_f32 v[36:37], v[24:25], 0.5 op_sel_hi:[1,0]
	v_pk_mul_f32 v[34:35], v[18:19], 0.5 op_sel_hi:[1,0]
	v_pk_mul_f32 v[32:33], v[16:17], 0.5 op_sel_hi:[1,0]
	v_pk_mul_f32 v[46:47], v[6:7], 0.5 op_sel_hi:[1,0]
	v_pk_mul_f32 v[44:45], v[4:5], 0.5 op_sel_hi:[1,0]
	v_pk_mul_f32 v[42:43], v[2:3], 0.5 op_sel_hi:[1,0]
	v_pk_mul_f32 v[40:41], v[0:1], 0.5 op_sel_hi:[1,0]

; #define PG8_STAGE(bufoff, gbase, voff) do { _Pragma("unroll") for (int _i = 0; _i < 2; ++_i) \
;         __builtin_amdgcn_global_load_lds((const unsigned*)((const char*)(gbase) + (voff)[_i]), (LAS unsigned*)(lds + (bufoff) + ldsw + _i * 8192), 16, 0, 0); } while (0)
; #define PG8_LDA(dst, b, h) do { _Pragma("unroll") for (int m = 0; m < 4; ++m) _Pragma("unroll") for (int k = 0; k < 2; ++k) dst[m][k] = *(const LAS bf16x8*)(lds + PG8_SA(b, h) + aoff + m * 2048 + k * 1024); } while (0)
; #define PG8_LDB(dst, b, h) do { _Pragma("unroll") for (int n = 0; n < 2; ++n) _Pragma("unroll") for (int k = 0; k < 2; ++k) dst[n][k] = *(const LAS bf16x8*)(lds + PG8_SB(b, h) + boff + n * 2048 + k * 1024); } while (0)
; #define PG8_MMA(ai, bj, At, Bt) do { __builtin_amdgcn_s_setprio(1); _Pragma("unroll") for (int m = 0; m < 4; ++m) _Pragma("unroll") for (int n = 0; n < 2; ++n) _Pragma("unroll") for (int k = 0; k < 2; ++k) \
;         acc[ai][bj][m][n] = __builtin_amdgcn_mfma_f32_16x16x32_bf16(Bt[n][k], At[m][k], acc[ai][bj][m][n], 0, 0, 0); __builtin_amdgcn_s_setprio(0); } while (0)
; #define PG8_WAIT_V(n) asm volatile("s_waitcnt vmcnt(" #n ")" ::: "memory")
; #define PG8_WAIT_L(n) asm volatile("s_waitcnt lgkmcnt(" #n ")" ::: "memory")
; #define PG8_BAR __builtin_amdgcn_s_barrier()
; #define PG8_SCHED __builtin_amdgcn_sched_barrier(0)
; template <class Epi>
; __device__ __forceinline__ void gemm_phase(LAS unsigned char* lds, const Gemm g, const StaticOrder& S, const Epi& E) {
;     ...
;         for (int t = 0; t < nt; t += 2) {
;             const bool last = (t == nt - 2);
;             const char* a1 = cA + (size_t)(t + 1) * kstep;
;             const char* a2 = last ? nA : cA + (size_t)(t + 2) * kstep; const char* b2 = last ? nB : cB + (size_t)(t + 2) * kstep;
;             const char* a3 = a2 + kstep; const char* b3 = b2 + kstep;
;             PG8_LDB(B0, 0, 0); PG8_LDB(B1, 0, 1); PG8_SCHED; PG8_LDA(At, 0, 0); PG8_STAGE(PG8_SA(1, 1), a1 + hstepA, voffA);
;             PG8_WAIT_V(8); PG8_WAIT_L(0); PG8_BAR; PG8_MMA(0, 0, At, B0); PG8_MMA(0, 1, At, B1); PG8_BAR; PG8_SCHED;
;             PG8_LDA(At, 0, 1); PG8_STAGE(PG8_SB(0, 0), b2, voffB); PG8_STAGE(PG8_SB(0, 1), b2 + hstepB, voffB); PG8_STAGE(PG8_SA(0, 0), a2, voffA);
;             PG8_WAIT_V(8); PG8_WAIT_L(0); PG8_BAR; PG8_MMA(1, 0, At, B0); PG8_MMA(1, 1, At, B1); PG8_BAR; PG8_SCHED;
.LBB0_1338:
	ds_read_b128 v[128:131], v173
	ds_read_b128 v[132:135], v173 offset:1024
	ds_read_b128 v[136:139], v173 offset:2048
	ds_read_b128 v[140:143], v173 offset:3072
	ds_read_b128 v[144:147], v175
	ds_read_b128 v[148:151], v175 offset:1024
	ds_read_b128 v[176:179], v175 offset:2048
	ds_read_b128 v[184:187], v175 offset:3072
	s_add_i32 s20, s10, 2
	s_add_u32 s11, s8, 0xfff80080
	s_addc_u32 s12, s9, -1
	s_cmp_eq_u32 s56, s10
	s_cselect_b32 s10, s17, s18
	s_cselect_b32 s13, s1, s12
	s_cselect_b32 s12, s15, s11
	s_cselect_b32 s11, s16, s19
	v_lshl_add_u64 v[224:225], s[8:9], 0, v[164:165]
	s_add_i32 m0, s47, 0xc000
	ds_read_b128 v[188:191], v181
	ds_read_b128 v[192:195], v181 offset:1024
	ds_read_b128 v[196:199], v181 offset:2048
	ds_read_b128 v[200:203], v181 offset:3072
	ds_read_b128 v[208:211], v181 offset:4096
	ds_read_b128 v[212:215], v181 offset:5120
	ds_read_b128 v[216:219], v181 offset:6144
	ds_read_b128 v[220:223], v181 offset:7168
	global_load_lds_dwordx4 v[224:225], off
	v_lshl_add_u64 v[224:225], s[8:9], 0, v[166:167]
	s_add_i32 m0, s47, 0xe000
	s_nop 0
	global_load_lds_dwordx4 v[224:225], off
	s_waitcnt vmcnt(8)
	s_waitcnt lgkmcnt(0)
	s_barrier
	s_setprio 1
	s_waitcnt lgkmcnt(0)
	v_mfma_f32_16x16x32_bf16 v[124:127], v[128:131], v[188:191], v[124:127]
	v_mfma_f32_16x16x32_bf16 v[124:127], v[132:135], v[192:195], v[124:127]
	v_mfma_f32_16x16x32_bf16 v[120:123], v[140:143], v[192:195], v[120:123]
	v_mfma_f32_16x16x32_bf16 v[120:123], v[136:139], v[188:191], v[120:123]
	v_mfma_f32_16x16x32_bf16 v[116:119], v[144:147], v[188:191], v[116:119]
	v_mfma_f32_16x16x32_bf16 v[116:119], v[148:151], v[192:195], v[116:119]
	v_mfma_f32_16x16x32_bf16 v[112:115], v[184:187], v[192:195], v[112:115]
	v_mfma_f32_16x16x32_bf16 v[112:115], v[176:179], v[188:191], v[112:115]
	s_setprio 0
	s_setprio 1
	v_mfma_f32_16x16x32_bf16 v[96:99], v[176:179], v[196:199], v[96:99]
	v_mfma_f32_16x16x32_bf16 v[96:99], v[184:187], v[200:203], v[96:99]
	v_mfma_f32_16x16x32_bf16 v[100:103], v[148:151], v[200:203], v[100:103]
	v_mfma_f32_16x16x32_bf16 v[100:103], v[144:147], v[196:199], v[100:103]
	v_mfma_f32_16x16x32_bf16 v[104:107], v[136:139], v[196:199], v[104:107]
	v_mfma_f32_16x16x32_bf16 v[104:107], v[140:143], v[200:203], v[104:107]
	v_mfma_f32_16x16x32_bf16 v[108:111], v[132:135], v[200:203], v[108:111]
	v_mfma_f32_16x16x32_bf16 v[108:111], v[128:131], v[196:199], v[108:111]
	s_setprio 0
	s_setprio 1
	v_mfma_f32_16x16x32_bf16 v[92:95], v[128:131], v[208:211], v[92:95]
	v_mfma_f32_16x16x32_bf16 v[92:95], v[132:135], v[212:215], v[92:95]
	v_mfma_f32_16x16x32_bf16 v[88:91], v[140:143], v[212:215], v[88:91]
	v_mfma_f32_16x16x32_bf16 v[88:91], v[136:139], v[208:211], v[88:91]
	v_mfma_f32_16x16x32_bf16 v[84:87], v[144:147], v[208:211], v[84:87]
	v_mfma_f32_16x16x32_bf16 v[84:87], v[148:151], v[212:215], v[84:87]
	v_mfma_f32_16x16x32_bf16 v[80:83], v[184:187], v[212:215], v[80:83]
	v_mfma_f32_16x16x32_bf16 v[80:83], v[176:179], v[208:211], v[80:83]
	s_setprio 0
	s_setprio 1
	v_mfma_f32_16x16x32_bf16 v[64:67], v[176:179], v[216:219], v[64:67]
	v_mfma_f32_16x16x32_bf16 v[64:67], v[184:187], v[220:223], v[64:67]
	v_mfma_f32_16x16x32_bf16 v[68:71], v[148:151], v[220:223], v[68:71]
	v_mfma_f32_16x16x32_bf16 v[68:71], v[144:147], v[216:219], v[68:71]
	v_mfma_f32_16x16x32_bf16 v[72:75], v[136:139], v[216:219], v[72:75]
	v_mfma_f32_16x16x32_bf16 v[72:75], v[140:143], v[220:223], v[72:75]
	v_mfma_f32_16x16x32_bf16 v[76:79], v[132:135], v[220:223], v[76:79]
	v_mfma_f32_16x16x32_bf16 v[76:79], v[128:131], v[216:219], v[76:79]
	s_setprio 0
	s_barrier
	s_add_i32 s21, s59, s46
	v_lshl_add_u64 v[224:225], s[10:11], 0, v[154:155]
	s_mov_b32 m0, s21
	ds_read_b128 v[188:191], v181 offset:16384
	ds_read_b128 v[192:195], v181 offset:17408
	ds_read_b128 v[196:199], v181 offset:18432
	ds_read_b128 v[200:203], v181 offset:19456
	ds_read_b128 v[208:211], v181 offset:20480
	ds_read_b128 v[212:215], v181 offset:21504
	ds_read_b128 v[216:219], v181 offset:22528
	ds_read_b128 v[220:223], v181 offset:23552
	global_load_lds_dwordx4 v[224:225], off
	s_add_i32 m0, s21, 0x2000
	s_add_u32 s68, s10, 0x80000
	v_lshl_add_u64 v[226:227], s[10:11], 0, v[158:159]
	s_addc_u32 s69, s11, 0
	s_add_i32 s21, s60, s46
	global_load_lds_dwordx4 v[226:227], off
	v_lshl_add_u64 v[230:231], s[68:69], 0, v[154:155]
	s_mov_b32 m0, s21
	v_lshl_add_u64 v[232:233], s[12:13], 0, v[156:157]
	global_load_lds_dwordx4 v[230:231], off
	v_lshl_add_u64 v[230:231], s[68:69], 0, v[158:159]
	s_add_i32 m0, s21, 0x2000
	s_nop 0
	global_load_lds_dwordx4 v[230:231], off
	v_lshl_add_u64 v[230:231], s[12:13], 0, v[152:153]
	s_mov_b32 m0, s47
	s_nop 0
	global_load_lds_dwordx4 v[230:231], off
	s_mov_b32 m0, s48
	s_nop 0
	global_load_lds_dwordx4 v[232:233], off
	s_waitcnt vmcnt(8)
	s_waitcnt lgkmcnt(0)
	s_barrier
; #define PG8_STAGE(bufoff, gbase, voff) do { _Pragma("unroll") for (int _i = 0; _i < 2; ++_i) \
;         __builtin_amdgcn_global_load_lds((const unsigned*)((const char*)(gbase) + (voff)[_i]), (LAS unsigned*)(lds + (bufoff) + ldsw + _i * 8192), 16, 0, 0); } while (0)
; #define PG8_LDA(dst, b, h) do { _Pragma("unroll") for (int m = 0; m < 4; ++m) _Pragma("unroll") for (int k = 0; k < 2; ++k) dst[m][k] = *(const LAS bf16x8*)(lds + PG8_SA(b, h) + aoff + m * 2048 + k * 1024); } while (0)
; #define PG8_LDB(dst, b, h) do { _Pragma("unroll") for (int n = 0; n < 2; ++n) _Pragma("unroll") for (int k = 0; k < 2; ++k) dst[n][k] = *(const LAS bf16x8*)(lds + PG8_SB(b, h) + boff + n * 2048 + k * 1024); } while (0)
; #define PG8_MMA(ai, bj, At, Bt) do { __builtin_amdgcn_s_setprio(1); _Pragma("unroll") for (int m = 0; m < 4; ++m) _Pragma("unroll") for (int n = 0; n < 2; ++n) _Pragma("unroll") for (int k = 0; k < 2; ++k) \
;         acc[ai][bj][m][n] = __builtin_amdgcn_mfma_f32_16x16x32_bf16(Bt[n][k], At[m][k], acc[ai][bj][m][n], 0, 0, 0); __builtin_amdgcn_s_setprio(0); } while (0)
; #define PG8_WAIT_V(n) asm volatile("s_waitcnt vmcnt(" #n ")" ::: "memory")
; #define PG8_WAIT_L(n) asm volatile("s_waitcnt lgkmcnt(" #n ")" ::: "memory")
; #define PG8_BAR __builtin_amdgcn_s_barrier()
; #define PG8_SCHED __builtin_amdgcn_sched_barrier(0)
; template <class Epi>
; __device__ __forceinline__ void gemm_phase(LAS unsigned char* lds, const Gemm g, const StaticOrder& S, const Epi& E) {
;     ...
;             PG8_WAIT_V(8); PG8_WAIT_L(0); PG8_BAR; PG8_MMA(1, 0, At, B0); PG8_MMA(1, 1, At, B1); PG8_BAR; PG8_SCHED;
;             PG8_LDB(B0, 1, 0); PG8_LDB(B1, 1, 1); PG8_SCHED; PG8_LDA(At, 1, 0); PG8_STAGE(PG8_SA(0, 1), a2 + hstepA, voffA);
;             PG8_WAIT_V(8); PG8_WAIT_L(0); PG8_BAR; PG8_MMA(0, 0, At, B0); PG8_MMA(0, 1, At, B1); PG8_BAR; PG8_SCHED;
	s_setprio 1
	s_waitcnt lgkmcnt(0)
	v_mfma_f32_16x16x32_bf16 v[60:63], v[128:131], v[188:191], v[60:63]
	v_mfma_f32_16x16x32_bf16 v[60:63], v[132:135], v[192:195], v[60:63]
	v_mfma_f32_16x16x32_bf16 v[56:59], v[140:143], v[192:195], v[56:59]
	v_mfma_f32_16x16x32_bf16 v[56:59], v[136:139], v[188:191], v[56:59]
	v_mfma_f32_16x16x32_bf16 v[52:55], v[144:147], v[188:191], v[52:55]
	v_mfma_f32_16x16x32_bf16 v[52:55], v[148:151], v[192:195], v[52:55]
	v_mfma_f32_16x16x32_bf16 v[48:51], v[184:187], v[192:195], v[48:51]
	v_mfma_f32_16x16x32_bf16 v[48:51], v[176:179], v[188:191], v[48:51]
	s_setprio 0
	s_setprio 1
	v_mfma_f32_16x16x32_bf16 v[32:35], v[176:179], v[196:199], v[32:35]
	v_mfma_f32_16x16x32_bf16 v[32:35], v[184:187], v[200:203], v[32:35]
	v_mfma_f32_16x16x32_bf16 v[36:39], v[148:151], v[200:203], v[36:39]
	v_mfma_f32_16x16x32_bf16 v[36:39], v[144:147], v[196:199], v[36:39]
	v_mfma_f32_16x16x32_bf16 v[40:43], v[136:139], v[196:199], v[40:43]
	v_mfma_f32_16x16x32_bf16 v[40:43], v[140:143], v[200:203], v[40:43]
	v_mfma_f32_16x16x32_bf16 v[44:47], v[132:135], v[200:203], v[44:47]
	v_mfma_f32_16x16x32_bf16 v[44:47], v[128:131], v[196:199], v[44:47]
	s_setprio 0
	s_setprio 1
	v_mfma_f32_16x16x32_bf16 v[28:31], v[128:131], v[208:211], v[28:31]
	v_mfma_f32_16x16x32_bf16 v[28:31], v[132:135], v[212:215], v[28:31]
	v_mfma_f32_16x16x32_bf16 v[24:27], v[140:143], v[212:215], v[24:27]
	v_mfma_f32_16x16x32_bf16 v[24:27], v[136:139], v[208:211], v[24:27]
	v_mfma_f32_16x16x32_bf16 v[20:23], v[144:147], v[208:211], v[20:23]
	v_mfma_f32_16x16x32_bf16 v[20:23], v[148:151], v[212:215], v[20:23]
	v_mfma_f32_16x16x32_bf16 v[16:19], v[184:187], v[212:215], v[16:19]
	v_mfma_f32_16x16x32_bf16 v[16:19], v[176:179], v[208:211], v[16:19]
	s_setprio 0
	s_setprio 1
	v_mfma_f32_16x16x32_bf16 v[0:3], v[176:179], v[216:219], v[0:3]
	v_mfma_f32_16x16x32_bf16 v[0:3], v[184:187], v[220:223], v[0:3]
	v_mfma_f32_16x16x32_bf16 v[4:7], v[148:151], v[220:223], v[4:7]
	v_mfma_f32_16x16x32_bf16 v[4:7], v[144:147], v[216:219], v[4:7]
	v_mfma_f32_16x16x32_bf16 v[8:11], v[136:139], v[216:219], v[8:11]
	v_mfma_f32_16x16x32_bf16 v[8:11], v[140:143], v[220:223], v[8:11]
	v_mfma_f32_16x16x32_bf16 v[12:15], v[132:135], v[220:223], v[12:15]
	v_mfma_f32_16x16x32_bf16 v[12:15], v[128:131], v[216:219], v[12:15]
	s_setprio 0
	s_barrier
	s_add_i32 s21, 0, 0x18000
	s_add_i32 s33, 0, 0x1c000
	v_add_u32_e32 v140, s21, v163
	v_add_u32_e32 v172, s33, v163
	ds_read_b128 v[128:131], v140
	ds_read_b128 v[132:135], v140 offset:1024
	ds_read_b128 v[136:139], v140 offset:2048
	ds_read_b128 v[140:143], v140 offset:3072
	ds_read_b128 v[144:147], v172
	ds_read_b128 v[148:151], v172 offset:1024
	ds_read_b128 v[176:179], v172 offset:2048
	ds_read_b128 v[184:187], v172 offset:3072
	s_add_u32 s12, s12, 0x80000
	s_addc_u32 s13, s13, 0
	s_mov_b32 m0, s49
	v_lshl_add_u64 v[234:235], s[12:13], 0, v[152:153]
	ds_read_b128 v[188:191], v181 offset:32768
	ds_read_b128 v[192:195], v181 offset:33792
	ds_read_b128 v[196:199], v181 offset:34816
	ds_read_b128 v[200:203], v181 offset:35840
	ds_read_b128 v[208:211], v181 offset:36864
	ds_read_b128 v[212:215], v181 offset:37888
	ds_read_b128 v[216:219], v181 offset:38912
	ds_read_b128 v[220:223], v181 offset:39936
	global_load_lds_dwordx4 v[234:235], off
	v_lshl_add_u64 v[234:235], s[12:13], 0, v[156:157]
	s_mov_b32 m0, s50
	s_nop 0
	global_load_lds_dwordx4 v[234:235], off
	s_waitcnt vmcnt(8)
	s_waitcnt lgkmcnt(0)
	s_barrier
	s_setprio 1
	s_waitcnt lgkmcnt(0)
	v_mfma_f32_16x16x32_bf16 v[124:127], v[128:131], v[188:191], v[124:127]
	v_mfma_f32_16x16x32_bf16 v[124:127], v[132:135], v[192:195], v[124:127]
	v_mfma_f32_16x16x32_bf16 v[120:123], v[140:143], v[192:195], v[120:123]
	v_mfma_f32_16x16x32_bf16 v[120:123], v[136:139], v[188:191], v[120:123]
	v_mfma_f32_16x16x32_bf16 v[116:119], v[144:147], v[188:191], v[116:119]
	v_mfma_f32_16x16x32_bf16 v[116:119], v[148:151], v[192:195], v[116:119]
	v_mfma_f32_16x16x32_bf16 v[112:115], v[184:187], v[192:195], v[112:115]
	v_mfma_f32_16x16x32_bf16 v[112:115], v[176:179], v[188:191], v[112:115]
	s_setprio 0
	s_setprio 1
	v_mfma_f32_16x16x32_bf16 v[96:99], v[176:179], v[196:199], v[96:99]
	v_mfma_f32_16x16x32_bf16 v[96:99], v[184:187], v[200:203], v[96:99]
	v_mfma_f32_16x16x32_bf16 v[100:103], v[148:151], v[200:203], v[100:103]
	v_mfma_f32_16x16x32_bf16 v[100:103], v[144:147], v[196:199], v[100:103]
	v_mfma_f32_16x16x32_bf16 v[104:107], v[136:139], v[196:199], v[104:107]
	v_mfma_f32_16x16x32_bf16 v[104:107], v[140:143], v[200:203], v[104:107]
	v_mfma_f32_16x16x32_bf16 v[108:111], v[132:135], v[200:203], v[108:111]
	v_mfma_f32_16x16x32_bf16 v[108:111], v[128:131], v[196:199], v[108:111]
	s_setprio 0
	s_setprio 1
	v_mfma_f32_16x16x32_bf16 v[92:95], v[128:131], v[208:211], v[92:95]
	v_mfma_f32_16x16x32_bf16 v[92:95], v[132:135], v[212:215], v[92:95]
	v_mfma_f32_16x16x32_bf16 v[88:91], v[140:143], v[212:215], v[88:91]
	v_mfma_f32_16x16x32_bf16 v[88:91], v[136:139], v[208:211], v[88:91]
	v_mfma_f32_16x16x32_bf16 v[84:87], v[144:147], v[208:211], v[84:87]
	v_mfma_f32_16x16x32_bf16 v[84:87], v[148:151], v[212:215], v[84:87]
	v_mfma_f32_16x16x32_bf16 v[80:83], v[184:187], v[212:215], v[80:83]
	v_mfma_f32_16x16x32_bf16 v[80:83], v[176:179], v[208:211], v[80:83]
	s_setprio 0
	s_setprio 1
	v_mfma_f32_16x16x32_bf16 v[64:67], v[176:179], v[216:219], v[64:67]
	v_mfma_f32_16x16x32_bf16 v[64:67], v[184:187], v[220:223], v[64:67]
	v_mfma_f32_16x16x32_bf16 v[68:71], v[148:151], v[220:223], v[68:71]
	v_mfma_f32_16x16x32_bf16 v[68:71], v[144:147], v[216:219], v[68:71]
	v_mfma_f32_16x16x32_bf16 v[72:75], v[136:139], v[216:219], v[72:75]
	v_mfma_f32_16x16x32_bf16 v[72:75], v[140:143], v[220:223], v[72:75]
	v_mfma_f32_16x16x32_bf16 v[76:79], v[132:135], v[220:223], v[76:79]
	v_mfma_f32_16x16x32_bf16 v[76:79], v[128:131], v[216:219], v[76:79]
	s_setprio 0
	s_barrier
; #define PG8_STAGE(bufoff, gbase, voff) do { _Pragma("unroll") for (int _i = 0; _i < 2; ++_i) \
;         __builtin_amdgcn_global_load_lds((const unsigned*)((const char*)(gbase) + (voff)[_i]), (LAS unsigned*)(lds + (bufoff) + ldsw + _i * 8192), 16, 0, 0); } while (0)
; #define PG8_LDA(dst, b, h) do { _Pragma("unroll") for (int m = 0; m < 4; ++m) _Pragma("unroll") for (int k = 0; k < 2; ++k) dst[m][k] = *(const LAS bf16x8*)(lds + PG8_SA(b, h) + aoff + m * 2048 + k * 1024); } while (0)
; #define PG8_MMA(ai, bj, At, Bt) do { __builtin_amdgcn_s_setprio(1); _Pragma("unroll") for (int m = 0; m < 4; ++m) _Pragma("unroll") for (int n = 0; n < 2; ++n) _Pragma("unroll") for (int k = 0; k < 2; ++k) \
;         acc[ai][bj][m][n] = __builtin_amdgcn_mfma_f32_16x16x32_bf16(Bt[n][k], At[m][k], acc[ai][bj][m][n], 0, 0, 0); __builtin_amdgcn_s_setprio(0); } while (0)
; #define PG8_WAIT_V(n) asm volatile("s_waitcnt vmcnt(" #n ")" ::: "memory")
; #define PG8_WAIT_L(n) asm volatile("s_waitcnt lgkmcnt(" #n ")" ::: "memory")
; #define PG8_BAR __builtin_amdgcn_s_barrier()
; #define PG8_SCHED __builtin_amdgcn_sched_barrier(0)
; template <class Epi>
; __device__ __forceinline__ void gemm_phase(LAS unsigned char* lds, const Gemm g, const StaticOrder& S, const Epi& E) {
;     ...
;             PG8_LDA(At, 1, 1); PG8_STAGE(PG8_SB(1, 0), b3, voffB); PG8_STAGE(PG8_SB(1, 1), b3 + hstepB, voffB); PG8_STAGE(PG8_SA(1, 0), a3, voffA);
;             PG8_WAIT_V(8); PG8_WAIT_L(0); PG8_BAR; PG8_MMA(1, 0, At, B0); PG8_MMA(1, 1, At, B1); PG8_BAR; PG8_SCHED;
;         }
	s_add_i32 s12, s21, s46
	v_lshl_add_u64 v[224:225], v[224:225], 0, s[28:29]
	s_mov_b32 m0, s12
	ds_read_b128 v[188:191], v181 offset:49152
	ds_read_b128 v[192:195], v181 offset:50176
	ds_read_b128 v[196:199], v181 offset:51200
	ds_read_b128 v[200:203], v181 offset:52224
	ds_read_b128 v[208:211], v181 offset:53248
	ds_read_b128 v[212:215], v181 offset:54272
	ds_read_b128 v[216:219], v181 offset:55296
	ds_read_b128 v[220:223], v181 offset:56320
	global_load_lds_dwordx4 v[224:225], off
	s_add_i32 m0, s12, 0x2000
	s_add_u32 s10, s10, 0x80080
	v_lshl_add_u64 v[224:225], v[226:227], 0, s[28:29]
	s_addc_u32 s11, s11, 0
	s_add_i32 s12, s33, s46
	global_load_lds_dwordx4 v[224:225], off
	v_lshl_add_u64 v[224:225], s[10:11], 0, v[154:155]
	s_mov_b32 m0, s12
	s_nop 0
	global_load_lds_dwordx4 v[224:225], off
	v_lshl_add_u64 v[224:225], s[10:11], 0, v[158:159]
	s_add_i32 m0, s12, 0x2000
	s_nop 0
	global_load_lds_dwordx4 v[224:225], off
	v_lshl_add_u64 v[224:225], v[230:231], 0, s[28:29]
	s_mov_b32 m0, s54
	s_nop 0
	global_load_lds_dwordx4 v[224:225], off
	v_lshl_add_u64 v[224:225], v[232:233], 0, s[28:29]
	s_mov_b32 m0, s55
	s_nop 0
	global_load_lds_dwordx4 v[224:225], off
	s_waitcnt vmcnt(8)
	s_waitcnt lgkmcnt(0)
	s_barrier
	s_setprio 1
	s_waitcnt lgkmcnt(0)
	v_mfma_f32_16x16x32_bf16 v[60:63], v[128:131], v[188:191], v[60:63]
	v_mfma_f32_16x16x32_bf16 v[60:63], v[132:135], v[192:195], v[60:63]
	v_mfma_f32_16x16x32_bf16 v[56:59], v[140:143], v[192:195], v[56:59]
	v_mfma_f32_16x16x32_bf16 v[56:59], v[136:139], v[188:191], v[56:59]
	v_mfma_f32_16x16x32_bf16 v[52:55], v[144:147], v[188:191], v[52:55]
	v_mfma_f32_16x16x32_bf16 v[52:55], v[148:151], v[192:195], v[52:55]
	v_mfma_f32_16x16x32_bf16 v[48:51], v[184:187], v[192:195], v[48:51]
	v_mfma_f32_16x16x32_bf16 v[48:51], v[176:179], v[188:191], v[48:51]
	s_setprio 0
	s_setprio 1
	v_mfma_f32_16x16x32_bf16 v[32:35], v[176:179], v[196:199], v[32:35]
	v_mfma_f32_16x16x32_bf16 v[32:35], v[184:187], v[200:203], v[32:35]
	v_mfma_f32_16x16x32_bf16 v[36:39], v[148:151], v[200:203], v[36:39]
	v_mfma_f32_16x16x32_bf16 v[36:39], v[144:147], v[196:199], v[36:39]
	v_mfma_f32_16x16x32_bf16 v[40:43], v[136:139], v[196:199], v[40:43]
	v_mfma_f32_16x16x32_bf16 v[40:43], v[140:143], v[200:203], v[40:43]
	v_mfma_f32_16x16x32_bf16 v[44:47], v[132:135], v[200:203], v[44:47]
	v_mfma_f32_16x16x32_bf16 v[44:47], v[128:131], v[196:199], v[44:47]
	s_setprio 0
	s_setprio 1
	v_mfma_f32_16x16x32_bf16 v[28:31], v[128:131], v[208:211], v[28:31]
	v_mfma_f32_16x16x32_bf16 v[28:31], v[132:135], v[212:215], v[28:31]
	v_mfma_f32_16x16x32_bf16 v[24:27], v[140:143], v[212:215], v[24:27]
	v_mfma_f32_16x16x32_bf16 v[24:27], v[136:139], v[208:211], v[24:27]
	v_mfma_f32_16x16x32_bf16 v[20:23], v[144:147], v[208:211], v[20:23]
	v_mfma_f32_16x16x32_bf16 v[20:23], v[148:151], v[212:215], v[20:23]
	v_mfma_f32_16x16x32_bf16 v[16:19], v[184:187], v[212:215], v[16:19]
	v_mfma_f32_16x16x32_bf16 v[16:19], v[176:179], v[208:211], v[16:19]
	s_setprio 0
	s_setprio 1
	v_mfma_f32_16x16x32_bf16 v[0:3], v[176:179], v[216:219], v[0:3]
	v_mfma_f32_16x16x32_bf16 v[0:3], v[184:187], v[220:223], v[0:3]
	v_mfma_f32_16x16x32_bf16 v[4:7], v[148:151], v[220:223], v[4:7]
	v_mfma_f32_16x16x32_bf16 v[4:7], v[144:147], v[216:219], v[4:7]
	v_mfma_f32_16x16x32_bf16 v[8:11], v[136:139], v[216:219], v[8:11]
	v_mfma_f32_16x16x32_bf16 v[8:11], v[140:143], v[220:223], v[8:11]
	v_mfma_f32_16x16x32_bf16 v[12:15], v[132:135], v[220:223], v[12:15]
	v_mfma_f32_16x16x32_bf16 v[12:15], v[128:131], v[216:219], v[12:15]
	s_setprio 0
	s_barrier
	s_add_u32 s8, s8, 0x100
	s_addc_u32 s9, s9, 0
	s_add_u32 s18, s18, 0x100
	s_addc_u32 s19, s19, 0
	s_cmp_ge_i32 s20, s53
	s_mov_b32 s10, s20
	s_cbranch_scc0 .LBB0_1338
